# hand-scheduled f32 forward substitution in gdn_passA (immediate-offset LDS reads, panel right-looking order)
# speedup vs baseline: 1.0333x; 1.0333x over previous
.LBB0_389:
	v_writelane_b32 v245, s42, 0
	s_mov_b64 s[4:5], s[0:1]
	s_mov_b32 s6, s94
	v_writelane_b32 v245, s43, 1
	v_writelane_b32 v245, s88, 2
	v_writelane_b32 v245, s85, 3
	v_writelane_b32 v245, s86, 4
	s_cmpk_gt_i32 s6, 0x3ff
	s_nop 0
	v_writelane_b32 v245, s87, 5
	v_writelane_b32 v245, s95, 6
	v_writelane_b32 v245, s96, 7
	s_nop 1
	v_writelane_b32 v245, s97, 8
	v_writelane_b32 v245, s94, 9
	s_cbranch_scc1 .LBB0_575
	s_load_dwordx4 s[8:11], s[4:5], 0xd8
	s_load_dwordx2 s[12:13], s[4:5], 0x58
	v_mbcnt_lo_u32_b32 v0, -1, 0
	s_movk_i32 s28, 0x600
	s_movk_i32 s51, 0x3c00
	s_waitcnt lgkmcnt(0)
	s_add_u32 s14, s10, 0x2030000
	s_addc_u32 s15, s11, 0
	s_add_u32 s2, s8, 0x2000000
	v_writelane_b32 v245, s2, 10
	s_addc_u32 s2, s9, 0
	v_writelane_b32 v245, s2, 11
	s_add_u32 s2, s8, 0x3000000
	v_writelane_b32 v245, s2, 12
	s_addc_u32 s2, s9, 0
	v_writelane_b32 v245, s2, 13
	s_add_u32 s2, s10, 0x117b0000
	v_writelane_b32 v245, s2, 14
	s_addc_u32 s2, s11, 0
	v_writelane_b32 v245, s2, 15
	s_add_u32 s2, s10, 0x127b0000
	v_writelane_b32 v245, s2, 16
	s_addc_u32 s2, s11, 0
	s_add_u32 s45, s10, 0x137b0000
	s_addc_u32 s46, s11, 0
	v_writelane_b32 v245, s2, 17
	s_add_u32 s2, s10, 0x1716800
	v_writelane_b32 v245, s2, 18
	s_addc_u32 s2, s11, 0
	s_add_u32 s16, s8, 0x4e00000
	v_writelane_b32 v245, s2, 19
	s_addc_u32 s17, s9, 0
	s_add_i32 s2, 0, 0x1d700
	v_writelane_b32 v245, s2, 20
	s_add_i32 s2, 0, 0x1df00
	v_writelane_b32 v245, s2, 21
	s_add_i32 s2, 0, 0x1d504
	v_writelane_b32 v245, s2, 22
	s_add_i32 s2, 0, 0x1d604
	v_writelane_b32 v245, s2, 23
	s_add_i32 s2, 0, 0x1d508
	v_writelane_b32 v245, s2, 24
	s_add_i32 s2, 0, 0x1d608
	v_writelane_b32 v245, s2, 25
	s_add_i32 s2, 0, 0x1d50c
	v_writelane_b32 v245, s2, 26
	s_add_i32 s2, 0, 0x1d60c
	v_writelane_b32 v245, s2, 27
	s_add_i32 s2, 0, 0x1d510
	v_writelane_b32 v245, s2, 28
	s_add_i32 s2, 0, 0x1d610
	v_writelane_b32 v245, s2, 29
	s_add_i32 s2, 0, 0x1d514
	v_writelane_b32 v245, s2, 30
	s_add_i32 s2, 0, 0x1d614
	v_writelane_b32 v245, s2, 31
	s_add_i32 s2, 0, 0x1d518
	v_writelane_b32 v245, s2, 32
	s_add_i32 s2, 0, 0x1d618
	v_writelane_b32 v245, s2, 33
	s_add_i32 s2, 0, 0x1d51c
	v_writelane_b32 v245, s2, 34
	s_add_i32 s2, 0, 0x1d61c
	v_writelane_b32 v245, s2, 35
	s_add_i32 s2, 0, 0x1d520
	v_writelane_b32 v245, s2, 36
	s_add_i32 s2, 0, 0x1d620
	v_writelane_b32 v245, s2, 37
	s_add_i32 s2, 0, 0x1d524
	v_writelane_b32 v245, s2, 38
	s_add_i32 s2, 0, 0x1d624
	v_writelane_b32 v245, s2, 39
	s_add_i32 s2, 0, 0x1d528
	v_writelane_b32 v245, s2, 40
	s_add_i32 s2, 0, 0x1d628
	v_writelane_b32 v245, s2, 41
	s_add_i32 s2, 0, 0x1d52c
	v_writelane_b32 v245, s2, 42
	s_add_i32 s2, 0, 0x1d62c
	v_writelane_b32 v245, s2, 43
	s_add_i32 s2, 0, 0x1d530
	v_writelane_b32 v245, s2, 44
	s_add_i32 s2, 0, 0x1d630
	v_writelane_b32 v245, s2, 45
	s_add_i32 s2, 0, 0x1d534
	v_writelane_b32 v245, s2, 46
	s_add_i32 s2, 0, 0x1d634
	v_writelane_b32 v245, s2, 47
	s_add_i32 s2, 0, 0x1d538
	v_writelane_b32 v245, s2, 48
	s_add_i32 s2, 0, 0x1d638
	v_writelane_b32 v245, s2, 49
	s_add_i32 s2, 0, 0x1d53c
	v_writelane_b32 v245, s2, 50
	s_add_i32 s2, 0, 0x1d63c
	v_writelane_b32 v245, s2, 51
	s_add_i32 s2, 0, 0x19110
	v_writelane_b32 v245, s2, 52
	s_add_i32 s2, 0, 0x19220
	v_writelane_b32 v245, s2, 53
	s_add_i32 s2, 0, 0x19330
	v_writelane_b32 v245, s2, 54
	s_add_i32 s2, 0, 0x19440
	v_writelane_b32 v245, s2, 55
	s_add_i32 s2, 0, 0x19550
	v_writelane_b32 v245, s2, 56
	s_add_i32 s2, 0, 0x19560
	v_writelane_b32 v245, s2, 57
	s_add_i32 s2, 0, 0x19660
	v_writelane_b32 v245, s2, 58
	s_add_i32 s2, 0, 0x19670
	v_writelane_b32 v245, s2, 59
	s_add_i32 s2, 0, 0x19770
	v_writelane_b32 v245, s2, 60
	s_add_i32 s2, 0, 0x19780
	v_writelane_b32 v245, s2, 61
	s_add_i32 s2, 0, 0x19880
	v_writelane_b32 v245, s2, 62
	s_add_i32 s2, 0, 0x19890
	v_writelane_b32 v245, s2, 63
	s_add_i32 s2, 0, 0x19990
	v_writelane_b32 v244, s2, 0
	s_add_i32 s2, 0, 0x199a0
	v_writelane_b32 v244, s2, 1
	s_add_i32 s2, 0, 0x199b0
	v_writelane_b32 v244, s2, 2
	s_add_i32 s2, 0, 0x19aa0
	v_writelane_b32 v244, s2, 3
	s_add_i32 s2, 0, 0x19ab0
	v_writelane_b32 v244, s2, 4
	s_add_i32 s2, 0, 0x19ac0
	v_writelane_b32 v244, s2, 5
	s_add_i32 s2, 0, 0x19bb0
	v_writelane_b32 v244, s2, 6
	s_add_i32 s2, 0, 0x19bc0
	v_writelane_b32 v244, s2, 7
	s_add_i32 s2, 0, 0x19bd0
	v_writelane_b32 v244, s2, 8
	s_add_i32 s2, 0, 0x19cc0
	v_writelane_b32 v244, s2, 9
	s_add_i32 s2, 0, 0x19cd0
	v_writelane_b32 v244, s2, 10
	s_add_i32 s2, 0, 0x19ce0
	v_writelane_b32 v244, s2, 11
	s_add_i32 s2, 0, 0x19dd0
	v_writelane_b32 v244, s2, 12
	s_add_i32 s2, 0, 0x19de0
	v_writelane_b32 v244, s2, 13
	s_add_i32 s2, 0, 0x19df0
	v_writelane_b32 v244, s2, 14
	s_add_i32 s2, 0, 0x19e00
	v_writelane_b32 v244, s2, 15
	s_add_i32 s2, 0, 0x19ee0
	v_writelane_b32 v244, s2, 16
	s_add_i32 s2, 0, 0x19ef0
	v_writelane_b32 v244, s2, 17
	s_add_i32 s2, 0, 0x19f00
	v_writelane_b32 v244, s2, 18
	s_add_i32 s2, 0, 0x19f10
	v_writelane_b32 v244, s2, 19
	s_add_i32 s2, 0, 0x19ff0
	v_writelane_b32 v244, s2, 20
	s_add_i32 s2, 0, 0x1a000
	v_writelane_b32 v244, s2, 21
	s_add_i32 s2, 0, 0x1a010
	v_writelane_b32 v244, s2, 22
	s_add_i32 s2, 0, 0x1a020
	v_writelane_b32 v244, s2, 23
	s_add_i32 s2, 0, 0x1d540
	v_writelane_b32 v244, s2, 24
	s_add_i32 s2, 0, 0x1d640
	v_writelane_b32 v244, s2, 25
	s_add_i32 s2, 0, 0x1d544
	v_writelane_b32 v244, s2, 26
	s_add_i32 s2, 0, 0x1d644
	v_writelane_b32 v244, s2, 27
	s_add_i32 s2, 0, 0x1d548
	v_writelane_b32 v244, s2, 28
	s_add_i32 s2, 0, 0x1d648
	v_writelane_b32 v244, s2, 29
	s_add_i32 s2, 0, 0x1d54c
	v_writelane_b32 v244, s2, 30
	s_add_i32 s2, 0, 0x1d64c
	v_writelane_b32 v244, s2, 31
	s_add_i32 s2, 0, 0x1d550
	v_writelane_b32 v244, s2, 32
	s_add_i32 s2, 0, 0x1d650
	v_writelane_b32 v244, s2, 33
	s_add_i32 s2, 0, 0x1d554
	v_writelane_b32 v244, s2, 34
	s_add_i32 s2, 0, 0x1d654
	v_writelane_b32 v244, s2, 35
	s_add_i32 s2, 0, 0x1d558
	v_writelane_b32 v244, s2, 36
	s_add_i32 s2, 0, 0x1d658
	v_writelane_b32 v244, s2, 37
	s_add_i32 s2, 0, 0x1d55c
	v_writelane_b32 v244, s2, 38
	s_add_i32 s2, 0, 0x1d65c
	v_writelane_b32 v244, s2, 39
	s_add_i32 s2, 0, 0x1d560
	v_writelane_b32 v244, s2, 40
	s_add_i32 s2, 0, 0x1d660
	v_writelane_b32 v244, s2, 41
	s_add_i32 s2, 0, 0x1d564
	v_writelane_b32 v244, s2, 42
	s_add_i32 s2, 0, 0x1d664
	v_writelane_b32 v244, s2, 43
	s_add_i32 s2, 0, 0x1d568
	v_writelane_b32 v244, s2, 44
	s_add_i32 s2, 0, 0x1d668
	v_writelane_b32 v244, s2, 45
	s_add_i32 s2, 0, 0x1d56c
	v_writelane_b32 v244, s2, 46
	s_add_i32 s2, 0, 0x1d66c
	v_writelane_b32 v244, s2, 47
	s_add_i32 s2, 0, 0x1d570
	v_writelane_b32 v244, s2, 48
	s_add_i32 s2, 0, 0x1d670
	v_writelane_b32 v244, s2, 49
	s_add_i32 s2, 0, 0x1d574
	v_writelane_b32 v244, s2, 50
	s_add_i32 s2, 0, 0x1d674
	v_writelane_b32 v244, s2, 51
	s_add_i32 s2, 0, 0x1d578
	v_writelane_b32 v244, s2, 52
	s_add_i32 s2, 0, 0x1d678
	v_writelane_b32 v244, s2, 53
	s_add_i32 s2, 0, 0x1d57c
	v_writelane_b32 v244, s2, 54
	s_add_i32 s2, 0, 0x1d67c
	v_writelane_b32 v244, s2, 55
	s_add_i32 s2, 0, 0x1a100
	v_writelane_b32 v244, s2, 56
	s_add_i32 s2, 0, 0x1a210
	v_writelane_b32 v244, s2, 57
	s_add_i32 s2, 0, 0x1a320
	v_writelane_b32 v244, s2, 58
	s_add_i32 s2, 0, 0x1a430
	v_writelane_b32 v244, s2, 59
	s_add_i32 s2, 0, 0x1a540
	v_writelane_b32 v244, s2, 60
	s_add_i32 s2, 0, 0x1a650
	v_writelane_b32 v244, s2, 61
	s_add_i32 s2, 0, 0x1a760
	v_writelane_b32 v244, s2, 62
	s_add_i32 s2, 0, 0x1a870
	v_writelane_b32 v244, s2, 63
	s_add_i32 s2, 0, 0x1a980
	v_writelane_b32 v243, s2, 0
	s_add_i32 s2, 0, 0x1aa90
	v_writelane_b32 v243, s2, 1
	s_add_i32 s2, 0, 0x1aba0
	v_writelane_b32 v243, s2, 2
	s_add_i32 s2, 0, 0x1acb0
	v_writelane_b32 v243, s2, 3
	s_add_i32 s2, 0, 0x1adc0
	v_writelane_b32 v243, s2, 4
	s_add_i32 s2, 0, 0x1aed0
	v_writelane_b32 v243, s2, 5
	s_add_i32 s2, 0, 0x1afe0
	v_writelane_b32 v243, s2, 6
	s_add_i32 s2, 0, 0x1b0f0
	v_writelane_b32 v243, s2, 7
	s_add_i32 s2, 0, 0x1a110
	v_writelane_b32 v243, s2, 8
	s_add_i32 s2, 0, 0x1a220
	v_writelane_b32 v243, s2, 9
	s_add_i32 s2, 0, 0x1a330
	v_writelane_b32 v243, s2, 10
	s_add_i32 s2, 0, 0x1a440
	v_writelane_b32 v243, s2, 11
	s_add_i32 s2, 0, 0x1a550
	v_writelane_b32 v243, s2, 12
	s_add_i32 s2, 0, 0x1a660
	v_writelane_b32 v243, s2, 13
	s_add_i32 s2, 0, 0x1a770
	v_writelane_b32 v243, s2, 14
	s_add_i32 s2, 0, 0x1a880
	v_writelane_b32 v243, s2, 15
	s_add_i32 s2, 0, 0x1a990
	v_writelane_b32 v243, s2, 16
	s_add_i32 s2, 0, 0x1aaa0
	v_writelane_b32 v243, s2, 17
	s_add_i32 s2, 0, 0x1abb0
	v_writelane_b32 v243, s2, 18
	s_add_i32 s2, 0, 0x1acc0
	v_writelane_b32 v243, s2, 19
	s_add_i32 s2, 0, 0x1add0
	v_writelane_b32 v243, s2, 20
	s_add_i32 s2, 0, 0x1aee0
	v_writelane_b32 v243, s2, 21
	s_add_i32 s2, 0, 0x1aff0
	v_writelane_b32 v243, s2, 22
	s_add_i32 s2, 0, 0x1b100
	v_writelane_b32 v243, s2, 23
	s_add_i32 s2, 0, 0x1a120
	v_writelane_b32 v243, s2, 24
	s_add_i32 s2, 0, 0x1a230
	v_writelane_b32 v243, s2, 25
	s_add_i32 s2, 0, 0x1a340
	v_writelane_b32 v243, s2, 26
	s_add_i32 s2, 0, 0x1a450
	v_writelane_b32 v243, s2, 27
	s_add_i32 s2, 0, 0x1a560
	v_writelane_b32 v243, s2, 28
	s_add_i32 s2, 0, 0x1a670
	v_writelane_b32 v243, s2, 29
	s_add_i32 s2, 0, 0x1a780
	v_writelane_b32 v243, s2, 30
	s_add_i32 s2, 0, 0x1a890
	v_writelane_b32 v243, s2, 31
	s_add_i32 s2, 0, 0x1a9a0
	v_writelane_b32 v243, s2, 32
	s_add_i32 s2, 0, 0x1aab0
	v_writelane_b32 v243, s2, 33
	s_add_i32 s2, 0, 0x1abc0
	v_writelane_b32 v243, s2, 34
	s_add_i32 s2, 0, 0x1acd0
	v_writelane_b32 v243, s2, 35
	s_add_i32 s2, 0, 0x1ade0
	v_writelane_b32 v243, s2, 36
	s_add_i32 s2, 0, 0x1aef0
	v_writelane_b32 v243, s2, 37
	s_add_i32 s2, 0, 0x1b000
	v_writelane_b32 v243, s2, 38
	s_add_i32 s2, 0, 0x1b110
	v_writelane_b32 v243, s2, 39
	s_add_i32 s2, 0, 0x1a130
	v_writelane_b32 v243, s2, 40
	s_add_i32 s2, 0, 0x1a240
	v_writelane_b32 v243, s2, 41
	s_add_i32 s2, 0, 0x1a350
	v_writelane_b32 v243, s2, 42
	s_add_i32 s2, 0, 0x1a460
	v_writelane_b32 v243, s2, 43
	s_add_i32 s2, 0, 0x1a570
	v_writelane_b32 v243, s2, 44
	s_add_i32 s2, 0, 0x1a680
	v_writelane_b32 v243, s2, 45
	s_add_i32 s2, 0, 0x1a790
	v_writelane_b32 v243, s2, 46
	s_add_i32 s2, 0, 0x1a8a0
	v_writelane_b32 v243, s2, 47
	s_add_i32 s2, 0, 0x1a9b0
	v_writelane_b32 v243, s2, 48
	s_add_i32 s2, 0, 0x1aac0
	v_writelane_b32 v243, s2, 49
	s_add_i32 s2, 0, 0x1abd0
	v_writelane_b32 v243, s2, 50
	s_add_i32 s2, 0, 0x1ace0
	v_writelane_b32 v243, s2, 51
	s_add_i32 s2, 0, 0x1adf0
	v_writelane_b32 v243, s2, 52
	s_add_i32 s2, 0, 0x1af00
	v_writelane_b32 v243, s2, 53
	s_add_i32 s2, 0, 0x1b010
	v_writelane_b32 v243, s2, 54
	s_add_i32 s2, 0, 0x1b120
	v_writelane_b32 v243, s2, 55
	s_add_i32 s2, 0, 0x1a250
	v_writelane_b32 v243, s2, 56
	s_add_i32 s2, 0, 0x1a360
	v_writelane_b32 v243, s2, 57
	s_add_i32 s2, 0, 0x1a470
	v_writelane_b32 v243, s2, 58
	s_add_i32 s2, 0, 0x1a580
	v_writelane_b32 v243, s2, 59
	s_add_i32 s2, 0, 0x1a690
	v_writelane_b32 v243, s2, 60
	s_add_i32 s2, 0, 0x1a6a0
	v_writelane_b32 v243, s2, 61
	s_add_i32 s2, 0, 0x1a7a0
	v_writelane_b32 v243, s2, 62
	s_add_i32 s2, 0, 0x1a7b0
	v_writelane_b32 v243, s2, 63
	s_add_i32 s2, 0, 0x1a8b0
	v_writelane_b32 v242, s2, 0
	s_add_i32 s2, 0, 0x1a8c0
	v_writelane_b32 v242, s2, 1
	s_add_i32 s2, 0, 0x1a9c0
	v_writelane_b32 v242, s2, 2
	s_add_i32 s2, 0, 0x1a9d0
	v_writelane_b32 v242, s2, 3
	s_add_i32 s2, 0, 0x1aad0
	v_writelane_b32 v242, s2, 4
	s_add_i32 s2, 0, 0x1aae0
	v_writelane_b32 v242, s2, 5
	s_add_i32 s2, 0, 0x1aaf0
	v_writelane_b32 v242, s2, 6
	s_add_i32 s2, 0, 0x1abe0
	v_writelane_b32 v242, s2, 7
	s_add_i32 s2, 0, 0x1abf0
	v_writelane_b32 v242, s2, 8
	s_add_i32 s2, 0, 0x1ac00
	v_writelane_b32 v242, s2, 9
	s_add_i32 s2, 0, 0x1acf0
	v_writelane_b32 v242, s2, 10
	s_add_i32 s2, 0, 0x1ad00
	v_writelane_b32 v242, s2, 11
	s_add_i32 s2, 0, 0x1ad10
	v_writelane_b32 v242, s2, 12
	s_add_i32 s2, 0, 0x1ae00
	v_writelane_b32 v242, s2, 13
	s_add_i32 s2, 0, 0x1ae10
	v_writelane_b32 v242, s2, 14
	s_add_i32 s2, 0, 0x1ae20
	v_writelane_b32 v242, s2, 15
	s_add_i32 s2, 0, 0x1af10
	v_writelane_b32 v242, s2, 16
	s_add_i32 s2, 0, 0x1af20
	v_writelane_b32 v242, s2, 17
	s_add_i32 s2, 0, 0x1af30
	v_writelane_b32 v242, s2, 18
	s_add_i32 s2, 0, 0x1af40
	v_writelane_b32 v242, s2, 19
	s_add_i32 s2, 0, 0x1b020
	v_writelane_b32 v242, s2, 20
	s_add_i32 s2, 0, 0x1b030
	v_writelane_b32 v242, s2, 21
	s_add_i32 s2, 0, 0x1b040
	v_writelane_b32 v242, s2, 22
	s_add_i32 s2, 0, 0x1b050
	v_writelane_b32 v242, s2, 23
	s_add_i32 s2, 0, 0x1b130
	v_writelane_b32 v242, s2, 24
	s_add_i32 s2, 0, 0x1b140
	v_writelane_b32 v242, s2, 25
	s_add_i32 s2, 0, 0x1b150
	v_writelane_b32 v242, s2, 26
	s_add_i32 s2, 0, 0x1b160
	v_writelane_b32 v242, s2, 27
	s_add_i32 s2, 0, 0x1d580
	v_writelane_b32 v242, s2, 28
	s_add_i32 s2, 0, 0x1d680
	v_writelane_b32 v242, s2, 29
	s_add_i32 s2, 0, 0x1d584
	v_writelane_b32 v242, s2, 30
	s_add_i32 s2, 0, 0x1d684
	v_writelane_b32 v242, s2, 31
	s_add_i32 s2, 0, 0x1d588
	v_writelane_b32 v242, s2, 32
	s_add_i32 s2, 0, 0x1d688
	v_writelane_b32 v242, s2, 33
	s_add_i32 s2, 0, 0x1d58c
	v_writelane_b32 v242, s2, 34
	s_add_i32 s2, 0, 0x1d68c
	v_writelane_b32 v242, s2, 35
	s_add_i32 s2, 0, 0x1d590
	v_writelane_b32 v242, s2, 36
	s_add_i32 s2, 0, 0x1d690
	v_writelane_b32 v242, s2, 37
	s_add_i32 s2, 0, 0x1d594
	v_writelane_b32 v242, s2, 38
	s_add_i32 s2, 0, 0x1d694
	v_writelane_b32 v242, s2, 39
	s_add_i32 s2, 0, 0x1d598
	v_writelane_b32 v242, s2, 40
	s_add_i32 s2, 0, 0x1d698
	v_writelane_b32 v242, s2, 41
	s_add_i32 s2, 0, 0x1d59c
	v_writelane_b32 v242, s2, 42
	s_add_i32 s2, 0, 0x1d69c
	v_writelane_b32 v242, s2, 43
	s_add_i32 s2, 0, 0x1d5a0
	v_writelane_b32 v242, s2, 44
	s_add_i32 s2, 0, 0x1d6a0
	v_writelane_b32 v242, s2, 45
	s_add_i32 s2, 0, 0x1d5a4
	v_writelane_b32 v242, s2, 46
	s_add_i32 s2, 0, 0x1d6a4
	v_writelane_b32 v242, s2, 47
	s_add_i32 s2, 0, 0x1d5a8
	v_writelane_b32 v242, s2, 48
	s_add_i32 s2, 0, 0x1d6a8
	v_writelane_b32 v242, s2, 49
	s_add_i32 s2, 0, 0x1d5ac
	v_writelane_b32 v242, s2, 50
	s_add_i32 s2, 0, 0x1d5b4
	v_writelane_b32 v242, s2, 51
	s_add_i32 s2, 0, 0x1d6b4
	v_writelane_b32 v242, s2, 52
	s_add_i32 s2, 0, 0x1d5b8
	v_writelane_b32 v242, s2, 53
	s_add_i32 s2, 0, 0x1d6b8
	v_writelane_b32 v242, s2, 54
	s_add_i32 s2, 0, 0x1d5bc
	v_writelane_b32 v242, s2, 55
	s_add_i32 s2, 0, 0x1d6bc
	v_writelane_b32 v242, s2, 56
	s_add_i32 s2, 0, 0x1b200
	v_writelane_b32 v242, s2, 57
	s_add_i32 s2, 0, 0x1b310
	v_writelane_b32 v242, s2, 58
	s_add_i32 s2, 0, 0x1b420
	v_writelane_b32 v242, s2, 59
	s_add_i32 s2, 0, 0x1b530
	v_writelane_b32 v242, s2, 60
	s_add_i32 s2, 0, 0x1d5cc
	v_writelane_b32 v242, s2, 61
	s_add_i32 s2, 0, 0x1d6c8
	v_writelane_b32 v242, s2, 62
	s_add_i32 s2, 0, 0x1d5c8
	v_writelane_b32 v242, s2, 63
	s_add_i32 s2, 0, 0x1d6c4
	v_writelane_b32 v241, s2, 0
	s_add_i32 s2, 0, 0x1d5c4
	v_writelane_b32 v241, s2, 1
	s_add_i32 s2, 0, 0x1d6c0
	v_writelane_b32 v241, s2, 2
	s_add_i32 s2, 0, 0x1d5c0
	v_writelane_b32 v241, s2, 3
	s_add_i32 s2, 0, 0x1c2a0
	v_writelane_b32 v241, s2, 4
	s_add_i32 s2, 0, 0x1c290
	v_writelane_b32 v241, s2, 5
	s_add_i32 s2, 0, 0x1c280
	v_writelane_b32 v241, s2, 6
	s_add_i32 s2, 0, 0x1c270
	v_writelane_b32 v241, s2, 7
	s_add_i32 s2, 0, 0x1c190
	v_writelane_b32 v241, s2, 8
	s_add_i32 s2, 0, 0x1c180
	v_writelane_b32 v241, s2, 9
	s_add_i32 s2, 0, 0x1c170
	v_writelane_b32 v241, s2, 10
	s_add_i32 s2, 0, 0x1c160
	v_writelane_b32 v241, s2, 11
	s_add_i32 s2, 0, 0x1c080
	v_writelane_b32 v241, s2, 12
	s_add_i32 s2, 0, 0x1c070
	v_writelane_b32 v241, s2, 13
	s_add_i32 s2, 0, 0x1c060
	v_writelane_b32 v241, s2, 14
	s_add_i32 s2, 0, 0x1c050
	v_writelane_b32 v241, s2, 15
	s_add_i32 s2, 0, 0x1bf60
	v_writelane_b32 v241, s2, 16
	s_add_i32 s2, 0, 0x1bf50
	v_writelane_b32 v241, s2, 17
	s_add_i32 s2, 0, 0x1bf40
	v_writelane_b32 v241, s2, 18
	s_add_i32 s2, 0, 0x1be50
	v_writelane_b32 v241, s2, 19
	s_add_i32 s2, 0, 0x1be40
	v_writelane_b32 v241, s2, 20
	s_add_i32 s2, 0, 0x1be30
	v_writelane_b32 v241, s2, 21
	s_add_i32 s2, 0, 0x1bd40
	v_writelane_b32 v241, s2, 22
	s_add_i32 s2, 0, 0x1bd30
	v_writelane_b32 v241, s2, 23
	s_add_i32 s2, 0, 0x1bd20
	v_writelane_b32 v241, s2, 24
	s_add_i32 s2, 0, 0x1bc30
	v_writelane_b32 v241, s2, 25
	s_add_i32 s2, 0, 0x1bc20
	v_writelane_b32 v241, s2, 26
	s_add_i32 s2, 0, 0x1bc10
	v_writelane_b32 v241, s2, 27
	s_add_i32 s2, 0, 0x1bb10
	v_writelane_b32 v241, s2, 28
	s_add_i32 s2, 0, 0x1bb00
	v_writelane_b32 v241, s2, 29
	s_add_i32 s2, 0, 0x1ba00
	v_writelane_b32 v241, s2, 30
	s_add_i32 s2, 0, 0x1b9f0
	v_writelane_b32 v241, s2, 31
	s_add_i32 s2, 0, 0x1b8f0
	v_writelane_b32 v241, s2, 32
	s_add_i32 s2, 0, 0x1b8e0
	v_writelane_b32 v241, s2, 33
	s_add_i32 s2, 0, 0x1b7e0
	v_writelane_b32 v241, s2, 34
	s_add_i32 s2, 0, 0x1b7d0
	v_writelane_b32 v241, s2, 35
	s_add_i32 s2, 0, 0x1b6c0
	v_writelane_b32 v241, s2, 36
	s_add_i32 s2, 0, 0x1b5b0
	v_writelane_b32 v241, s2, 37
	s_add_i32 s2, 0, 0x1b4a0
	v_writelane_b32 v241, s2, 38
	s_add_i32 s2, 0, 0x1b390
	v_writelane_b32 v241, s2, 39
	s_add_i32 s2, 0, 0x1c260
	v_writelane_b32 v241, s2, 40
	s_add_i32 s2, 0, 0x1c150
	v_writelane_b32 v241, s2, 41
	s_add_i32 s2, 0, 0x1c040
	v_writelane_b32 v241, s2, 42
	s_add_i32 s2, 0, 0x1bf30
	v_writelane_b32 v241, s2, 43
	s_add_i32 s2, 0, 0x1be20
	v_writelane_b32 v241, s2, 44
	s_add_i32 s2, 0, 0x1bd10
	v_writelane_b32 v241, s2, 45
	s_add_i32 s2, 0, 0x1bc00
	v_writelane_b32 v241, s2, 46
	s_add_i32 s2, 0, 0x1baf0
	v_writelane_b32 v241, s2, 47
	s_add_i32 s2, 0, 0x1b9e0
	v_writelane_b32 v241, s2, 48
	s_add_i32 s2, 0, 0x1b8d0
	v_writelane_b32 v241, s2, 49
	s_add_i32 s2, 0, 0x1b7c0
	v_writelane_b32 v241, s2, 50
	s_add_i32 s2, 0, 0x1b6b0
	v_writelane_b32 v241, s2, 51
	s_add_i32 s2, 0, 0x1b5a0
	v_writelane_b32 v241, s2, 52
	s_add_i32 s2, 0, 0x1b490
	v_writelane_b32 v241, s2, 53
	s_add_i32 s2, 0, 0x1b380
	v_writelane_b32 v241, s2, 54
	s_add_i32 s2, 0, 0x1b270
	v_writelane_b32 v241, s2, 55
	s_add_i32 s2, 0, 0x1c250
	v_writelane_b32 v241, s2, 56
	s_add_i32 s2, 0, 0x1c140
	v_writelane_b32 v241, s2, 57
	s_add_i32 s2, 0, 0x1c030
	v_writelane_b32 v241, s2, 58
	s_add_i32 s2, 0, 0x1bf20
	v_writelane_b32 v241, s2, 59
	s_add_i32 s2, 0, 0x1be10
	v_writelane_b32 v241, s2, 60
	s_add_i32 s2, 0, 0x1bd00
	v_writelane_b32 v241, s2, 61
	s_add_i32 s2, 0, 0x1bbf0
	v_writelane_b32 v241, s2, 62
	s_add_i32 s2, 0, 0x1bae0
	v_writelane_b32 v241, s2, 63
	s_add_i32 s2, 0, 0x1b9d0
	v_writelane_b32 v240, s2, 0
	s_add_i32 s2, 0, 0x1b8c0
	v_writelane_b32 v240, s2, 1
	s_add_i32 s2, 0, 0x1b7b0
	v_writelane_b32 v240, s2, 2
	s_add_i32 s2, 0, 0x1b6a0
	v_writelane_b32 v240, s2, 3
	s_add_i32 s2, 0, 0x1b590
	v_writelane_b32 v240, s2, 4
	s_add_i32 s2, 0, 0x1b480
	v_writelane_b32 v240, s2, 5
	s_add_i32 s2, 0, 0x1b370
	v_writelane_b32 v240, s2, 6
	s_add_i32 s2, 0, 0x1b260
	v_writelane_b32 v240, s2, 7
	s_add_i32 s2, 0, 0x1c240
	v_writelane_b32 v240, s2, 8
	s_add_i32 s2, 0, 0x1c130
	v_writelane_b32 v240, s2, 9
	s_add_i32 s2, 0, 0x1c020
	v_writelane_b32 v240, s2, 10
	s_add_i32 s2, 0, 0x1bf10
	v_writelane_b32 v240, s2, 11
	s_add_i32 s2, 0, 0x1be00
	v_writelane_b32 v240, s2, 12
	s_add_i32 s2, 0, 0x1bcf0
	v_writelane_b32 v240, s2, 13
	s_add_i32 s2, 0, 0x1bbe0
	v_writelane_b32 v240, s2, 14
	s_add_i32 s2, 0, 0x1bad0
	v_writelane_b32 v240, s2, 15
	s_add_i32 s2, 0, 0x1b9c0
	v_writelane_b32 v240, s2, 16
	s_add_i32 s2, 0, 0x1b8b0
	v_writelane_b32 v240, s2, 17
	s_add_i32 s2, 0, 0x1b7a0
	v_writelane_b32 v240, s2, 18
	s_add_i32 s2, 0, 0x1b690
	v_writelane_b32 v240, s2, 19
	s_add_i32 s2, 0, 0x1b580
	v_writelane_b32 v240, s2, 20
	s_add_i32 s2, 0, 0x1b470
	v_writelane_b32 v240, s2, 21
	s_add_i32 s2, 0, 0x1b360
	v_writelane_b32 v240, s2, 22
	s_add_i32 s2, 0, 0x1b250
	v_writelane_b32 v240, s2, 23
	s_add_i32 s2, 0, 0x1c230
	v_writelane_b32 v240, s2, 24
	s_add_i32 s2, 0, 0x1c120
	v_writelane_b32 v240, s2, 25
	s_add_i32 s2, 0, 0x1c010
	v_writelane_b32 v240, s2, 26
	s_add_i32 s2, 0, 0x1bf00
	v_writelane_b32 v240, s2, 27
	s_add_i32 s2, 0, 0x1bdf0
	v_writelane_b32 v240, s2, 28
	s_add_i32 s2, 0, 0x1bce0
	v_writelane_b32 v240, s2, 29
	s_add_i32 s2, 0, 0x1bbd0
	v_writelane_b32 v240, s2, 30
	s_add_i32 s2, 0, 0x1bac0
	v_writelane_b32 v240, s2, 31
	s_add_i32 s2, 0, 0x1b9b0
	v_writelane_b32 v240, s2, 32
	s_add_i32 s2, 0, 0x1b8a0
	v_writelane_b32 v240, s2, 33
	s_add_i32 s2, 0, 0x1b790
	v_writelane_b32 v240, s2, 34
	s_add_i32 s2, 0, 0x1b680
	v_writelane_b32 v240, s2, 35
	s_add_i32 s2, 0, 0x1b570
	v_writelane_b32 v240, s2, 36
	s_add_i32 s2, 0, 0x1b460
	v_writelane_b32 v240, s2, 37
	s_add_i32 s2, 0, 0x1b350
	v_writelane_b32 v240, s2, 38
	s_add_i32 s2, 0, 0x1b240
	v_writelane_b32 v240, s2, 39
	s_add_i32 s2, 0, 0x1c220
	v_writelane_b32 v240, s2, 40
	s_add_i32 s2, 0, 0x1c110
	v_writelane_b32 v240, s2, 41
	s_add_i32 s2, 0, 0x1c000
	v_writelane_b32 v240, s2, 42
	s_add_i32 s2, 0, 0x1bef0
	v_writelane_b32 v240, s2, 43
	s_add_i32 s2, 0, 0x1bde0
	v_writelane_b32 v240, s2, 44
	s_add_i32 s2, 0, 0x1bcd0
	v_writelane_b32 v240, s2, 45
	s_add_i32 s2, 0, 0x1bbc0
	v_writelane_b32 v240, s2, 46
	s_add_i32 s2, 0, 0x1bab0
	v_writelane_b32 v240, s2, 47
	s_add_i32 s2, 0, 0x1b9a0
	v_writelane_b32 v240, s2, 48
	s_add_i32 s2, 0, 0x1b890
	v_writelane_b32 v240, s2, 49
	s_add_i32 s2, 0, 0x1b780
	v_writelane_b32 v240, s2, 50
	s_add_i32 s2, 0, 0x1b670
	v_writelane_b32 v240, s2, 51
	s_add_i32 s2, 0, 0x1b560
	v_writelane_b32 v240, s2, 52
	s_add_i32 s2, 0, 0x1b450
	v_writelane_b32 v240, s2, 53
	s_add_i32 s2, 0, 0x1b340
	v_writelane_b32 v240, s2, 54
	s_add_i32 s2, 0, 0x1b230
	v_writelane_b32 v240, s2, 55
	s_add_i32 s2, 0, 0x1c210
	v_writelane_b32 v240, s2, 56
	s_add_i32 s2, 0, 0x1c100
	v_writelane_b32 v240, s2, 57
	s_add_i32 s2, 0, 0x1bff0
	v_writelane_b32 v240, s2, 58
	s_add_i32 s2, 0, 0x1bee0
	v_writelane_b32 v240, s2, 59
	s_add_i32 s2, 0, 0x1bdd0
	v_writelane_b32 v240, s2, 60
	s_add_i32 s2, 0, 0x1bcc0
	v_writelane_b32 v240, s2, 61
	s_add_i32 s2, 0, 0x1bbb0
	v_writelane_b32 v240, s2, 62
	s_add_i32 s2, 0, 0x1baa0
	v_writelane_b32 v240, s2, 63
	s_add_i32 s2, 0, 0x1b990
	v_writelane_b32 v239, s2, 0
	s_add_i32 s2, 0, 0x1b880
	v_writelane_b32 v239, s2, 1
	s_add_i32 s2, 0, 0x1b770
	v_writelane_b32 v239, s2, 2
	s_add_i32 s2, 0, 0x1b660
	v_writelane_b32 v239, s2, 3
	s_add_i32 s2, 0, 0x1b550
	v_writelane_b32 v239, s2, 4
	s_add_i32 s2, 0, 0x1b440
	v_writelane_b32 v239, s2, 5
	s_add_i32 s2, 0, 0x1b330
	v_writelane_b32 v239, s2, 6
	s_add_i32 s2, 0, 0x1b220
	v_writelane_b32 v239, s2, 7
	s_add_i32 s2, 0, 0x1c200
	v_writelane_b32 v239, s2, 8
	s_add_i32 s2, 0, 0x1c0f0
	v_writelane_b32 v239, s2, 9
	s_add_i32 s2, 0, 0x1bfe0
	v_writelane_b32 v239, s2, 10
	s_add_i32 s2, 0, 0x1bed0
	v_writelane_b32 v239, s2, 11
	s_add_i32 s2, 0, 0x1bdc0
	v_writelane_b32 v239, s2, 12
	s_add_i32 s2, 0, 0x1bcb0
	v_writelane_b32 v239, s2, 13
	s_add_i32 s2, 0, 0x1bba0
	v_writelane_b32 v239, s2, 14
	s_add_i32 s2, 0, 0x1ba90
	v_writelane_b32 v239, s2, 15
	s_add_i32 s2, 0, 0x1b980
	v_writelane_b32 v239, s2, 16
	s_add_i32 s2, 0, 0x1b870
	v_writelane_b32 v239, s2, 17
	s_add_i32 s2, 0, 0x1b760
	v_writelane_b32 v239, s2, 18
	s_add_i32 s2, 0, 0x1b650
	v_writelane_b32 v239, s2, 19
	s_add_i32 s2, 0, 0x1b540
	v_writelane_b32 v239, s2, 20
	s_add_i32 s2, 0, 0x1b430
	v_writelane_b32 v239, s2, 21
	s_add_i32 s2, 0, 0x1b320
	v_writelane_b32 v239, s2, 22
	s_add_i32 s2, 0, 0x1b210
	v_writelane_b32 v239, s2, 23
	s_add_i32 s2, 0, 0x1c1f0
	v_writelane_b32 v239, s2, 24
	s_add_i32 s2, 0, 0x1c0e0
	v_writelane_b32 v239, s2, 25
	s_add_i32 s2, 0, 0x1bfd0
	v_writelane_b32 v239, s2, 26
	s_add_i32 s2, 0, 0x1bec0
	v_writelane_b32 v239, s2, 27
	s_add_i32 s2, 0, 0x1bdb0
	v_writelane_b32 v239, s2, 28
	s_add_i32 s2, 0, 0x1bca0
	v_writelane_b32 v239, s2, 29
	s_add_i32 s2, 0, 0x1bb90
	v_writelane_b32 v239, s2, 30
	s_add_i32 s2, 0, 0x1ba80
	v_writelane_b32 v239, s2, 31
	s_add_i32 s2, 0, 0x1b970
	v_writelane_b32 v239, s2, 32
	s_add_i32 s2, 0, 0x1b860
	v_writelane_b32 v239, s2, 33
	s_add_i32 s2, 0, 0x1b750
	v_writelane_b32 v239, s2, 34
	s_add_i32 s2, 0, 0x1b640
	v_writelane_b32 v239, s2, 35
	s_add_i32 s2, 0, 0x1d6cc
	v_writelane_b32 v239, s2, 36
	s_add_i32 s2, 0, 0x1d5d0
	v_writelane_b32 v239, s2, 37
	s_add_i32 s2, 0, 0x1d6d0
	v_writelane_b32 v239, s2, 38
	s_add_i32 s2, 0, 0x1d6b0
	v_writelane_b32 v239, s2, 39
	s_add_i32 s2, 0, 0x1d5b0
	v_writelane_b32 v239, s2, 40
	s_add_i32 s2, 0, 0x1d6ac
	v_writelane_b32 v239, s2, 41
	s_add_i32 s2, 0, 0x1d5d4
	v_writelane_b32 v239, s2, 42
	s_add_i32 s2, 0, 0x1d6d4
	v_writelane_b32 v239, s2, 43
	s_add_i32 s2, 0, 0x1d5d8
	v_writelane_b32 v239, s2, 44
	s_add_i32 s2, 0, 0x1d6d8
	v_writelane_b32 v239, s2, 45
	s_add_i32 s2, 0, 0x1d5dc
	v_writelane_b32 v239, s2, 46
	s_add_i32 s2, 0, 0x1d6dc
	v_writelane_b32 v239, s2, 47
	s_add_i32 s2, 0, 0x1d5e0
	v_writelane_b32 v239, s2, 48
	s_add_i32 s2, 0, 0x1d6e0
	v_writelane_b32 v239, s2, 49
	s_add_i32 s2, 0, 0x1d5e4
	v_writelane_b32 v239, s2, 50
	s_add_i32 s2, 0, 0x1d6e4
	v_writelane_b32 v239, s2, 51
	s_add_i32 s2, 0, 0x1d5e8
	v_writelane_b32 v239, s2, 52
	s_add_i32 s2, 0, 0x1d6e8
	v_writelane_b32 v239, s2, 53
	s_add_i32 s2, 0, 0x1d5ec
	v_writelane_b32 v239, s2, 54
	s_add_i32 s2, 0, 0x1d6ec
	v_writelane_b32 v239, s2, 55
	s_add_i32 s2, 0, 0x1d5f0
	v_writelane_b32 v239, s2, 56
	s_add_i32 s2, 0, 0x1d6f0
	v_writelane_b32 v239, s2, 57
	s_add_i32 s2, 0, 0x1d5f4
	v_writelane_b32 v239, s2, 58
	s_add_i32 s2, 0, 0x1d6f4
	v_writelane_b32 v239, s2, 59
	s_add_i32 s2, 0, 0x1d5f8
	v_writelane_b32 v239, s2, 60
	s_add_i32 s2, 0, 0x1d6f8
	v_writelane_b32 v239, s2, 61
	s_add_i32 s2, 0, 0x1d5fc
	v_writelane_b32 v239, s2, 62
	s_add_i32 s2, 0, 0x1c300
	v_writelane_b32 v239, s2, 63
	s_add_i32 s2, 0, 0x1c410
	v_writelane_b32 v238, s2, 0
	s_add_i32 s2, 0, 0x1c520
	v_writelane_b32 v238, s2, 1
	s_add_i32 s2, 0, 0x1c630
	v_writelane_b32 v238, s2, 2
	s_add_i32 s2, 0, 0x1c740
	v_writelane_b32 v238, s2, 3
	s_add_i32 s2, 0, 0x1c850
	v_writelane_b32 v238, s2, 4
	s_add_i32 s2, 0, 0x1c960
	v_writelane_b32 v238, s2, 5
	s_add_i32 s2, 0, 0x1ca70
	v_writelane_b32 v238, s2, 6
	s_add_i32 s2, 0, 0x1cb80
	v_writelane_b32 v238, s2, 7
	s_add_i32 s2, 0, 0x1cc90
	v_writelane_b32 v238, s2, 8
	s_add_i32 s2, 0, 0x1cda0
	v_writelane_b32 v238, s2, 9
	s_add_i32 s2, 0, 0x1ceb0
	v_writelane_b32 v238, s2, 10
	s_add_i32 s2, 0, 0x1cfc0
	v_writelane_b32 v238, s2, 11
	s_add_i32 s2, 0, 0x1d0d0
	v_writelane_b32 v238, s2, 12
	s_add_i32 s2, 0, 0x1d1e0
	v_writelane_b32 v238, s2, 13
	s_add_i32 s2, 0, 0x1d2f0
	v_writelane_b32 v238, s2, 14
	s_add_i32 s2, 0, 0x1c310
	v_writelane_b32 v238, s2, 15
	s_add_i32 s2, 0, 0x1c420
	v_writelane_b32 v238, s2, 16
	s_add_i32 s2, 0, 0x1c530
	v_writelane_b32 v238, s2, 17
	s_add_i32 s2, 0, 0x1c640
	v_writelane_b32 v238, s2, 18
	s_add_i32 s2, 0, 0x1c750
	v_writelane_b32 v238, s2, 19
	s_add_i32 s2, 0, 0x1c860
	v_writelane_b32 v238, s2, 20
	s_add_i32 s2, 0, 0x1c970
	v_writelane_b32 v238, s2, 21
	s_add_i32 s2, 0, 0x1ca80
	v_writelane_b32 v238, s2, 22
	s_add_i32 s2, 0, 0x1cb90
	v_writelane_b32 v238, s2, 23
	s_add_i32 s2, 0, 0x1cca0
	v_writelane_b32 v238, s2, 24
	s_add_i32 s2, 0, 0x1cdb0
	v_writelane_b32 v238, s2, 25
	s_add_i32 s2, 0, 0x1cec0
	v_writelane_b32 v238, s2, 26
	s_add_i32 s2, 0, 0x1cfd0
	v_writelane_b32 v238, s2, 27
	s_add_i32 s2, 0, 0x1d0e0
	v_writelane_b32 v238, s2, 28
	s_add_i32 s2, 0, 0x1d1f0
	v_writelane_b32 v238, s2, 29
	s_add_i32 s2, 0, 0x1d300
	v_writelane_b32 v238, s2, 30
	s_add_i32 s2, 0, 0x1c320
	v_writelane_b32 v238, s2, 31
	s_add_i32 s2, 0, 0x1c430
	v_writelane_b32 v238, s2, 32
	s_add_i32 s2, 0, 0x1c540
	v_writelane_b32 v238, s2, 33
	s_add_i32 s2, 0, 0x1c650
	v_writelane_b32 v238, s2, 34
	s_add_i32 s2, 0, 0x1c760
	v_writelane_b32 v238, s2, 35
	s_add_i32 s2, 0, 0x1c870
	v_writelane_b32 v238, s2, 36
	s_add_i32 s2, 0, 0x1c980
	v_writelane_b32 v238, s2, 37
	s_add_i32 s2, 0, 0x1ca90
	v_writelane_b32 v238, s2, 38
	s_add_i32 s2, 0, 0x1cba0
	v_writelane_b32 v238, s2, 39
	s_add_i32 s2, 0, 0x1ccb0
	v_writelane_b32 v238, s2, 40
	s_add_i32 s2, 0, 0x1cdc0
	v_writelane_b32 v238, s2, 41
	s_add_i32 s2, 0, 0x1ced0
	v_writelane_b32 v238, s2, 42
	s_add_i32 s2, 0, 0x1cfe0
	v_writelane_b32 v238, s2, 43
	s_add_i32 s2, 0, 0x1d0f0
	v_writelane_b32 v238, s2, 44
	s_add_i32 s2, 0, 0x1d200
	v_writelane_b32 v238, s2, 45
	s_add_i32 s2, 0, 0x1d310
	v_writelane_b32 v238, s2, 46
	s_add_i32 s2, 0, 0x1c330
	v_writelane_b32 v238, s2, 47
	s_add_i32 s2, 0, 0x1c440
	v_writelane_b32 v238, s2, 48
	s_add_i32 s2, 0, 0x1c550
	v_writelane_b32 v238, s2, 49
	s_add_i32 s2, 0, 0x1c660
	v_writelane_b32 v238, s2, 50
	s_add_i32 s2, 0, 0x1c770
	v_writelane_b32 v238, s2, 51
	s_add_i32 s2, 0, 0x1c880
	v_writelane_b32 v238, s2, 52
	s_add_i32 s2, 0, 0x1c990
	v_writelane_b32 v238, s2, 53
	s_add_i32 s2, 0, 0x1caa0
	v_writelane_b32 v238, s2, 54
	s_add_i32 s2, 0, 0x1cbb0
	v_writelane_b32 v238, s2, 55
	s_add_i32 s2, 0, 0x1ccc0
	v_writelane_b32 v238, s2, 56
	s_add_i32 s2, 0, 0x1cdd0
	v_writelane_b32 v238, s2, 57
	s_add_i32 s2, 0, 0x1cee0
	v_writelane_b32 v238, s2, 58
	s_add_i32 s2, 0, 0x1cff0
	v_writelane_b32 v238, s2, 59
	s_add_i32 s2, 0, 0x1d100
	v_writelane_b32 v238, s2, 60
	s_add_i32 s2, 0, 0x1d210
	v_writelane_b32 v238, s2, 61
	s_add_i32 s2, 0, 0x1d320
	v_writelane_b32 v238, s2, 62
	s_add_i32 s2, 0, 0x1c340
	v_writelane_b32 v238, s2, 63
	s_add_i32 s2, 0, 0x1c450
	v_writelane_b32 v237, s2, 0
	s_add_i32 s2, 0, 0x1c560
	v_writelane_b32 v237, s2, 1
	s_add_i32 s2, 0, 0x1c670
	v_writelane_b32 v237, s2, 2
	s_add_i32 s2, 0, 0x1c780
	v_writelane_b32 v237, s2, 3
	s_add_i32 s2, 0, 0x1c890
	v_writelane_b32 v237, s2, 4
	s_add_i32 s2, 0, 0x1c9a0
	v_writelane_b32 v237, s2, 5
	s_add_i32 s2, 0, 0x1cab0
	v_writelane_b32 v237, s2, 6
	s_add_i32 s2, 0, 0x1cbc0
	v_writelane_b32 v237, s2, 7
	s_add_i32 s2, 0, 0x1ccd0
	v_writelane_b32 v237, s2, 8
	s_add_i32 s2, 0, 0x1cde0
	v_writelane_b32 v237, s2, 9
	s_add_i32 s2, 0, 0x1cef0
	v_writelane_b32 v237, s2, 10
	s_add_i32 s2, 0, 0x1d000
	v_writelane_b32 v237, s2, 11
	s_add_i32 s2, 0, 0x1d110
	v_writelane_b32 v237, s2, 12
	s_add_i32 s2, 0, 0x1d220
	v_writelane_b32 v237, s2, 13
	s_add_i32 s2, 0, 0x1d330
	v_writelane_b32 v237, s2, 14
	s_add_i32 s2, 0, 0x1c350
	v_writelane_b32 v237, s2, 15
	s_add_i32 s2, 0, 0x1c460
	v_writelane_b32 v237, s2, 16
	s_add_i32 s2, 0, 0x1c570
	v_writelane_b32 v237, s2, 17
	s_add_i32 s2, 0, 0x1c680
	v_writelane_b32 v237, s2, 18
	s_add_i32 s2, 0, 0x1c790
	v_writelane_b32 v237, s2, 19
	s_add_i32 s2, 0, 0x1c8a0
	v_writelane_b32 v237, s2, 20
	s_add_i32 s2, 0, 0x1c9b0
	v_writelane_b32 v237, s2, 21
	s_add_i32 s2, 0, 0x1cac0
	v_writelane_b32 v237, s2, 22
	s_add_i32 s2, 0, 0x1cbd0
	v_writelane_b32 v237, s2, 23
	s_add_i32 s2, 0, 0x1cce0
	v_writelane_b32 v237, s2, 24
	s_add_i32 s2, 0, 0x1cdf0
	v_writelane_b32 v237, s2, 25
	s_add_i32 s2, 0, 0x1cf00
	v_writelane_b32 v237, s2, 26
	s_add_i32 s2, 0, 0x1d010
	v_writelane_b32 v237, s2, 27
	s_add_i32 s2, 0, 0x1d120
	v_writelane_b32 v237, s2, 28
	s_add_i32 s2, 0, 0x1d230
	v_writelane_b32 v237, s2, 29
	s_add_i32 s2, 0, 0x1d340
	v_writelane_b32 v237, s2, 30
	s_add_i32 s2, 0, 0x1c360
	v_writelane_b32 v237, s2, 31
	s_add_i32 s2, 0, 0x1c470
	v_writelane_b32 v237, s2, 32
	s_add_i32 s2, 0, 0x1c580
	v_writelane_b32 v237, s2, 33
	s_add_i32 s2, 0, 0x1c690
	v_writelane_b32 v237, s2, 34
	s_add_i32 s2, 0, 0x1c7a0
	v_writelane_b32 v237, s2, 35
	s_add_i32 s2, 0, 0x1c8b0
	v_writelane_b32 v237, s2, 36
	s_add_i32 s2, 0, 0x1c9c0
	v_writelane_b32 v237, s2, 37
	s_add_i32 s2, 0, 0x1cad0
	v_writelane_b32 v237, s2, 38
	s_add_i32 s2, 0, 0x1cbe0
	v_writelane_b32 v237, s2, 39
	s_add_i32 s2, 0, 0x1ccf0
	v_writelane_b32 v237, s2, 40
	s_add_i32 s2, 0, 0x1ce00
	v_writelane_b32 v237, s2, 41
	s_add_i32 s2, 0, 0x1cf10
	v_writelane_b32 v237, s2, 42
	s_add_i32 s2, 0, 0x1d020
	v_writelane_b32 v237, s2, 43
	s_add_i32 s2, 0, 0x1d130
	v_writelane_b32 v237, s2, 44
	s_add_i32 s2, 0, 0x1d240
	v_writelane_b32 v237, s2, 45
	s_add_i32 s2, 0, 0x1d350
	v_writelane_b32 v237, s2, 46
	s_add_i32 s2, 0, 0x1c370
	v_writelane_b32 v237, s2, 47
	s_add_i32 s2, 0, 0x1c480
	v_writelane_b32 v237, s2, 48
	s_add_i32 s2, 0, 0x1c590
	v_writelane_b32 v237, s2, 49
	s_add_i32 s2, 0, 0x1c6a0
	v_writelane_b32 v237, s2, 50
	s_add_i32 s2, 0, 0x1c7b0
	v_writelane_b32 v237, s2, 51
	s_add_i32 s2, 0, 0x1c8c0
	v_writelane_b32 v237, s2, 52
	s_add_i32 s2, 0, 0x1c9d0
	v_writelane_b32 v237, s2, 53
	s_add_i32 s2, 0, 0x1cae0
	v_writelane_b32 v237, s2, 54
	s_add_i32 s2, 0, 0x1cbf0
	v_writelane_b32 v237, s2, 55
	s_add_i32 s2, 0, 0x1cd00
	v_writelane_b32 v237, s2, 56
	s_add_i32 s2, 0, 0x1ce10
	v_writelane_b32 v237, s2, 57
	s_add_i32 s2, 0, 0x1cf20
	v_writelane_b32 v237, s2, 58
	s_add_i32 s2, 0, 0x1d030
	v_writelane_b32 v237, s2, 59
	s_add_i32 s2, 0, 0x1d140
	v_writelane_b32 v237, s2, 60
	s_add_i32 s2, 0, 0x1d250
	v_writelane_b32 v237, s2, 61
	s_add_i32 s2, 0, 0x1d360
	v_writelane_b32 v237, s2, 62
	s_add_i32 s2, 0, 0x1c380
	v_writelane_b32 v237, s2, 63
	s_add_i32 s2, 0, 0x1c490
	v_writelane_b32 v236, s2, 0
	s_add_i32 s2, 0, 0x1c5a0
	v_writelane_b32 v236, s2, 1
	s_add_i32 s2, 0, 0x1c6b0
	v_writelane_b32 v236, s2, 2
	s_add_i32 s2, 0, 0x1c7c0
	v_writelane_b32 v236, s2, 3
	s_add_i32 s2, 0, 0x1c8d0
	v_writelane_b32 v236, s2, 4
	s_add_i32 s2, 0, 0x1c9e0
	v_writelane_b32 v236, s2, 5
	s_add_i32 s2, 0, 0x1caf0
	v_writelane_b32 v236, s2, 6
	s_add_i32 s2, 0, 0x1cc00
	v_writelane_b32 v236, s2, 7
	s_add_i32 s2, 0, 0x1cd10
	v_writelane_b32 v236, s2, 8
	s_add_i32 s2, 0, 0x1ce20
	v_writelane_b32 v236, s2, 9
	s_add_i32 s2, 0, 0x1cf30
	v_writelane_b32 v236, s2, 10
	s_add_i32 s2, 0, 0x1d040
	v_writelane_b32 v236, s2, 11
	s_add_i32 s2, 0, 0x1d150
	v_writelane_b32 v236, s2, 12
	s_add_i32 s2, 0, 0x1d260
	v_writelane_b32 v236, s2, 13
	s_add_i32 s2, 0, 0x1d370
	v_writelane_b32 v236, s2, 14
	s_add_i32 s2, 0, 0x1c390
	v_writelane_b32 v236, s2, 15
	s_add_i32 s2, 0, 0x1c4a0
	v_writelane_b32 v236, s2, 16
	s_add_i32 s2, 0, 0x1c5b0
	v_writelane_b32 v236, s2, 17
	s_add_i32 s2, 0, 0x1c6c0
	v_writelane_b32 v236, s2, 18
	s_add_i32 s2, 0, 0x1c7d0
	v_writelane_b32 v236, s2, 19
	s_add_i32 s2, 0, 0x1c8e0
	v_writelane_b32 v236, s2, 20
	s_add_i32 s2, 0, 0x1c9f0
	v_writelane_b32 v236, s2, 21
	s_add_i32 s2, 0, 0x1cb00
	v_writelane_b32 v236, s2, 22
	s_add_i32 s2, 0, 0x1cc10
	v_writelane_b32 v236, s2, 23
	s_add_i32 s2, 0, 0x1cd20
	v_writelane_b32 v236, s2, 24
	s_add_i32 s2, 0, 0x1ce30
	v_writelane_b32 v236, s2, 25
	s_add_i32 s2, 0, 0x1cf40
	v_writelane_b32 v236, s2, 26
	s_add_i32 s2, 0, 0x1d050
	v_writelane_b32 v236, s2, 27
	s_add_i32 s2, 0, 0x1d160
	v_writelane_b32 v236, s2, 28
	s_add_i32 s2, 0, 0x1d270
	v_writelane_b32 v236, s2, 29
	s_add_i32 s2, 0, 0x1d380
	v_writelane_b32 v236, s2, 30
	s_add_i32 s2, 0, 0x1c3a0
	v_writelane_b32 v236, s2, 31
	s_add_i32 s2, 0, 0x1c4b0
	v_writelane_b32 v236, s2, 32
	s_add_i32 s2, 0, 0x1c5c0
	v_writelane_b32 v236, s2, 33
	s_add_i32 s2, 0, 0x1c6d0
	v_writelane_b32 v236, s2, 34
	s_add_i32 s2, 0, 0x1c7e0
	v_writelane_b32 v236, s2, 35
	s_add_i32 s2, 0, 0x1c8f0
	v_writelane_b32 v236, s2, 36
	s_add_i32 s2, 0, 0x1ca00
	v_writelane_b32 v236, s2, 37
	s_add_i32 s2, 0, 0x1cb10
	v_writelane_b32 v236, s2, 38
	s_add_i32 s2, 0, 0x1cc20
	v_writelane_b32 v236, s2, 39
	s_add_i32 s2, 0, 0x1cd30
	v_writelane_b32 v236, s2, 40
	s_add_i32 s2, 0, 0x1ce40
	v_writelane_b32 v236, s2, 41
	s_add_i32 s2, 0, 0x1cf50
	v_writelane_b32 v236, s2, 42
	s_add_i32 s2, 0, 0x1d060
	v_mov_b32_e32 v97, 0
	s_movk_i32 s52, 0x1800
	s_mov_b32 s53, 0xffff0000
	s_movk_i32 s54, 0x110
	v_mbcnt_hi_u32_b32 v124, -1, v0
	s_mov_b32 s55, 0x800000
	s_movk_i32 s56, 0x7fff
	s_movk_i32 s57, 0x210
	s_add_i32 s58, 0, 0x10c00
	v_mov_b32_e32 v125, 0x3ecc95a3
	s_add_i32 s59, 0, 0x1d600
	s_add_i32 s60, 0, 0x19000
	s_add_i32 s61, 0, 0x1d6fc
	v_mov_b32_e32 v126, 0x400
	v_mov_b32_e32 v98, 0x3f317218
	v_mov_b32_e32 v127, 0x7f800000
	v_mov_b32_e32 v128, 0x7fc00000
	v_mov_b32_e32 v129, 0xff800000
	v_mov_b32_e32 v130, 1
	v_writelane_b32 v236, s2, 43
	s_add_i32 s42, 0, 0x1d170
	s_add_i32 s43, 0, 0x1d280
	s_add_i32 s49, 0, 0x1d390
	s_add_i32 s29, 0, 0x1c3b0
	s_add_i32 s30, 0, 0x1c4c0
	s_add_i32 s31, 0, 0x1c5d0
	s_add_i32 s36, 0, 0x1c6e0
	s_add_i32 s47, 0, 0x1c7f0
	s_add_i32 s48, 0, 0x1c900
	s_add_i32 s63, 0, 0x1ca10
	s_add_i32 s67, 0, 0x1cb20
	s_add_i32 s69, 0, 0x1cc30
	s_add_i32 s71, 0, 0x1cd40
	s_add_i32 s73, 0, 0x1ce50
	s_add_i32 s75, 0, 0x1cf60
	s_add_i32 s77, 0, 0x1d070
	s_add_i32 s79, 0, 0x1d180
	s_add_i32 s81, 0, 0x1d290
	s_add_i32 s83, 0, 0x1d3a0
	s_add_i32 s85, 0, 0x1c4d0
	s_add_i32 s87, 0, 0x1c5e0
	s_add_i32 s89, 0, 0x1c6f0
	s_add_i32 s91, 0, 0x1c800
	s_add_i32 s93, 0, 0x1c910
	s_add_i32 s8, 0, 0x1c920
	s_add_i32 s9, 0, 0x1ca20
	s_add_i32 s3, 0, 0x1ca30
	s_add_i32 s2, 0, 0x1cb30
	s_add_i32 s64, 0, 0x1cb40
	s_add_i32 s65, 0, 0x1cc40
	s_add_i32 s37, 0, 0x1cc50
	s_add_i32 s38, 0, 0x1cd50
	s_add_i32 s39, 0, 0x1cd60
	s_add_i32 s44, 0, 0x1cd70
	s_add_i32 s62, 0, 0x1ce60
	s_add_i32 s66, 0, 0x1ce70
	s_add_i32 s68, 0, 0x1ce80
	s_add_i32 s70, 0, 0x1cf70
	s_add_i32 s72, 0, 0x1cf80
	s_add_i32 s74, 0, 0x1cf90
	s_add_i32 s76, 0, 0x1d080
	s_add_i32 s78, 0, 0x1d090
	s_add_i32 s80, 0, 0x1d0a0
	s_add_i32 s82, 0, 0x1d190
	s_add_i32 s84, 0, 0x1d1a0
	s_add_i32 s86, 0, 0x1d1b0
	s_add_i32 s88, 0, 0x1d1c0
	s_add_i32 s90, 0, 0x1d2a0
	s_add_i32 s92, 0, 0x1d2b0
	s_add_i32 s94, 0, 0x1d2c0
	s_add_i32 s95, 0, 0x1d2d0
	s_add_i32 s96, 0, 0x1d3b0
	s_add_i32 s97, 0, 0x1d3c0
	s_add_i32 s33, 0, 0x1d3d0
	s_add_i32 s50, 0, 0x1d3e0
	s_mov_b64 s[18:19], 0x1000
	s_mov_b32 s21, 0
	s_branch .LBB0_393
.LBB0_392:
	s_or_b64 exec, exec, s[4:5]
	s_add_i32 s6, s6, s34
	s_cmpk_gt_i32 s6, 0x3ff
	s_waitcnt vmcnt(63) expcnt(7) lgkmcnt(15)
	s_barrier
	s_cbranch_scc1 .LBB0_575

.LBB0_442:
	s_andn2_saveexec_b64 s[4:5], s[4:5]
	s_cbranch_execz .LBB0_392
	v_lshlrev_b32_e32 v60, 2, v100
	v_add_u32_e32 v61, 0x10c00, v60
	v_add_u32_e32 v62, 0x8600, v60
	s_movk_i32 s7, 0x80
	v_cmp_gt_u32_e64 s[24:25], s7, v100
	v_mov_b32_e32 v63, 0x19000
	v_mov_b32_e32 v64, 0x1d500
	v_cndmask_b32_e64 v61, v62, v61, s[24:25]
	ds_read_b32 v160, v61 offset:0
	ds_read_b32 v161, v61 offset:528
	ds_read_b32 v162, v61 offset:1056
	ds_read_b32 v163, v61 offset:1584
	ds_read_b32 v164, v61 offset:2112
	ds_read_b32 v165, v61 offset:2640
	ds_read_b32 v166, v61 offset:3168
	ds_read_b32 v167, v61 offset:3696
	ds_read_b32 v168, v61 offset:4224
	ds_read_b32 v169, v61 offset:4752
	ds_read_b32 v170, v61 offset:5280
	ds_read_b32 v171, v61 offset:5808
	ds_read_b32 v172, v61 offset:6336
	ds_read_b32 v173, v61 offset:6864
	ds_read_b32 v174, v61 offset:7392
	ds_read_b32 v175, v61 offset:7920
	ds_read_b32 v176, v61 offset:8448
	ds_read_b32 v177, v61 offset:8976
	ds_read_b32 v178, v61 offset:9504
	ds_read_b32 v179, v61 offset:10032
	ds_read_b32 v180, v61 offset:10560
	ds_read_b32 v181, v61 offset:11088
	ds_read_b32 v182, v61 offset:11616
	ds_read_b32 v183, v61 offset:12144
	ds_read_b32 v184, v61 offset:12672
	ds_read_b32 v185, v61 offset:13200
	ds_read_b32 v186, v61 offset:13728
	ds_read_b32 v187, v61 offset:14256
	ds_read_b32 v188, v61 offset:14784
	ds_read_b32 v189, v61 offset:15312
	ds_read_b32 v190, v61 offset:15840
	ds_read_b32 v191, v61 offset:16368
	ds_read_b32 v192, v61 offset:16896
	ds_read_b32 v193, v61 offset:17424
	ds_read_b32 v194, v61 offset:17952
	ds_read_b32 v195, v61 offset:18480
	ds_read_b32 v196, v61 offset:19008
	ds_read_b32 v197, v61 offset:19536
	ds_read_b32 v198, v61 offset:20064
	ds_read_b32 v199, v61 offset:20592
	ds_read_b32 v200, v61 offset:21120
	ds_read_b32 v201, v61 offset:21648
	ds_read_b32 v202, v61 offset:22176
	ds_read_b32 v203, v61 offset:22704
	ds_read_b32 v204, v61 offset:23232
	ds_read_b32 v205, v61 offset:23760
	ds_read_b32 v206, v61 offset:24288
	ds_read_b32 v207, v61 offset:24816
	ds_read_b32 v208, v61 offset:25344
	ds_read_b32 v209, v61 offset:25872
	ds_read_b32 v210, v61 offset:26400
	ds_read_b32 v211, v61 offset:26928
	ds_read_b32 v212, v61 offset:27456
	ds_read_b32 v213, v61 offset:27984
	ds_read_b32 v214, v61 offset:28512
	ds_read_b32 v215, v61 offset:29040
	ds_read_b32 v216, v61 offset:29568
	ds_read_b32 v217, v61 offset:30096
	ds_read_b32 v218, v61 offset:30624
	ds_read_b32 v219, v61 offset:31152
	ds_read_b32 v220, v61 offset:31680
	ds_read_b32 v221, v61 offset:32208
	ds_read_b32 v222, v61 offset:32736
	ds_read_b32 v223, v61 offset:33264
	ds_read_b128 v[16:19], v64 offset:0
	ds_read_b128 v[20:23], v64 offset:16
	ds_read_b128 v[24:27], v64 offset:32
	ds_read_b128 v[28:31], v64 offset:48
	ds_read_b128 v[0:3], v64 offset:256
	ds_read_b128 v[4:7], v64 offset:272
	ds_read_b128 v[8:11], v64 offset:288
	ds_read_b128 v[12:15], v64 offset:304
	s_waitcnt lgkmcnt(0)
	v_mul_f32_e32 v0, 0x3fb8aa3b, v0
	v_mul_f32_e32 v1, 0x3fb8aa3b, v1
	v_mul_f32_e32 v2, 0x3fb8aa3b, v2
	v_mul_f32_e32 v3, 0x3fb8aa3b, v3
	v_mul_f32_e32 v4, 0x3fb8aa3b, v4
	v_mul_f32_e32 v5, 0x3fb8aa3b, v5
	v_mul_f32_e32 v6, 0x3fb8aa3b, v6
	v_mul_f32_e32 v7, 0x3fb8aa3b, v7
	v_mul_f32_e32 v8, 0x3fb8aa3b, v8
	v_mul_f32_e32 v9, 0x3fb8aa3b, v9
	v_mul_f32_e32 v10, 0x3fb8aa3b, v10
	v_mul_f32_e32 v11, 0x3fb8aa3b, v11
	v_mul_f32_e32 v12, 0x3fb8aa3b, v12
	v_mul_f32_e32 v13, 0x3fb8aa3b, v13
	v_mul_f32_e32 v14, 0x3fb8aa3b, v14
	v_mul_f32_e32 v15, 0x3fb8aa3b, v15
	v_exp_f32_e32 v0, v0
	v_exp_f32_e32 v1, v1
	v_exp_f32_e32 v2, v2
	v_exp_f32_e32 v3, v3
	v_exp_f32_e32 v4, v4
	v_exp_f32_e32 v5, v5
	v_exp_f32_e32 v6, v6
	v_exp_f32_e32 v7, v7
	v_exp_f32_e32 v8, v8
	v_exp_f32_e32 v9, v9
	v_exp_f32_e32 v10, v10
	v_exp_f32_e32 v11, v11
	v_exp_f32_e32 v12, v12
	v_exp_f32_e32 v13, v13
	v_exp_f32_e32 v14, v14
	v_exp_f32_e32 v15, v15
	s_nop 0
	v_cndmask_b32_e64 v0, v0, 1.0, s[24:25]
	v_cndmask_b32_e64 v1, v1, 1.0, s[24:25]
	v_cndmask_b32_e64 v2, v2, 1.0, s[24:25]
	v_cndmask_b32_e64 v3, v3, 1.0, s[24:25]
	v_cndmask_b32_e64 v4, v4, 1.0, s[24:25]
	v_cndmask_b32_e64 v5, v5, 1.0, s[24:25]
	v_cndmask_b32_e64 v6, v6, 1.0, s[24:25]
	v_cndmask_b32_e64 v7, v7, 1.0, s[24:25]
	v_cndmask_b32_e64 v8, v8, 1.0, s[24:25]
	v_cndmask_b32_e64 v9, v9, 1.0, s[24:25]
	v_cndmask_b32_e64 v10, v10, 1.0, s[24:25]
	v_cndmask_b32_e64 v11, v11, 1.0, s[24:25]
	v_cndmask_b32_e64 v12, v12, 1.0, s[24:25]
	v_cndmask_b32_e64 v13, v13, 1.0, s[24:25]
	v_cndmask_b32_e64 v14, v14, 1.0, s[24:25]
	v_cndmask_b32_e64 v15, v15, 1.0, s[24:25]
	v_mul_f32_e32 v16, v16, v0
	v_mul_f32_e32 v17, v17, v1
	v_mul_f32_e32 v18, v18, v2
	v_mul_f32_e32 v19, v19, v3
	v_mul_f32_e32 v20, v20, v4
	v_mul_f32_e32 v21, v21, v5
	v_mul_f32_e32 v22, v22, v6
	v_mul_f32_e32 v23, v23, v7
	v_mul_f32_e32 v24, v24, v8
	v_mul_f32_e32 v25, v25, v9
	v_mul_f32_e32 v26, v26, v10
	v_mul_f32_e32 v27, v27, v11
	v_mul_f32_e32 v28, v28, v12
	v_mul_f32_e32 v29, v29, v13
	v_mul_f32_e32 v30, v30, v14
	v_mul_f32_e32 v31, v31, v15
	v_mul_f32_e32 v160, v160, v16
	v_mul_f32_e32 v161, v161, v17
	v_mul_f32_e32 v162, v162, v18
	v_mul_f32_e32 v163, v163, v19
	v_mul_f32_e32 v164, v164, v20
	v_mul_f32_e32 v165, v165, v21
	v_mul_f32_e32 v166, v166, v22
	v_mul_f32_e32 v167, v167, v23
	v_mul_f32_e32 v168, v168, v24
	v_mul_f32_e32 v169, v169, v25
	v_mul_f32_e32 v170, v170, v26
	v_mul_f32_e32 v171, v171, v27
	v_mul_f32_e32 v172, v172, v28
	v_mul_f32_e32 v173, v173, v29
	v_mul_f32_e32 v174, v174, v30
	v_mul_f32_e32 v175, v175, v31
	ds_read_b128 v[16:19], v64 offset:64
	ds_read_b128 v[20:23], v64 offset:80
	ds_read_b128 v[24:27], v64 offset:96
	ds_read_b128 v[28:31], v64 offset:112
	ds_read_b128 v[0:3], v64 offset:320
	ds_read_b128 v[4:7], v64 offset:336
	ds_read_b128 v[8:11], v64 offset:352
	ds_read_b128 v[12:15], v64 offset:368
	s_waitcnt lgkmcnt(0)
	v_mul_f32_e32 v0, 0x3fb8aa3b, v0
	v_mul_f32_e32 v1, 0x3fb8aa3b, v1
	v_mul_f32_e32 v2, 0x3fb8aa3b, v2
	v_mul_f32_e32 v3, 0x3fb8aa3b, v3
	v_mul_f32_e32 v4, 0x3fb8aa3b, v4
	v_mul_f32_e32 v5, 0x3fb8aa3b, v5
	v_mul_f32_e32 v6, 0x3fb8aa3b, v6
	v_mul_f32_e32 v7, 0x3fb8aa3b, v7
	v_mul_f32_e32 v8, 0x3fb8aa3b, v8
	v_mul_f32_e32 v9, 0x3fb8aa3b, v9
	v_mul_f32_e32 v10, 0x3fb8aa3b, v10
	v_mul_f32_e32 v11, 0x3fb8aa3b, v11
	v_mul_f32_e32 v12, 0x3fb8aa3b, v12
	v_mul_f32_e32 v13, 0x3fb8aa3b, v13
	v_mul_f32_e32 v14, 0x3fb8aa3b, v14
	v_mul_f32_e32 v15, 0x3fb8aa3b, v15
	v_exp_f32_e32 v0, v0
	v_exp_f32_e32 v1, v1
	v_exp_f32_e32 v2, v2
	v_exp_f32_e32 v3, v3
	v_exp_f32_e32 v4, v4
	v_exp_f32_e32 v5, v5
	v_exp_f32_e32 v6, v6
	v_exp_f32_e32 v7, v7
	v_exp_f32_e32 v8, v8
	v_exp_f32_e32 v9, v9
	v_exp_f32_e32 v10, v10
	v_exp_f32_e32 v11, v11
	v_exp_f32_e32 v12, v12
	v_exp_f32_e32 v13, v13
	v_exp_f32_e32 v14, v14
	v_exp_f32_e32 v15, v15
	s_nop 0
	v_cndmask_b32_e64 v0, v0, 1.0, s[24:25]
	v_cndmask_b32_e64 v1, v1, 1.0, s[24:25]
	v_cndmask_b32_e64 v2, v2, 1.0, s[24:25]
	v_cndmask_b32_e64 v3, v3, 1.0, s[24:25]
	v_cndmask_b32_e64 v4, v4, 1.0, s[24:25]
	v_cndmask_b32_e64 v5, v5, 1.0, s[24:25]
	v_cndmask_b32_e64 v6, v6, 1.0, s[24:25]
	v_cndmask_b32_e64 v7, v7, 1.0, s[24:25]
	v_cndmask_b32_e64 v8, v8, 1.0, s[24:25]
	v_cndmask_b32_e64 v9, v9, 1.0, s[24:25]
	v_cndmask_b32_e64 v10, v10, 1.0, s[24:25]
	v_cndmask_b32_e64 v11, v11, 1.0, s[24:25]
	v_cndmask_b32_e64 v12, v12, 1.0, s[24:25]
	v_cndmask_b32_e64 v13, v13, 1.0, s[24:25]
	v_cndmask_b32_e64 v14, v14, 1.0, s[24:25]
	v_cndmask_b32_e64 v15, v15, 1.0, s[24:25]
	v_mul_f32_e32 v16, v16, v0
	v_mul_f32_e32 v17, v17, v1
	v_mul_f32_e32 v18, v18, v2
	v_mul_f32_e32 v19, v19, v3
	v_mul_f32_e32 v20, v20, v4
	v_mul_f32_e32 v21, v21, v5
	v_mul_f32_e32 v22, v22, v6
	v_mul_f32_e32 v23, v23, v7
	v_mul_f32_e32 v24, v24, v8
	v_mul_f32_e32 v25, v25, v9
	v_mul_f32_e32 v26, v26, v10
	v_mul_f32_e32 v27, v27, v11
	v_mul_f32_e32 v28, v28, v12
	v_mul_f32_e32 v29, v29, v13
	v_mul_f32_e32 v30, v30, v14
	v_mul_f32_e32 v31, v31, v15
	v_mul_f32_e32 v176, v176, v16
	v_mul_f32_e32 v177, v177, v17
	v_mul_f32_e32 v178, v178, v18
	v_mul_f32_e32 v179, v179, v19
	v_mul_f32_e32 v180, v180, v20
	v_mul_f32_e32 v181, v181, v21
	v_mul_f32_e32 v182, v182, v22
	v_mul_f32_e32 v183, v183, v23
	v_mul_f32_e32 v184, v184, v24
	v_mul_f32_e32 v185, v185, v25
	v_mul_f32_e32 v186, v186, v26
	v_mul_f32_e32 v187, v187, v27
	v_mul_f32_e32 v188, v188, v28
	v_mul_f32_e32 v189, v189, v29
	v_mul_f32_e32 v190, v190, v30
	v_mul_f32_e32 v191, v191, v31
	ds_read_b128 v[16:19], v64 offset:128
	ds_read_b128 v[20:23], v64 offset:144
	ds_read_b128 v[24:27], v64 offset:160
	ds_read_b128 v[28:31], v64 offset:176
	ds_read_b128 v[0:3], v64 offset:384
	ds_read_b128 v[4:7], v64 offset:400
	ds_read_b128 v[8:11], v64 offset:416
	ds_read_b128 v[12:15], v64 offset:432
	s_waitcnt lgkmcnt(0)
	v_mul_f32_e32 v0, 0x3fb8aa3b, v0
	v_mul_f32_e32 v1, 0x3fb8aa3b, v1
	v_mul_f32_e32 v2, 0x3fb8aa3b, v2
	v_mul_f32_e32 v3, 0x3fb8aa3b, v3
	v_mul_f32_e32 v4, 0x3fb8aa3b, v4
	v_mul_f32_e32 v5, 0x3fb8aa3b, v5
	v_mul_f32_e32 v6, 0x3fb8aa3b, v6
	v_mul_f32_e32 v7, 0x3fb8aa3b, v7
	v_mul_f32_e32 v8, 0x3fb8aa3b, v8
	v_mul_f32_e32 v9, 0x3fb8aa3b, v9
	v_mul_f32_e32 v10, 0x3fb8aa3b, v10
	v_mul_f32_e32 v11, 0x3fb8aa3b, v11
	v_mul_f32_e32 v12, 0x3fb8aa3b, v12
	v_mul_f32_e32 v13, 0x3fb8aa3b, v13
	v_mul_f32_e32 v14, 0x3fb8aa3b, v14
	v_mul_f32_e32 v15, 0x3fb8aa3b, v15
	v_exp_f32_e32 v0, v0
	v_exp_f32_e32 v1, v1
	v_exp_f32_e32 v2, v2
	v_exp_f32_e32 v3, v3
	v_exp_f32_e32 v4, v4
	v_exp_f32_e32 v5, v5
	v_exp_f32_e32 v6, v6
	v_exp_f32_e32 v7, v7
	v_exp_f32_e32 v8, v8
	v_exp_f32_e32 v9, v9
	v_exp_f32_e32 v10, v10
	v_exp_f32_e32 v11, v11
	v_exp_f32_e32 v12, v12
	v_exp_f32_e32 v13, v13
	v_exp_f32_e32 v14, v14
	v_exp_f32_e32 v15, v15
	s_nop 0
	v_cndmask_b32_e64 v0, v0, 1.0, s[24:25]
	v_cndmask_b32_e64 v1, v1, 1.0, s[24:25]
	v_cndmask_b32_e64 v2, v2, 1.0, s[24:25]
	v_cndmask_b32_e64 v3, v3, 1.0, s[24:25]
	v_cndmask_b32_e64 v4, v4, 1.0, s[24:25]
	v_cndmask_b32_e64 v5, v5, 1.0, s[24:25]
	v_cndmask_b32_e64 v6, v6, 1.0, s[24:25]
	v_cndmask_b32_e64 v7, v7, 1.0, s[24:25]
	v_cndmask_b32_e64 v8, v8, 1.0, s[24:25]
	v_cndmask_b32_e64 v9, v9, 1.0, s[24:25]
	v_cndmask_b32_e64 v10, v10, 1.0, s[24:25]
	v_cndmask_b32_e64 v11, v11, 1.0, s[24:25]
	v_cndmask_b32_e64 v12, v12, 1.0, s[24:25]
	v_cndmask_b32_e64 v13, v13, 1.0, s[24:25]
	v_cndmask_b32_e64 v14, v14, 1.0, s[24:25]
	v_cndmask_b32_e64 v15, v15, 1.0, s[24:25]
	v_mul_f32_e32 v16, v16, v0
	v_mul_f32_e32 v17, v17, v1
	v_mul_f32_e32 v18, v18, v2
	v_mul_f32_e32 v19, v19, v3
	v_mul_f32_e32 v20, v20, v4
	v_mul_f32_e32 v21, v21, v5
	v_mul_f32_e32 v22, v22, v6
	v_mul_f32_e32 v23, v23, v7
	v_mul_f32_e32 v24, v24, v8
	v_mul_f32_e32 v25, v25, v9
	v_mul_f32_e32 v26, v26, v10
	v_mul_f32_e32 v27, v27, v11
	v_mul_f32_e32 v28, v28, v12
	v_mul_f32_e32 v29, v29, v13
	v_mul_f32_e32 v30, v30, v14
	v_mul_f32_e32 v31, v31, v15
	v_mul_f32_e32 v192, v192, v16
	v_mul_f32_e32 v193, v193, v17
	v_mul_f32_e32 v194, v194, v18
	v_mul_f32_e32 v195, v195, v19
	v_mul_f32_e32 v196, v196, v20
	v_mul_f32_e32 v197, v197, v21
	v_mul_f32_e32 v198, v198, v22
	v_mul_f32_e32 v199, v199, v23
	v_mul_f32_e32 v200, v200, v24
	v_mul_f32_e32 v201, v201, v25
	v_mul_f32_e32 v202, v202, v26
	v_mul_f32_e32 v203, v203, v27
	v_mul_f32_e32 v204, v204, v28
	v_mul_f32_e32 v205, v205, v29
	v_mul_f32_e32 v206, v206, v30
	v_mul_f32_e32 v207, v207, v31
	ds_read_b128 v[16:19], v64 offset:192
	ds_read_b128 v[20:23], v64 offset:208
	ds_read_b128 v[24:27], v64 offset:224
	ds_read_b128 v[28:31], v64 offset:240
	ds_read_b128 v[0:3], v64 offset:448
	ds_read_b128 v[4:7], v64 offset:464
	ds_read_b128 v[8:11], v64 offset:480
	ds_read_b128 v[12:15], v64 offset:496
	s_waitcnt lgkmcnt(0)
	v_mul_f32_e32 v0, 0x3fb8aa3b, v0
	v_mul_f32_e32 v1, 0x3fb8aa3b, v1
	v_mul_f32_e32 v2, 0x3fb8aa3b, v2
	v_mul_f32_e32 v3, 0x3fb8aa3b, v3
	v_mul_f32_e32 v4, 0x3fb8aa3b, v4
	v_mul_f32_e32 v5, 0x3fb8aa3b, v5
	v_mul_f32_e32 v6, 0x3fb8aa3b, v6
	v_mul_f32_e32 v7, 0x3fb8aa3b, v7
	v_mul_f32_e32 v8, 0x3fb8aa3b, v8
	v_mul_f32_e32 v9, 0x3fb8aa3b, v9
	v_mul_f32_e32 v10, 0x3fb8aa3b, v10
	v_mul_f32_e32 v11, 0x3fb8aa3b, v11
	v_mul_f32_e32 v12, 0x3fb8aa3b, v12
	v_mul_f32_e32 v13, 0x3fb8aa3b, v13
	v_mul_f32_e32 v14, 0x3fb8aa3b, v14
	v_mul_f32_e32 v15, 0x3fb8aa3b, v15
	v_exp_f32_e32 v0, v0
	v_exp_f32_e32 v1, v1
	v_exp_f32_e32 v2, v2
	v_exp_f32_e32 v3, v3
	v_exp_f32_e32 v4, v4
	v_exp_f32_e32 v5, v5
	v_exp_f32_e32 v6, v6
	v_exp_f32_e32 v7, v7
	v_exp_f32_e32 v8, v8
	v_exp_f32_e32 v9, v9
	v_exp_f32_e32 v10, v10
	v_exp_f32_e32 v11, v11
	v_exp_f32_e32 v12, v12
	v_exp_f32_e32 v13, v13
	v_exp_f32_e32 v14, v14
	v_exp_f32_e32 v15, v15
	s_nop 0
	v_cndmask_b32_e64 v0, v0, 1.0, s[24:25]
	v_cndmask_b32_e64 v1, v1, 1.0, s[24:25]
	v_cndmask_b32_e64 v2, v2, 1.0, s[24:25]
	v_cndmask_b32_e64 v3, v3, 1.0, s[24:25]
	v_cndmask_b32_e64 v4, v4, 1.0, s[24:25]
	v_cndmask_b32_e64 v5, v5, 1.0, s[24:25]
	v_cndmask_b32_e64 v6, v6, 1.0, s[24:25]
	v_cndmask_b32_e64 v7, v7, 1.0, s[24:25]
	v_cndmask_b32_e64 v8, v8, 1.0, s[24:25]
	v_cndmask_b32_e64 v9, v9, 1.0, s[24:25]
	v_cndmask_b32_e64 v10, v10, 1.0, s[24:25]
	v_cndmask_b32_e64 v11, v11, 1.0, s[24:25]
	v_cndmask_b32_e64 v12, v12, 1.0, s[24:25]
	v_cndmask_b32_e64 v13, v13, 1.0, s[24:25]
	v_cndmask_b32_e64 v14, v14, 1.0, s[24:25]
	v_cndmask_b32_e64 v15, v15, 1.0, s[24:25]
	v_mul_f32_e32 v16, v16, v0
	v_mul_f32_e32 v17, v17, v1
	v_mul_f32_e32 v18, v18, v2
	v_mul_f32_e32 v19, v19, v3
	v_mul_f32_e32 v20, v20, v4
	v_mul_f32_e32 v21, v21, v5
	v_mul_f32_e32 v22, v22, v6
	v_mul_f32_e32 v23, v23, v7
	v_mul_f32_e32 v24, v24, v8
	v_mul_f32_e32 v25, v25, v9
	v_mul_f32_e32 v26, v26, v10
	v_mul_f32_e32 v27, v27, v11
	v_mul_f32_e32 v28, v28, v12
	v_mul_f32_e32 v29, v29, v13
	v_mul_f32_e32 v30, v30, v14
	v_mul_f32_e32 v31, v31, v15
	v_mul_f32_e32 v208, v208, v16
	v_mul_f32_e32 v209, v209, v17
	v_mul_f32_e32 v210, v210, v18
	v_mul_f32_e32 v211, v211, v19
	v_mul_f32_e32 v212, v212, v20
	v_mul_f32_e32 v213, v213, v21
	v_mul_f32_e32 v214, v214, v22
	v_mul_f32_e32 v215, v215, v23
	v_mul_f32_e32 v216, v216, v24
	v_mul_f32_e32 v217, v217, v25
	v_mul_f32_e32 v218, v218, v26
	v_mul_f32_e32 v219, v219, v27
	v_mul_f32_e32 v220, v220, v28
	v_mul_f32_e32 v221, v221, v29
	v_mul_f32_e32 v222, v222, v30
	v_mul_f32_e32 v223, v223, v31
	ds_read_b128 v[48:51], v63 offset:272
	ds_read_b128 v[52:55], v63 offset:544
	ds_read_b128 v[56:59], v63 offset:816
	ds_read_b128 v[0:3], v63 offset:1088
	ds_read_b128 v[4:7], v63 offset:1360
	ds_read_b128 v[8:11], v63 offset:1632
	ds_read_b128 v[12:15], v63 offset:1904
	ds_read_b128 v[16:19], v63 offset:2176
	ds_read_b128 v[20:23], v63 offset:2448
	ds_read_b128 v[24:27], v63 offset:2720
	ds_read_b128 v[28:31], v63 offset:2992
	s_waitcnt lgkmcnt(10)
	v_fma_f32 v161, -v48, v160, v161
	s_waitcnt lgkmcnt(9)
	v_fma_f32 v162, -v52, v160, v162
	s_waitcnt lgkmcnt(8)
	v_fma_f32 v163, -v56, v160, v163
	v_fma_f32 v162, -v53, v161, v162
	v_fma_f32 v163, -v57, v161, v163
	v_fma_f32 v163, -v58, v162, v163
	ds_read_b128 v[48:51], v63 offset:1376
	ds_read_b128 v[52:55], v63 offset:1648
	ds_read_b128 v[56:59], v63 offset:1920
	ds_read_b128 v[32:35], v63 offset:3264
	ds_read_b128 v[36:39], v63 offset:3536
	ds_read_b128 v[40:43], v63 offset:3808
	ds_read_b128 v[44:47], v63 offset:4080
	s_waitcnt lgkmcnt(14)
	v_fma_f32 v164, -v0, v160, v164
	s_waitcnt lgkmcnt(13)
	v_fma_f32 v165, -v4, v160, v165
	s_waitcnt lgkmcnt(12)
	v_fma_f32 v166, -v8, v160, v166
	s_waitcnt lgkmcnt(11)
	v_fma_f32 v167, -v12, v160, v167
	v_fma_f32 v164, -v1, v161, v164
	v_fma_f32 v165, -v5, v161, v165
	v_fma_f32 v166, -v9, v161, v166
	v_fma_f32 v167, -v13, v161, v167
	v_fma_f32 v164, -v2, v162, v164
	v_fma_f32 v165, -v6, v162, v165
	v_fma_f32 v166, -v10, v162, v166
	v_fma_f32 v167, -v14, v162, v167
	v_fma_f32 v164, -v3, v163, v164
	v_fma_f32 v165, -v7, v163, v165
	v_fma_f32 v166, -v11, v163, v166
	v_fma_f32 v167, -v15, v163, v167
	ds_read_b128 v[0:3], v63 offset:4352
	ds_read_b128 v[4:7], v63 offset:4624
	ds_read_b128 v[8:11], v63 offset:4896
	ds_read_b128 v[12:15], v63 offset:5168
	s_waitcnt lgkmcnt(14)
	v_fma_f32 v168, -v16, v160, v168
	s_waitcnt lgkmcnt(13)
	v_fma_f32 v169, -v20, v160, v169
	s_waitcnt lgkmcnt(10)
	v_fma_f32 v165, -v48, v164, v165
	s_waitcnt lgkmcnt(12)
	v_fma_f32 v170, -v24, v160, v170
	s_waitcnt lgkmcnt(11)
	v_fma_f32 v171, -v28, v160, v171
	s_waitcnt lgkmcnt(9)
	v_fma_f32 v166, -v52, v164, v166
	v_fma_f32 v168, -v17, v161, v168
	v_fma_f32 v169, -v21, v161, v169
	s_waitcnt lgkmcnt(8)
	v_fma_f32 v167, -v56, v164, v167
	v_fma_f32 v170, -v25, v161, v170
	v_fma_f32 v171, -v29, v161, v171
	v_fma_f32 v166, -v53, v165, v166
	v_fma_f32 v168, -v18, v162, v168
	v_fma_f32 v169, -v22, v162, v169
	v_fma_f32 v167, -v57, v165, v167
	v_fma_f32 v170, -v26, v162, v170
	v_fma_f32 v171, -v30, v162, v171
	v_fma_f32 v167, -v58, v166, v167
	v_fma_f32 v168, -v19, v163, v168
	v_fma_f32 v169, -v23, v163, v169
	v_fma_f32 v170, -v27, v163, v170
	v_fma_f32 v171, -v31, v163, v171
	ds_read_b128 v[16:19], v63 offset:5440
	ds_read_b128 v[20:23], v63 offset:5712
	ds_read_b128 v[24:27], v63 offset:5984
	ds_read_b128 v[28:31], v63 offset:6256
	s_waitcnt lgkmcnt(11)
	v_fma_f32 v172, -v32, v160, v172
	s_waitcnt lgkmcnt(10)
	v_fma_f32 v173, -v36, v160, v173
	s_waitcnt lgkmcnt(9)
	v_fma_f32 v174, -v40, v160, v174
	s_waitcnt lgkmcnt(8)
	v_fma_f32 v175, -v44, v160, v175
	v_fma_f32 v172, -v33, v161, v172
	v_fma_f32 v173, -v37, v161, v173
	v_fma_f32 v174, -v41, v161, v174
	v_fma_f32 v175, -v45, v161, v175
	v_fma_f32 v172, -v34, v162, v172
	v_fma_f32 v173, -v38, v162, v173
	v_fma_f32 v174, -v42, v162, v174
	v_fma_f32 v175, -v46, v162, v175
	v_fma_f32 v172, -v35, v163, v172
	v_fma_f32 v173, -v39, v163, v173
	v_fma_f32 v174, -v43, v163, v174
	v_fma_f32 v175, -v47, v163, v175
	ds_read_b128 v[32:35], v63 offset:6528
	ds_read_b128 v[36:39], v63 offset:6800
	ds_read_b128 v[40:43], v63 offset:7072
	ds_read_b128 v[44:47], v63 offset:7344
	s_waitcnt lgkmcnt(11)
	v_fma_f32 v176, -v0, v160, v176
	s_waitcnt lgkmcnt(10)
	v_fma_f32 v177, -v4, v160, v177
	s_waitcnt lgkmcnt(9)
	v_fma_f32 v178, -v8, v160, v178
	s_waitcnt lgkmcnt(8)
	v_fma_f32 v179, -v12, v160, v179
	v_fma_f32 v176, -v1, v161, v176
	v_fma_f32 v177, -v5, v161, v177
	v_fma_f32 v178, -v9, v161, v178
	v_fma_f32 v179, -v13, v161, v179
	v_fma_f32 v176, -v2, v162, v176
	v_fma_f32 v177, -v6, v162, v177
	v_fma_f32 v178, -v10, v162, v178
	v_fma_f32 v179, -v14, v162, v179
	v_fma_f32 v176, -v3, v163, v176
	v_fma_f32 v177, -v7, v163, v177
	v_fma_f32 v178, -v11, v163, v178
	v_fma_f32 v179, -v15, v163, v179
	ds_read_b128 v[0:3], v63 offset:7616
	ds_read_b128 v[4:7], v63 offset:7888
	ds_read_b128 v[8:11], v63 offset:8160
	ds_read_b128 v[12:15], v63 offset:8432
	s_waitcnt lgkmcnt(11)
	v_fma_f32 v180, -v16, v160, v180
	s_waitcnt lgkmcnt(10)
	v_fma_f32 v181, -v20, v160, v181
	s_waitcnt lgkmcnt(9)
	v_fma_f32 v182, -v24, v160, v182
	s_waitcnt lgkmcnt(8)
	v_fma_f32 v183, -v28, v160, v183
	v_fma_f32 v180, -v17, v161, v180
	v_fma_f32 v181, -v21, v161, v181
	v_fma_f32 v182, -v25, v161, v182
	v_fma_f32 v183, -v29, v161, v183
	v_fma_f32 v180, -v18, v162, v180
	v_fma_f32 v181, -v22, v162, v181
	v_fma_f32 v182, -v26, v162, v182
	v_fma_f32 v183, -v30, v162, v183
	v_fma_f32 v180, -v19, v163, v180
	v_fma_f32 v181, -v23, v163, v181
	v_fma_f32 v182, -v27, v163, v182
	v_fma_f32 v183, -v31, v163, v183
	ds_read_b128 v[16:19], v63 offset:8704
	ds_read_b128 v[20:23], v63 offset:8976
	ds_read_b128 v[24:27], v63 offset:9248
	ds_read_b128 v[28:31], v63 offset:9520
	s_waitcnt lgkmcnt(11)
	v_fma_f32 v184, -v32, v160, v184
	s_waitcnt lgkmcnt(10)
	v_fma_f32 v185, -v36, v160, v185
	s_waitcnt lgkmcnt(9)
	v_fma_f32 v186, -v40, v160, v186
	s_waitcnt lgkmcnt(8)
	v_fma_f32 v187, -v44, v160, v187
	v_fma_f32 v184, -v33, v161, v184
	v_fma_f32 v185, -v37, v161, v185
	v_fma_f32 v186, -v41, v161, v186
	v_fma_f32 v187, -v45, v161, v187
	v_fma_f32 v184, -v34, v162, v184
	v_fma_f32 v185, -v38, v162, v185
	v_fma_f32 v186, -v42, v162, v186
	v_fma_f32 v187, -v46, v162, v187
	v_fma_f32 v184, -v35, v163, v184
	v_fma_f32 v185, -v39, v163, v185
	v_fma_f32 v186, -v43, v163, v186
	v_fma_f32 v187, -v47, v163, v187
	ds_read_b128 v[32:35], v63 offset:9792
	ds_read_b128 v[36:39], v63 offset:10064
	ds_read_b128 v[40:43], v63 offset:10336
	ds_read_b128 v[44:47], v63 offset:10608
	s_waitcnt lgkmcnt(11)
	v_fma_f32 v188, -v0, v160, v188
	s_waitcnt lgkmcnt(10)
	v_fma_f32 v189, -v4, v160, v189
	s_waitcnt lgkmcnt(9)
	v_fma_f32 v190, -v8, v160, v190
	s_waitcnt lgkmcnt(8)
	v_fma_f32 v191, -v12, v160, v191
	v_fma_f32 v188, -v1, v161, v188
	v_fma_f32 v189, -v5, v161, v189
	v_fma_f32 v190, -v9, v161, v190
	v_fma_f32 v191, -v13, v161, v191
	v_fma_f32 v188, -v2, v162, v188
	v_fma_f32 v189, -v6, v162, v189
	v_fma_f32 v190, -v10, v162, v190
	v_fma_f32 v191, -v14, v162, v191
	v_fma_f32 v188, -v3, v163, v188
	v_fma_f32 v189, -v7, v163, v189
	v_fma_f32 v190, -v11, v163, v190
	v_fma_f32 v191, -v15, v163, v191
	ds_read_b128 v[0:3], v63 offset:10880
	ds_read_b128 v[4:7], v63 offset:11152
	ds_read_b128 v[8:11], v63 offset:11424
	ds_read_b128 v[12:15], v63 offset:11696
	s_waitcnt lgkmcnt(11)
	v_fma_f32 v192, -v16, v160, v192
	s_waitcnt lgkmcnt(10)
	v_fma_f32 v193, -v20, v160, v193
	s_waitcnt lgkmcnt(9)
	v_fma_f32 v194, -v24, v160, v194
	s_waitcnt lgkmcnt(8)
	v_fma_f32 v195, -v28, v160, v195
	v_fma_f32 v192, -v17, v161, v192
	v_fma_f32 v193, -v21, v161, v193
	v_fma_f32 v194, -v25, v161, v194
	v_fma_f32 v195, -v29, v161, v195
	v_fma_f32 v192, -v18, v162, v192
	v_fma_f32 v193, -v22, v162, v193
	v_fma_f32 v194, -v26, v162, v194
	v_fma_f32 v195, -v30, v162, v195
	v_fma_f32 v192, -v19, v163, v192
	v_fma_f32 v193, -v23, v163, v193
	v_fma_f32 v194, -v27, v163, v194
	v_fma_f32 v195, -v31, v163, v195
	ds_read_b128 v[16:19], v63 offset:11968
	ds_read_b128 v[20:23], v63 offset:12240
	ds_read_b128 v[24:27], v63 offset:12512
	ds_read_b128 v[28:31], v63 offset:12784
	s_waitcnt lgkmcnt(11)
	v_fma_f32 v196, -v32, v160, v196
	s_waitcnt lgkmcnt(10)
	v_fma_f32 v197, -v36, v160, v197
	s_waitcnt lgkmcnt(9)
	v_fma_f32 v198, -v40, v160, v198
	s_waitcnt lgkmcnt(8)
	v_fma_f32 v199, -v44, v160, v199
	v_fma_f32 v196, -v33, v161, v196
	v_fma_f32 v197, -v37, v161, v197
	v_fma_f32 v198, -v41, v161, v198
	v_fma_f32 v199, -v45, v161, v199
	v_fma_f32 v196, -v34, v162, v196
	v_fma_f32 v197, -v38, v162, v197
	v_fma_f32 v198, -v42, v162, v198
	v_fma_f32 v199, -v46, v162, v199
	v_fma_f32 v196, -v35, v163, v196
	v_fma_f32 v197, -v39, v163, v197
	v_fma_f32 v198, -v43, v163, v198
	v_fma_f32 v199, -v47, v163, v199
	ds_read_b128 v[32:35], v63 offset:13056
	ds_read_b128 v[36:39], v63 offset:13328
	ds_read_b128 v[40:43], v63 offset:13600
	ds_read_b128 v[44:47], v63 offset:13872
	s_waitcnt lgkmcnt(11)
	v_fma_f32 v200, -v0, v160, v200
	s_waitcnt lgkmcnt(10)
	v_fma_f32 v201, -v4, v160, v201
	s_waitcnt lgkmcnt(9)
	v_fma_f32 v202, -v8, v160, v202
	s_waitcnt lgkmcnt(8)
	v_fma_f32 v203, -v12, v160, v203
	v_fma_f32 v200, -v1, v161, v200
	v_fma_f32 v201, -v5, v161, v201
	v_fma_f32 v202, -v9, v161, v202
	v_fma_f32 v203, -v13, v161, v203
	v_fma_f32 v200, -v2, v162, v200
	v_fma_f32 v201, -v6, v162, v201
	v_fma_f32 v202, -v10, v162, v202
	v_fma_f32 v203, -v14, v162, v203
	v_fma_f32 v200, -v3, v163, v200
	v_fma_f32 v201, -v7, v163, v201
	v_fma_f32 v202, -v11, v163, v202
	v_fma_f32 v203, -v15, v163, v203
	ds_read_b128 v[0:3], v63 offset:14144
	ds_read_b128 v[4:7], v63 offset:14416
	ds_read_b128 v[8:11], v63 offset:14688
	ds_read_b128 v[12:15], v63 offset:14960
	s_waitcnt lgkmcnt(11)
	v_fma_f32 v204, -v16, v160, v204
	s_waitcnt lgkmcnt(10)
	v_fma_f32 v205, -v20, v160, v205
	s_waitcnt lgkmcnt(9)
	v_fma_f32 v206, -v24, v160, v206
	s_waitcnt lgkmcnt(8)
	v_fma_f32 v207, -v28, v160, v207
	v_fma_f32 v204, -v17, v161, v204
	v_fma_f32 v205, -v21, v161, v205
	v_fma_f32 v206, -v25, v161, v206
	v_fma_f32 v207, -v29, v161, v207
	v_fma_f32 v204, -v18, v162, v204
	v_fma_f32 v205, -v22, v162, v205
	v_fma_f32 v206, -v26, v162, v206
	v_fma_f32 v207, -v30, v162, v207
	v_fma_f32 v204, -v19, v163, v204
	v_fma_f32 v205, -v23, v163, v205
	v_fma_f32 v206, -v27, v163, v206
	v_fma_f32 v207, -v31, v163, v207
	ds_read_b128 v[16:19], v63 offset:15232
	ds_read_b128 v[20:23], v63 offset:15504
	ds_read_b128 v[24:27], v63 offset:15776
	ds_read_b128 v[28:31], v63 offset:16048
	s_waitcnt lgkmcnt(11)
	v_fma_f32 v208, -v32, v160, v208
	s_waitcnt lgkmcnt(10)
	v_fma_f32 v209, -v36, v160, v209
	s_waitcnt lgkmcnt(9)
	v_fma_f32 v210, -v40, v160, v210
	s_waitcnt lgkmcnt(8)
	v_fma_f32 v211, -v44, v160, v211
	v_fma_f32 v208, -v33, v161, v208
	v_fma_f32 v209, -v37, v161, v209
	v_fma_f32 v210, -v41, v161, v210
	v_fma_f32 v211, -v45, v161, v211
	v_fma_f32 v208, -v34, v162, v208
	v_fma_f32 v209, -v38, v162, v209
	v_fma_f32 v210, -v42, v162, v210
	v_fma_f32 v211, -v46, v162, v211
	v_fma_f32 v208, -v35, v163, v208
	v_fma_f32 v209, -v39, v163, v209
	v_fma_f32 v210, -v43, v163, v210
	v_fma_f32 v211, -v47, v163, v211
	ds_read_b128 v[32:35], v63 offset:16320
	ds_read_b128 v[36:39], v63 offset:16592
	ds_read_b128 v[40:43], v63 offset:16864
	ds_read_b128 v[44:47], v63 offset:17136
	s_waitcnt lgkmcnt(11)
	v_fma_f32 v212, -v0, v160, v212
	s_waitcnt lgkmcnt(10)
	v_fma_f32 v213, -v4, v160, v213
	s_waitcnt lgkmcnt(9)
	v_fma_f32 v214, -v8, v160, v214
	s_waitcnt lgkmcnt(8)
	v_fma_f32 v215, -v12, v160, v215
	v_fma_f32 v212, -v1, v161, v212
	v_fma_f32 v213, -v5, v161, v213
	v_fma_f32 v214, -v9, v161, v214
	v_fma_f32 v215, -v13, v161, v215
	v_fma_f32 v212, -v2, v162, v212
	v_fma_f32 v213, -v6, v162, v213
	v_fma_f32 v214, -v10, v162, v214
	v_fma_f32 v215, -v14, v162, v215
	v_fma_f32 v212, -v3, v163, v212
	v_fma_f32 v213, -v7, v163, v213
	v_fma_f32 v214, -v11, v163, v214
	v_fma_f32 v215, -v15, v163, v215
	ds_read_b128 v[0:3], v63 offset:2192
	ds_read_b128 v[4:7], v63 offset:2464
	ds_read_b128 v[8:11], v63 offset:2736
	ds_read_b128 v[12:15], v63 offset:3008
	s_waitcnt lgkmcnt(11)
	v_fma_f32 v216, -v16, v160, v216
	s_waitcnt lgkmcnt(10)
	v_fma_f32 v217, -v20, v160, v217
	s_waitcnt lgkmcnt(9)
	v_fma_f32 v218, -v24, v160, v218
	s_waitcnt lgkmcnt(8)
	v_fma_f32 v219, -v28, v160, v219
	v_fma_f32 v216, -v17, v161, v216
	v_fma_f32 v217, -v21, v161, v217
	v_fma_f32 v218, -v25, v161, v218
	v_fma_f32 v219, -v29, v161, v219
	v_fma_f32 v216, -v18, v162, v216
	v_fma_f32 v217, -v22, v162, v217
	v_fma_f32 v218, -v26, v162, v218
	v_fma_f32 v219, -v30, v162, v219
	v_fma_f32 v216, -v19, v163, v216
	v_fma_f32 v217, -v23, v163, v217
	v_fma_f32 v218, -v27, v163, v218
	v_fma_f32 v219, -v31, v163, v219
	ds_read_b128 v[16:19], v63 offset:3280
	ds_read_b128 v[20:23], v63 offset:3552
	ds_read_b128 v[24:27], v63 offset:3824
	ds_read_b128 v[28:31], v63 offset:4096
	s_waitcnt lgkmcnt(11)
	v_fma_f32 v220, -v32, v160, v220
	s_waitcnt lgkmcnt(10)
	v_fma_f32 v221, -v36, v160, v221
	s_waitcnt lgkmcnt(9)
	v_fma_f32 v222, -v40, v160, v222
	s_waitcnt lgkmcnt(8)
	v_fma_f32 v223, -v44, v160, v223
	v_fma_f32 v220, -v33, v161, v220
	v_fma_f32 v221, -v37, v161, v221
	v_fma_f32 v222, -v41, v161, v222
	v_fma_f32 v223, -v45, v161, v223
	v_fma_f32 v220, -v34, v162, v220
	v_fma_f32 v221, -v38, v162, v221
	v_fma_f32 v222, -v42, v162, v222
	v_fma_f32 v223, -v46, v162, v223
	v_fma_f32 v220, -v35, v163, v220
	v_fma_f32 v221, -v39, v163, v221
	v_fma_f32 v222, -v43, v163, v222
	v_fma_f32 v223, -v47, v163, v223
	ds_read_b128 v[48:51], v63 offset:2480
	ds_read_b128 v[52:55], v63 offset:2752
	ds_read_b128 v[56:59], v63 offset:3024
	ds_read_b128 v[32:35], v63 offset:4368
	ds_read_b128 v[36:39], v63 offset:4640
	ds_read_b128 v[40:43], v63 offset:4912
	ds_read_b128 v[44:47], v63 offset:5184
	s_waitcnt lgkmcnt(14)
	v_fma_f32 v168, -v0, v164, v168
	s_waitcnt lgkmcnt(13)
	v_fma_f32 v169, -v4, v164, v169
	s_waitcnt lgkmcnt(12)
	v_fma_f32 v170, -v8, v164, v170
	s_waitcnt lgkmcnt(11)
	v_fma_f32 v171, -v12, v164, v171
	v_fma_f32 v168, -v1, v165, v168
	v_fma_f32 v169, -v5, v165, v169
	v_fma_f32 v170, -v9, v165, v170
	v_fma_f32 v171, -v13, v165, v171
	v_fma_f32 v168, -v2, v166, v168
	v_fma_f32 v169, -v6, v166, v169
	v_fma_f32 v170, -v10, v166, v170
	v_fma_f32 v171, -v14, v166, v171
	v_fma_f32 v168, -v3, v167, v168
	v_fma_f32 v169, -v7, v167, v169
	v_fma_f32 v170, -v11, v167, v170
	v_fma_f32 v171, -v15, v167, v171
	ds_read_b128 v[0:3], v63 offset:5456
	ds_read_b128 v[4:7], v63 offset:5728
	ds_read_b128 v[8:11], v63 offset:6000
	ds_read_b128 v[12:15], v63 offset:6272
	s_waitcnt lgkmcnt(14)
	v_fma_f32 v172, -v16, v164, v172
	s_waitcnt lgkmcnt(13)
	v_fma_f32 v173, -v20, v164, v173
	s_waitcnt lgkmcnt(10)
	v_fma_f32 v169, -v48, v168, v169
	s_waitcnt lgkmcnt(12)
	v_fma_f32 v174, -v24, v164, v174
	s_waitcnt lgkmcnt(11)
	v_fma_f32 v175, -v28, v164, v175
	s_waitcnt lgkmcnt(9)
	v_fma_f32 v170, -v52, v168, v170
	v_fma_f32 v172, -v17, v165, v172
	v_fma_f32 v173, -v21, v165, v173
	s_waitcnt lgkmcnt(8)
	v_fma_f32 v171, -v56, v168, v171
	v_fma_f32 v174, -v25, v165, v174
	v_fma_f32 v175, -v29, v165, v175
	v_fma_f32 v170, -v53, v169, v170
	v_fma_f32 v172, -v18, v166, v172
	v_fma_f32 v173, -v22, v166, v173
	v_fma_f32 v171, -v57, v169, v171
	v_fma_f32 v174, -v26, v166, v174
	v_fma_f32 v175, -v30, v166, v175
	v_fma_f32 v171, -v58, v170, v171
	v_fma_f32 v172, -v19, v167, v172
	v_fma_f32 v173, -v23, v167, v173
	v_fma_f32 v174, -v27, v167, v174
	v_fma_f32 v175, -v31, v167, v175
	ds_read_b128 v[16:19], v63 offset:6544
	ds_read_b128 v[20:23], v63 offset:6816
	ds_read_b128 v[24:27], v63 offset:7088
	ds_read_b128 v[28:31], v63 offset:7360
	s_waitcnt lgkmcnt(11)
	v_fma_f32 v176, -v32, v164, v176
	s_waitcnt lgkmcnt(10)
	v_fma_f32 v177, -v36, v164, v177
	s_waitcnt lgkmcnt(9)
	v_fma_f32 v178, -v40, v164, v178
	s_waitcnt lgkmcnt(8)
	v_fma_f32 v179, -v44, v164, v179
	v_fma_f32 v176, -v33, v165, v176
	v_fma_f32 v177, -v37, v165, v177
	v_fma_f32 v178, -v41, v165, v178
	v_fma_f32 v179, -v45, v165, v179
	v_fma_f32 v176, -v34, v166, v176
	v_fma_f32 v177, -v38, v166, v177
	v_fma_f32 v178, -v42, v166, v178
	v_fma_f32 v179, -v46, v166, v179
	v_fma_f32 v176, -v35, v167, v176
	v_fma_f32 v177, -v39, v167, v177
	v_fma_f32 v178, -v43, v167, v178
	v_fma_f32 v179, -v47, v167, v179
	ds_read_b128 v[32:35], v63 offset:7632
	ds_read_b128 v[36:39], v63 offset:7904
	ds_read_b128 v[40:43], v63 offset:8176
	ds_read_b128 v[44:47], v63 offset:8448
	s_waitcnt lgkmcnt(11)
	v_fma_f32 v180, -v0, v164, v180
	s_waitcnt lgkmcnt(10)
	v_fma_f32 v181, -v4, v164, v181
	s_waitcnt lgkmcnt(9)
	v_fma_f32 v182, -v8, v164, v182
	s_waitcnt lgkmcnt(8)
	v_fma_f32 v183, -v12, v164, v183
	v_fma_f32 v180, -v1, v165, v180
	v_fma_f32 v181, -v5, v165, v181
	v_fma_f32 v182, -v9, v165, v182
	v_fma_f32 v183, -v13, v165, v183
	v_fma_f32 v180, -v2, v166, v180
	v_fma_f32 v181, -v6, v166, v181
	v_fma_f32 v182, -v10, v166, v182
	v_fma_f32 v183, -v14, v166, v183
	v_fma_f32 v180, -v3, v167, v180
	v_fma_f32 v181, -v7, v167, v181
	v_fma_f32 v182, -v11, v167, v182
	v_fma_f32 v183, -v15, v167, v183
	ds_read_b128 v[0:3], v63 offset:8720
	ds_read_b128 v[4:7], v63 offset:8992
	ds_read_b128 v[8:11], v63 offset:9264
	ds_read_b128 v[12:15], v63 offset:9536
	s_waitcnt lgkmcnt(11)
	v_fma_f32 v184, -v16, v164, v184
	s_waitcnt lgkmcnt(10)
	v_fma_f32 v185, -v20, v164, v185
	s_waitcnt lgkmcnt(9)
	v_fma_f32 v186, -v24, v164, v186
	s_waitcnt lgkmcnt(8)
	v_fma_f32 v187, -v28, v164, v187
	v_fma_f32 v184, -v17, v165, v184
	v_fma_f32 v185, -v21, v165, v185
	v_fma_f32 v186, -v25, v165, v186
	v_fma_f32 v187, -v29, v165, v187
	v_fma_f32 v184, -v18, v166, v184
	v_fma_f32 v185, -v22, v166, v185
	v_fma_f32 v186, -v26, v166, v186
	v_fma_f32 v187, -v30, v166, v187
	v_fma_f32 v184, -v19, v167, v184
	v_fma_f32 v185, -v23, v167, v185
	v_fma_f32 v186, -v27, v167, v186
	v_fma_f32 v187, -v31, v167, v187
	ds_read_b128 v[16:19], v63 offset:9808
	ds_read_b128 v[20:23], v63 offset:10080
	ds_read_b128 v[24:27], v63 offset:10352
	ds_read_b128 v[28:31], v63 offset:10624
	s_waitcnt lgkmcnt(11)
	v_fma_f32 v188, -v32, v164, v188
	s_waitcnt lgkmcnt(10)
	v_fma_f32 v189, -v36, v164, v189
	s_waitcnt lgkmcnt(9)
	v_fma_f32 v190, -v40, v164, v190
	s_waitcnt lgkmcnt(8)
	v_fma_f32 v191, -v44, v164, v191
	v_fma_f32 v188, -v33, v165, v188
	v_fma_f32 v189, -v37, v165, v189
	v_fma_f32 v190, -v41, v165, v190
	v_fma_f32 v191, -v45, v165, v191
	v_fma_f32 v188, -v34, v166, v188
	v_fma_f32 v189, -v38, v166, v189
	v_fma_f32 v190, -v42, v166, v190
	v_fma_f32 v191, -v46, v166, v191
	v_fma_f32 v188, -v35, v167, v188
	v_fma_f32 v189, -v39, v167, v189
	v_fma_f32 v190, -v43, v167, v190
	v_fma_f32 v191, -v47, v167, v191
	ds_read_b128 v[32:35], v63 offset:10896
	ds_read_b128 v[36:39], v63 offset:11168
	ds_read_b128 v[40:43], v63 offset:11440
	ds_read_b128 v[44:47], v63 offset:11712
	s_waitcnt lgkmcnt(11)
	v_fma_f32 v192, -v0, v164, v192
	s_waitcnt lgkmcnt(10)
	v_fma_f32 v193, -v4, v164, v193
	s_waitcnt lgkmcnt(9)
	v_fma_f32 v194, -v8, v164, v194
	s_waitcnt lgkmcnt(8)
	v_fma_f32 v195, -v12, v164, v195
	v_fma_f32 v192, -v1, v165, v192
	v_fma_f32 v193, -v5, v165, v193
	v_fma_f32 v194, -v9, v165, v194
	v_fma_f32 v195, -v13, v165, v195
	v_fma_f32 v192, -v2, v166, v192
	v_fma_f32 v193, -v6, v166, v193
	v_fma_f32 v194, -v10, v166, v194
	v_fma_f32 v195, -v14, v166, v195
	v_fma_f32 v192, -v3, v167, v192
	v_fma_f32 v193, -v7, v167, v193
	v_fma_f32 v194, -v11, v167, v194
	v_fma_f32 v195, -v15, v167, v195
	ds_read_b128 v[0:3], v63 offset:11984
	ds_read_b128 v[4:7], v63 offset:12256
	ds_read_b128 v[8:11], v63 offset:12528
	ds_read_b128 v[12:15], v63 offset:12800
	s_waitcnt lgkmcnt(11)
	v_fma_f32 v196, -v16, v164, v196
	s_waitcnt lgkmcnt(10)
	v_fma_f32 v197, -v20, v164, v197
	s_waitcnt lgkmcnt(9)
	v_fma_f32 v198, -v24, v164, v198
	s_waitcnt lgkmcnt(8)
	v_fma_f32 v199, -v28, v164, v199
	v_fma_f32 v196, -v17, v165, v196
	v_fma_f32 v197, -v21, v165, v197
	v_fma_f32 v198, -v25, v165, v198
	v_fma_f32 v199, -v29, v165, v199
	v_fma_f32 v196, -v18, v166, v196
	v_fma_f32 v197, -v22, v166, v197
	v_fma_f32 v198, -v26, v166, v198
	v_fma_f32 v199, -v30, v166, v199
	v_fma_f32 v196, -v19, v167, v196
	v_fma_f32 v197, -v23, v167, v197
	v_fma_f32 v198, -v27, v167, v198
	v_fma_f32 v199, -v31, v167, v199
	ds_read_b128 v[16:19], v63 offset:13072
	ds_read_b128 v[20:23], v63 offset:13344
	ds_read_b128 v[24:27], v63 offset:13616
	ds_read_b128 v[28:31], v63 offset:13888
	s_waitcnt lgkmcnt(11)
	v_fma_f32 v200, -v32, v164, v200
	s_waitcnt lgkmcnt(10)
	v_fma_f32 v201, -v36, v164, v201
	s_waitcnt lgkmcnt(9)
	v_fma_f32 v202, -v40, v164, v202
	s_waitcnt lgkmcnt(8)
	v_fma_f32 v203, -v44, v164, v203
	v_fma_f32 v200, -v33, v165, v200
	v_fma_f32 v201, -v37, v165, v201
	v_fma_f32 v202, -v41, v165, v202
	v_fma_f32 v203, -v45, v165, v203
	v_fma_f32 v200, -v34, v166, v200
	v_fma_f32 v201, -v38, v166, v201
	v_fma_f32 v202, -v42, v166, v202
	v_fma_f32 v203, -v46, v166, v203
	v_fma_f32 v200, -v35, v167, v200
	v_fma_f32 v201, -v39, v167, v201
	v_fma_f32 v202, -v43, v167, v202
	v_fma_f32 v203, -v47, v167, v203
	ds_read_b128 v[32:35], v63 offset:14160
	ds_read_b128 v[36:39], v63 offset:14432
	ds_read_b128 v[40:43], v63 offset:14704
	ds_read_b128 v[44:47], v63 offset:14976
	s_waitcnt lgkmcnt(11)
	v_fma_f32 v204, -v0, v164, v204
	s_waitcnt lgkmcnt(10)
	v_fma_f32 v205, -v4, v164, v205
	s_waitcnt lgkmcnt(9)
	v_fma_f32 v206, -v8, v164, v206
	s_waitcnt lgkmcnt(8)
	v_fma_f32 v207, -v12, v164, v207
	v_fma_f32 v204, -v1, v165, v204
	v_fma_f32 v205, -v5, v165, v205
	v_fma_f32 v206, -v9, v165, v206
	v_fma_f32 v207, -v13, v165, v207
	v_fma_f32 v204, -v2, v166, v204
	v_fma_f32 v205, -v6, v166, v205
	v_fma_f32 v206, -v10, v166, v206
	v_fma_f32 v207, -v14, v166, v207
	v_fma_f32 v204, -v3, v167, v204
	v_fma_f32 v205, -v7, v167, v205
	v_fma_f32 v206, -v11, v167, v206
	v_fma_f32 v207, -v15, v167, v207
	ds_read_b128 v[0:3], v63 offset:15248
	ds_read_b128 v[4:7], v63 offset:15520
	ds_read_b128 v[8:11], v63 offset:15792
	ds_read_b128 v[12:15], v63 offset:16064
	s_waitcnt lgkmcnt(11)
	v_fma_f32 v208, -v16, v164, v208
	s_waitcnt lgkmcnt(10)
	v_fma_f32 v209, -v20, v164, v209
	s_waitcnt lgkmcnt(9)
	v_fma_f32 v210, -v24, v164, v210
	s_waitcnt lgkmcnt(8)
	v_fma_f32 v211, -v28, v164, v211
	v_fma_f32 v208, -v17, v165, v208
	v_fma_f32 v209, -v21, v165, v209
	v_fma_f32 v210, -v25, v165, v210
	v_fma_f32 v211, -v29, v165, v211
	v_fma_f32 v208, -v18, v166, v208
	v_fma_f32 v209, -v22, v166, v209
	v_fma_f32 v210, -v26, v166, v210
	v_fma_f32 v211, -v30, v166, v211
	v_fma_f32 v208, -v19, v167, v208
	v_fma_f32 v209, -v23, v167, v209
	v_fma_f32 v210, -v27, v167, v210
	v_fma_f32 v211, -v31, v167, v211
	ds_read_b128 v[16:19], v63 offset:16336
	ds_read_b128 v[20:23], v63 offset:16608
	ds_read_b128 v[24:27], v63 offset:16880
	ds_read_b128 v[28:31], v63 offset:17152
	s_waitcnt lgkmcnt(11)
	v_fma_f32 v212, -v32, v164, v212
	s_waitcnt lgkmcnt(10)
	v_fma_f32 v213, -v36, v164, v213
	s_waitcnt lgkmcnt(9)
	v_fma_f32 v214, -v40, v164, v214
	s_waitcnt lgkmcnt(8)
	v_fma_f32 v215, -v44, v164, v215
	v_fma_f32 v212, -v33, v165, v212
	v_fma_f32 v213, -v37, v165, v213
	v_fma_f32 v214, -v41, v165, v214
	v_fma_f32 v215, -v45, v165, v215
	v_fma_f32 v212, -v34, v166, v212
	v_fma_f32 v213, -v38, v166, v213
	v_fma_f32 v214, -v42, v166, v214
	v_fma_f32 v215, -v46, v166, v215
	v_fma_f32 v212, -v35, v167, v212
	v_fma_f32 v213, -v39, v167, v213
	v_fma_f32 v214, -v43, v167, v214
	v_fma_f32 v215, -v47, v167, v215
	ds_read_b128 v[32:35], v63 offset:3296
	ds_read_b128 v[36:39], v63 offset:3568
	ds_read_b128 v[40:43], v63 offset:3840
	ds_read_b128 v[44:47], v63 offset:4112
	s_waitcnt lgkmcnt(11)
	v_fma_f32 v216, -v0, v164, v216
	s_waitcnt lgkmcnt(10)
	v_fma_f32 v217, -v4, v164, v217
	s_waitcnt lgkmcnt(9)
	v_fma_f32 v218, -v8, v164, v218
	s_waitcnt lgkmcnt(8)
	v_fma_f32 v219, -v12, v164, v219
	v_fma_f32 v216, -v1, v165, v216
	v_fma_f32 v217, -v5, v165, v217
	v_fma_f32 v218, -v9, v165, v218
	v_fma_f32 v219, -v13, v165, v219
	v_fma_f32 v216, -v2, v166, v216
	v_fma_f32 v217, -v6, v166, v217
	v_fma_f32 v218, -v10, v166, v218
	v_fma_f32 v219, -v14, v166, v219
	v_fma_f32 v216, -v3, v167, v216
	v_fma_f32 v217, -v7, v167, v217
	v_fma_f32 v218, -v11, v167, v218
	v_fma_f32 v219, -v15, v167, v219
	ds_read_b128 v[0:3], v63 offset:4384
	ds_read_b128 v[4:7], v63 offset:4656
	ds_read_b128 v[8:11], v63 offset:4928
	ds_read_b128 v[12:15], v63 offset:5200
	s_waitcnt lgkmcnt(11)
	v_fma_f32 v220, -v16, v164, v220
	s_waitcnt lgkmcnt(10)
	v_fma_f32 v221, -v20, v164, v221
	s_waitcnt lgkmcnt(9)
	v_fma_f32 v222, -v24, v164, v222
	s_waitcnt lgkmcnt(8)
	v_fma_f32 v223, -v28, v164, v223
	v_fma_f32 v220, -v17, v165, v220
	v_fma_f32 v221, -v21, v165, v221
	v_fma_f32 v222, -v25, v165, v222
	v_fma_f32 v223, -v29, v165, v223
	v_fma_f32 v220, -v18, v166, v220
	v_fma_f32 v221, -v22, v166, v221
	v_fma_f32 v222, -v26, v166, v222
	v_fma_f32 v223, -v30, v166, v223
	v_fma_f32 v220, -v19, v167, v220
	v_fma_f32 v221, -v23, v167, v221
	v_fma_f32 v222, -v27, v167, v222
	v_fma_f32 v223, -v31, v167, v223
	ds_read_b128 v[48:51], v63 offset:3584
	ds_read_b128 v[52:55], v63 offset:3856
	ds_read_b128 v[56:59], v63 offset:4128
	ds_read_b128 v[16:19], v63 offset:5472
	ds_read_b128 v[20:23], v63 offset:5744
	ds_read_b128 v[24:27], v63 offset:6016
	ds_read_b128 v[28:31], v63 offset:6288
	s_waitcnt lgkmcnt(14)
	v_fma_f32 v172, -v32, v168, v172
	s_waitcnt lgkmcnt(13)
	v_fma_f32 v173, -v36, v168, v173
	s_waitcnt lgkmcnt(12)
	v_fma_f32 v174, -v40, v168, v174
	s_waitcnt lgkmcnt(11)
	v_fma_f32 v175, -v44, v168, v175
	v_fma_f32 v172, -v33, v169, v172
	v_fma_f32 v173, -v37, v169, v173
	v_fma_f32 v174, -v41, v169, v174
	v_fma_f32 v175, -v45, v169, v175
	v_fma_f32 v172, -v34, v170, v172
	v_fma_f32 v173, -v38, v170, v173
	v_fma_f32 v174, -v42, v170, v174
	v_fma_f32 v175, -v46, v170, v175
	v_fma_f32 v172, -v35, v171, v172
	v_fma_f32 v173, -v39, v171, v173
	v_fma_f32 v174, -v43, v171, v174
	v_fma_f32 v175, -v47, v171, v175
	ds_read_b128 v[32:35], v63 offset:6560
	ds_read_b128 v[36:39], v63 offset:6832
	ds_read_b128 v[40:43], v63 offset:7104
	ds_read_b128 v[44:47], v63 offset:7376
	s_waitcnt lgkmcnt(14)
	v_fma_f32 v176, -v0, v168, v176
	s_waitcnt lgkmcnt(13)
	v_fma_f32 v177, -v4, v168, v177
	s_waitcnt lgkmcnt(10)
	v_fma_f32 v173, -v48, v172, v173
	s_waitcnt lgkmcnt(12)
	v_fma_f32 v178, -v8, v168, v178
	s_waitcnt lgkmcnt(11)
	v_fma_f32 v179, -v12, v168, v179
	s_waitcnt lgkmcnt(9)
	v_fma_f32 v174, -v52, v172, v174
	v_fma_f32 v176, -v1, v169, v176
	v_fma_f32 v177, -v5, v169, v177
	s_waitcnt lgkmcnt(8)
	v_fma_f32 v175, -v56, v172, v175
	v_fma_f32 v178, -v9, v169, v178
	v_fma_f32 v179, -v13, v169, v179
	v_fma_f32 v174, -v53, v173, v174
	v_fma_f32 v176, -v2, v170, v176
	v_fma_f32 v177, -v6, v170, v177
	v_fma_f32 v175, -v57, v173, v175
	v_fma_f32 v178, -v10, v170, v178
	v_fma_f32 v179, -v14, v170, v179
	v_fma_f32 v175, -v58, v174, v175
	v_fma_f32 v176, -v3, v171, v176
	v_fma_f32 v177, -v7, v171, v177
	v_fma_f32 v178, -v11, v171, v178
	v_fma_f32 v179, -v15, v171, v179
	ds_read_b128 v[0:3], v63 offset:7648
	ds_read_b128 v[4:7], v63 offset:7920
	ds_read_b128 v[8:11], v63 offset:8192
	ds_read_b128 v[12:15], v63 offset:8464
	s_waitcnt lgkmcnt(11)
	v_fma_f32 v180, -v16, v168, v180
	s_waitcnt lgkmcnt(10)
	v_fma_f32 v181, -v20, v168, v181
	s_waitcnt lgkmcnt(9)
	v_fma_f32 v182, -v24, v168, v182
	s_waitcnt lgkmcnt(8)
	v_fma_f32 v183, -v28, v168, v183
	v_fma_f32 v180, -v17, v169, v180
	v_fma_f32 v181, -v21, v169, v181
	v_fma_f32 v182, -v25, v169, v182
	v_fma_f32 v183, -v29, v169, v183
	v_fma_f32 v180, -v18, v170, v180
	v_fma_f32 v181, -v22, v170, v181
	v_fma_f32 v182, -v26, v170, v182
	v_fma_f32 v183, -v30, v170, v183
	v_fma_f32 v180, -v19, v171, v180
	v_fma_f32 v181, -v23, v171, v181
	v_fma_f32 v182, -v27, v171, v182
	v_fma_f32 v183, -v31, v171, v183
	ds_read_b128 v[16:19], v63 offset:8736
	ds_read_b128 v[20:23], v63 offset:9008
	ds_read_b128 v[24:27], v63 offset:9280
	ds_read_b128 v[28:31], v63 offset:9552
	s_waitcnt lgkmcnt(11)
	v_fma_f32 v184, -v32, v168, v184
	s_waitcnt lgkmcnt(10)
	v_fma_f32 v185, -v36, v168, v185
	s_waitcnt lgkmcnt(9)
	v_fma_f32 v186, -v40, v168, v186
	s_waitcnt lgkmcnt(8)
	v_fma_f32 v187, -v44, v168, v187
	v_fma_f32 v184, -v33, v169, v184
	v_fma_f32 v185, -v37, v169, v185
	v_fma_f32 v186, -v41, v169, v186
	v_fma_f32 v187, -v45, v169, v187
	v_fma_f32 v184, -v34, v170, v184
	v_fma_f32 v185, -v38, v170, v185
	v_fma_f32 v186, -v42, v170, v186
	v_fma_f32 v187, -v46, v170, v187
	v_fma_f32 v184, -v35, v171, v184
	v_fma_f32 v185, -v39, v171, v185
	v_fma_f32 v186, -v43, v171, v186
	v_fma_f32 v187, -v47, v171, v187
	ds_read_b128 v[32:35], v63 offset:9824
	ds_read_b128 v[36:39], v63 offset:10096
	ds_read_b128 v[40:43], v63 offset:10368
	ds_read_b128 v[44:47], v63 offset:10640
	s_waitcnt lgkmcnt(11)
	v_fma_f32 v188, -v0, v168, v188
	s_waitcnt lgkmcnt(10)
	v_fma_f32 v189, -v4, v168, v189
	s_waitcnt lgkmcnt(9)
	v_fma_f32 v190, -v8, v168, v190
	s_waitcnt lgkmcnt(8)
	v_fma_f32 v191, -v12, v168, v191
	v_fma_f32 v188, -v1, v169, v188
	v_fma_f32 v189, -v5, v169, v189
	v_fma_f32 v190, -v9, v169, v190
	v_fma_f32 v191, -v13, v169, v191
	v_fma_f32 v188, -v2, v170, v188
	v_fma_f32 v189, -v6, v170, v189
	v_fma_f32 v190, -v10, v170, v190
	v_fma_f32 v191, -v14, v170, v191
	v_fma_f32 v188, -v3, v171, v188
	v_fma_f32 v189, -v7, v171, v189
	v_fma_f32 v190, -v11, v171, v190
	v_fma_f32 v191, -v15, v171, v191
	ds_read_b128 v[0:3], v63 offset:10912
	ds_read_b128 v[4:7], v63 offset:11184
	ds_read_b128 v[8:11], v63 offset:11456
	ds_read_b128 v[12:15], v63 offset:11728
	s_waitcnt lgkmcnt(11)
	v_fma_f32 v192, -v16, v168, v192
	s_waitcnt lgkmcnt(10)
	v_fma_f32 v193, -v20, v168, v193
	s_waitcnt lgkmcnt(9)
	v_fma_f32 v194, -v24, v168, v194
	s_waitcnt lgkmcnt(8)
	v_fma_f32 v195, -v28, v168, v195
	v_fma_f32 v192, -v17, v169, v192
	v_fma_f32 v193, -v21, v169, v193
	v_fma_f32 v194, -v25, v169, v194
	v_fma_f32 v195, -v29, v169, v195
	v_fma_f32 v192, -v18, v170, v192
	v_fma_f32 v193, -v22, v170, v193
	v_fma_f32 v194, -v26, v170, v194
	v_fma_f32 v195, -v30, v170, v195
	v_fma_f32 v192, -v19, v171, v192
	v_fma_f32 v193, -v23, v171, v193
	v_fma_f32 v194, -v27, v171, v194
	v_fma_f32 v195, -v31, v171, v195
	ds_read_b128 v[16:19], v63 offset:12000
	ds_read_b128 v[20:23], v63 offset:12272
	ds_read_b128 v[24:27], v63 offset:12544
	ds_read_b128 v[28:31], v63 offset:12816
	s_waitcnt lgkmcnt(11)
	v_fma_f32 v196, -v32, v168, v196
	s_waitcnt lgkmcnt(10)
	v_fma_f32 v197, -v36, v168, v197
	s_waitcnt lgkmcnt(9)
	v_fma_f32 v198, -v40, v168, v198
	s_waitcnt lgkmcnt(8)
	v_fma_f32 v199, -v44, v168, v199
	v_fma_f32 v196, -v33, v169, v196
	v_fma_f32 v197, -v37, v169, v197
	v_fma_f32 v198, -v41, v169, v198
	v_fma_f32 v199, -v45, v169, v199
	v_fma_f32 v196, -v34, v170, v196
	v_fma_f32 v197, -v38, v170, v197
	v_fma_f32 v198, -v42, v170, v198
	v_fma_f32 v199, -v46, v170, v199
	v_fma_f32 v196, -v35, v171, v196
	v_fma_f32 v197, -v39, v171, v197
	v_fma_f32 v198, -v43, v171, v198
	v_fma_f32 v199, -v47, v171, v199
	ds_read_b128 v[32:35], v63 offset:13088
	ds_read_b128 v[36:39], v63 offset:13360
	ds_read_b128 v[40:43], v63 offset:13632
	ds_read_b128 v[44:47], v63 offset:13904
	s_waitcnt lgkmcnt(11)
	v_fma_f32 v200, -v0, v168, v200
	s_waitcnt lgkmcnt(10)
	v_fma_f32 v201, -v4, v168, v201
	s_waitcnt lgkmcnt(9)
	v_fma_f32 v202, -v8, v168, v202
	s_waitcnt lgkmcnt(8)
	v_fma_f32 v203, -v12, v168, v203
	v_fma_f32 v200, -v1, v169, v200
	v_fma_f32 v201, -v5, v169, v201
	v_fma_f32 v202, -v9, v169, v202
	v_fma_f32 v203, -v13, v169, v203
	v_fma_f32 v200, -v2, v170, v200
	v_fma_f32 v201, -v6, v170, v201
	v_fma_f32 v202, -v10, v170, v202
	v_fma_f32 v203, -v14, v170, v203
	v_fma_f32 v200, -v3, v171, v200
	v_fma_f32 v201, -v7, v171, v201
	v_fma_f32 v202, -v11, v171, v202
	v_fma_f32 v203, -v15, v171, v203
	ds_read_b128 v[0:3], v63 offset:14176
	ds_read_b128 v[4:7], v63 offset:14448
	ds_read_b128 v[8:11], v63 offset:14720
	ds_read_b128 v[12:15], v63 offset:14992
	s_waitcnt lgkmcnt(11)
	v_fma_f32 v204, -v16, v168, v204
	s_waitcnt lgkmcnt(10)
	v_fma_f32 v205, -v20, v168, v205
	s_waitcnt lgkmcnt(9)
	v_fma_f32 v206, -v24, v168, v206
	s_waitcnt lgkmcnt(8)
	v_fma_f32 v207, -v28, v168, v207
	v_fma_f32 v204, -v17, v169, v204
	v_fma_f32 v205, -v21, v169, v205
	v_fma_f32 v206, -v25, v169, v206
	v_fma_f32 v207, -v29, v169, v207
	v_fma_f32 v204, -v18, v170, v204
	v_fma_f32 v205, -v22, v170, v205
	v_fma_f32 v206, -v26, v170, v206
	v_fma_f32 v207, -v30, v170, v207
	v_fma_f32 v204, -v19, v171, v204
	v_fma_f32 v205, -v23, v171, v205
	v_fma_f32 v206, -v27, v171, v206
	v_fma_f32 v207, -v31, v171, v207
	ds_read_b128 v[16:19], v63 offset:15264
	ds_read_b128 v[20:23], v63 offset:15536
	ds_read_b128 v[24:27], v63 offset:15808
	ds_read_b128 v[28:31], v63 offset:16080
	s_waitcnt lgkmcnt(11)
	v_fma_f32 v208, -v32, v168, v208
	s_waitcnt lgkmcnt(10)
	v_fma_f32 v209, -v36, v168, v209
	s_waitcnt lgkmcnt(9)
	v_fma_f32 v210, -v40, v168, v210
	s_waitcnt lgkmcnt(8)
	v_fma_f32 v211, -v44, v168, v211
	v_fma_f32 v208, -v33, v169, v208
	v_fma_f32 v209, -v37, v169, v209
	v_fma_f32 v210, -v41, v169, v210
	v_fma_f32 v211, -v45, v169, v211
	v_fma_f32 v208, -v34, v170, v208
	v_fma_f32 v209, -v38, v170, v209
	v_fma_f32 v210, -v42, v170, v210
	v_fma_f32 v211, -v46, v170, v211
	v_fma_f32 v208, -v35, v171, v208
	v_fma_f32 v209, -v39, v171, v209
	v_fma_f32 v210, -v43, v171, v210
	v_fma_f32 v211, -v47, v171, v211
	ds_read_b128 v[32:35], v63 offset:16352
	ds_read_b128 v[36:39], v63 offset:16624
	ds_read_b128 v[40:43], v63 offset:16896
	ds_read_b128 v[44:47], v63 offset:17168
	s_waitcnt lgkmcnt(11)
	v_fma_f32 v212, -v0, v168, v212
	s_waitcnt lgkmcnt(10)
	v_fma_f32 v213, -v4, v168, v213
	s_waitcnt lgkmcnt(9)
	v_fma_f32 v214, -v8, v168, v214
	s_waitcnt lgkmcnt(8)
	v_fma_f32 v215, -v12, v168, v215
	v_fma_f32 v212, -v1, v169, v212
	v_fma_f32 v213, -v5, v169, v213
	v_fma_f32 v214, -v9, v169, v214
	v_fma_f32 v215, -v13, v169, v215
	v_fma_f32 v212, -v2, v170, v212
	v_fma_f32 v213, -v6, v170, v213
	v_fma_f32 v214, -v10, v170, v214
	v_fma_f32 v215, -v14, v170, v215
	v_fma_f32 v212, -v3, v171, v212
	v_fma_f32 v213, -v7, v171, v213
	v_fma_f32 v214, -v11, v171, v214
	v_fma_f32 v215, -v15, v171, v215
	ds_read_b128 v[0:3], v63 offset:4400
	ds_read_b128 v[4:7], v63 offset:4672
	ds_read_b128 v[8:11], v63 offset:4944
	ds_read_b128 v[12:15], v63 offset:5216
	s_waitcnt lgkmcnt(11)
	v_fma_f32 v216, -v16, v168, v216
	s_waitcnt lgkmcnt(10)
	v_fma_f32 v217, -v20, v168, v217
	s_waitcnt lgkmcnt(9)
	v_fma_f32 v218, -v24, v168, v218
	s_waitcnt lgkmcnt(8)
	v_fma_f32 v219, -v28, v168, v219
	v_fma_f32 v216, -v17, v169, v216
	v_fma_f32 v217, -v21, v169, v217
	v_fma_f32 v218, -v25, v169, v218
	v_fma_f32 v219, -v29, v169, v219
	v_fma_f32 v216, -v18, v170, v216
	v_fma_f32 v217, -v22, v170, v217
	v_fma_f32 v218, -v26, v170, v218
	v_fma_f32 v219, -v30, v170, v219
	v_fma_f32 v216, -v19, v171, v216
	v_fma_f32 v217, -v23, v171, v217
	v_fma_f32 v218, -v27, v171, v218
	v_fma_f32 v219, -v31, v171, v219
	ds_read_b128 v[16:19], v63 offset:5488
	ds_read_b128 v[20:23], v63 offset:5760
	ds_read_b128 v[24:27], v63 offset:6032
	ds_read_b128 v[28:31], v63 offset:6304
	s_waitcnt lgkmcnt(11)
	v_fma_f32 v220, -v32, v168, v220
	s_waitcnt lgkmcnt(10)
	v_fma_f32 v221, -v36, v168, v221
	s_waitcnt lgkmcnt(9)
	v_fma_f32 v222, -v40, v168, v222
	s_waitcnt lgkmcnt(8)
	v_fma_f32 v223, -v44, v168, v223
	v_fma_f32 v220, -v33, v169, v220
	v_fma_f32 v221, -v37, v169, v221
	v_fma_f32 v222, -v41, v169, v222
	v_fma_f32 v223, -v45, v169, v223
	v_fma_f32 v220, -v34, v170, v220
	v_fma_f32 v221, -v38, v170, v221
	v_fma_f32 v222, -v42, v170, v222
	v_fma_f32 v223, -v46, v170, v223
	v_fma_f32 v220, -v35, v171, v220
	v_fma_f32 v221, -v39, v171, v221
	v_fma_f32 v222, -v43, v171, v222
	v_fma_f32 v223, -v47, v171, v223
	ds_read_b128 v[48:51], v63 offset:4688
	ds_read_b128 v[52:55], v63 offset:4960
	ds_read_b128 v[56:59], v63 offset:5232
	ds_read_b128 v[32:35], v63 offset:6576
	ds_read_b128 v[36:39], v63 offset:6848
	ds_read_b128 v[40:43], v63 offset:7120
	ds_read_b128 v[44:47], v63 offset:7392
	s_waitcnt lgkmcnt(14)
	v_fma_f32 v176, -v0, v172, v176
	s_waitcnt lgkmcnt(13)
	v_fma_f32 v177, -v4, v172, v177
	s_waitcnt lgkmcnt(12)
	v_fma_f32 v178, -v8, v172, v178
	s_waitcnt lgkmcnt(11)
	v_fma_f32 v179, -v12, v172, v179
	v_fma_f32 v176, -v1, v173, v176
	v_fma_f32 v177, -v5, v173, v177
	v_fma_f32 v178, -v9, v173, v178
	v_fma_f32 v179, -v13, v173, v179
	v_fma_f32 v176, -v2, v174, v176
	v_fma_f32 v177, -v6, v174, v177
	v_fma_f32 v178, -v10, v174, v178
	v_fma_f32 v179, -v14, v174, v179
	v_fma_f32 v176, -v3, v175, v176
	v_fma_f32 v177, -v7, v175, v177
	v_fma_f32 v178, -v11, v175, v178
	v_fma_f32 v179, -v15, v175, v179
	ds_read_b128 v[0:3], v63 offset:7664
	ds_read_b128 v[4:7], v63 offset:7936
	ds_read_b128 v[8:11], v63 offset:8208
	ds_read_b128 v[12:15], v63 offset:8480
	s_waitcnt lgkmcnt(14)
	v_fma_f32 v180, -v16, v172, v180
	s_waitcnt lgkmcnt(13)
	v_fma_f32 v181, -v20, v172, v181
	s_waitcnt lgkmcnt(10)
	v_fma_f32 v177, -v48, v176, v177
	s_waitcnt lgkmcnt(12)
	v_fma_f32 v182, -v24, v172, v182
	s_waitcnt lgkmcnt(11)
	v_fma_f32 v183, -v28, v172, v183
	s_waitcnt lgkmcnt(9)
	v_fma_f32 v178, -v52, v176, v178
	v_fma_f32 v180, -v17, v173, v180
	v_fma_f32 v181, -v21, v173, v181
	s_waitcnt lgkmcnt(8)
	v_fma_f32 v179, -v56, v176, v179
	v_fma_f32 v182, -v25, v173, v182
	v_fma_f32 v183, -v29, v173, v183
	v_fma_f32 v178, -v53, v177, v178
	v_fma_f32 v180, -v18, v174, v180
	v_fma_f32 v181, -v22, v174, v181
	v_fma_f32 v179, -v57, v177, v179
	v_fma_f32 v182, -v26, v174, v182
	v_fma_f32 v183, -v30, v174, v183
	v_fma_f32 v179, -v58, v178, v179
	v_fma_f32 v180, -v19, v175, v180
	v_fma_f32 v181, -v23, v175, v181
	v_fma_f32 v182, -v27, v175, v182
	v_fma_f32 v183, -v31, v175, v183
	ds_read_b128 v[16:19], v63 offset:8752
	ds_read_b128 v[20:23], v63 offset:9024
	ds_read_b128 v[24:27], v63 offset:9296
	ds_read_b128 v[28:31], v63 offset:9568
	s_waitcnt lgkmcnt(11)
	v_fma_f32 v184, -v32, v172, v184
	s_waitcnt lgkmcnt(10)
	v_fma_f32 v185, -v36, v172, v185
	s_waitcnt lgkmcnt(9)
	v_fma_f32 v186, -v40, v172, v186
	s_waitcnt lgkmcnt(8)
	v_fma_f32 v187, -v44, v172, v187
	v_fma_f32 v184, -v33, v173, v184
	v_fma_f32 v185, -v37, v173, v185
	v_fma_f32 v186, -v41, v173, v186
	v_fma_f32 v187, -v45, v173, v187
	v_fma_f32 v184, -v34, v174, v184
	v_fma_f32 v185, -v38, v174, v185
	v_fma_f32 v186, -v42, v174, v186
	v_fma_f32 v187, -v46, v174, v187
	v_fma_f32 v184, -v35, v175, v184
	v_fma_f32 v185, -v39, v175, v185
	v_fma_f32 v186, -v43, v175, v186
	v_fma_f32 v187, -v47, v175, v187
	ds_read_b128 v[32:35], v63 offset:9840
	ds_read_b128 v[36:39], v63 offset:10112
	ds_read_b128 v[40:43], v63 offset:10384
	ds_read_b128 v[44:47], v63 offset:10656
	s_waitcnt lgkmcnt(11)
	v_fma_f32 v188, -v0, v172, v188
	s_waitcnt lgkmcnt(10)
	v_fma_f32 v189, -v4, v172, v189
	s_waitcnt lgkmcnt(9)
	v_fma_f32 v190, -v8, v172, v190
	s_waitcnt lgkmcnt(8)
	v_fma_f32 v191, -v12, v172, v191
	v_fma_f32 v188, -v1, v173, v188
	v_fma_f32 v189, -v5, v173, v189
	v_fma_f32 v190, -v9, v173, v190
	v_fma_f32 v191, -v13, v173, v191
	v_fma_f32 v188, -v2, v174, v188
	v_fma_f32 v189, -v6, v174, v189
	v_fma_f32 v190, -v10, v174, v190
	v_fma_f32 v191, -v14, v174, v191
	v_fma_f32 v188, -v3, v175, v188
	v_fma_f32 v189, -v7, v175, v189
	v_fma_f32 v190, -v11, v175, v190
	v_fma_f32 v191, -v15, v175, v191
	ds_read_b128 v[0:3], v63 offset:10928
	ds_read_b128 v[4:7], v63 offset:11200
	ds_read_b128 v[8:11], v63 offset:11472
	ds_read_b128 v[12:15], v63 offset:11744
	s_waitcnt lgkmcnt(11)
	v_fma_f32 v192, -v16, v172, v192
	s_waitcnt lgkmcnt(10)
	v_fma_f32 v193, -v20, v172, v193
	s_waitcnt lgkmcnt(9)
	v_fma_f32 v194, -v24, v172, v194
	s_waitcnt lgkmcnt(8)
	v_fma_f32 v195, -v28, v172, v195
	v_fma_f32 v192, -v17, v173, v192
	v_fma_f32 v193, -v21, v173, v193
	v_fma_f32 v194, -v25, v173, v194
	v_fma_f32 v195, -v29, v173, v195
	v_fma_f32 v192, -v18, v174, v192
	v_fma_f32 v193, -v22, v174, v193
	v_fma_f32 v194, -v26, v174, v194
	v_fma_f32 v195, -v30, v174, v195
	v_fma_f32 v192, -v19, v175, v192
	v_fma_f32 v193, -v23, v175, v193
	v_fma_f32 v194, -v27, v175, v194
	v_fma_f32 v195, -v31, v175, v195
	ds_read_b128 v[16:19], v63 offset:12016
	ds_read_b128 v[20:23], v63 offset:12288
	ds_read_b128 v[24:27], v63 offset:12560
	ds_read_b128 v[28:31], v63 offset:12832
	s_waitcnt lgkmcnt(11)
	v_fma_f32 v196, -v32, v172, v196
	s_waitcnt lgkmcnt(10)
	v_fma_f32 v197, -v36, v172, v197
	s_waitcnt lgkmcnt(9)
	v_fma_f32 v198, -v40, v172, v198
	s_waitcnt lgkmcnt(8)
	v_fma_f32 v199, -v44, v172, v199
	v_fma_f32 v196, -v33, v173, v196
	v_fma_f32 v197, -v37, v173, v197
	v_fma_f32 v198, -v41, v173, v198
	v_fma_f32 v199, -v45, v173, v199
	v_fma_f32 v196, -v34, v174, v196
	v_fma_f32 v197, -v38, v174, v197
	v_fma_f32 v198, -v42, v174, v198
	v_fma_f32 v199, -v46, v174, v199
	v_fma_f32 v196, -v35, v175, v196
	v_fma_f32 v197, -v39, v175, v197
	v_fma_f32 v198, -v43, v175, v198
	v_fma_f32 v199, -v47, v175, v199
	ds_read_b128 v[32:35], v63 offset:13104
	ds_read_b128 v[36:39], v63 offset:13376
	ds_read_b128 v[40:43], v63 offset:13648
	ds_read_b128 v[44:47], v63 offset:13920
	s_waitcnt lgkmcnt(11)
	v_fma_f32 v200, -v0, v172, v200
	s_waitcnt lgkmcnt(10)
	v_fma_f32 v201, -v4, v172, v201
	s_waitcnt lgkmcnt(9)
	v_fma_f32 v202, -v8, v172, v202
	s_waitcnt lgkmcnt(8)
	v_fma_f32 v203, -v12, v172, v203
	v_fma_f32 v200, -v1, v173, v200
	v_fma_f32 v201, -v5, v173, v201
	v_fma_f32 v202, -v9, v173, v202
	v_fma_f32 v203, -v13, v173, v203
	v_fma_f32 v200, -v2, v174, v200
	v_fma_f32 v201, -v6, v174, v201
	v_fma_f32 v202, -v10, v174, v202
	v_fma_f32 v203, -v14, v174, v203
	v_fma_f32 v200, -v3, v175, v200
	v_fma_f32 v201, -v7, v175, v201
	v_fma_f32 v202, -v11, v175, v202
	v_fma_f32 v203, -v15, v175, v203
	ds_read_b128 v[0:3], v63 offset:14192
	ds_read_b128 v[4:7], v63 offset:14464
	ds_read_b128 v[8:11], v63 offset:14736
	ds_read_b128 v[12:15], v63 offset:15008
	s_waitcnt lgkmcnt(11)
	v_fma_f32 v204, -v16, v172, v204
	s_waitcnt lgkmcnt(10)
	v_fma_f32 v205, -v20, v172, v205
	s_waitcnt lgkmcnt(9)
	v_fma_f32 v206, -v24, v172, v206
	s_waitcnt lgkmcnt(8)
	v_fma_f32 v207, -v28, v172, v207
	v_fma_f32 v204, -v17, v173, v204
	v_fma_f32 v205, -v21, v173, v205
	v_fma_f32 v206, -v25, v173, v206
	v_fma_f32 v207, -v29, v173, v207
	v_fma_f32 v204, -v18, v174, v204
	v_fma_f32 v205, -v22, v174, v205
	v_fma_f32 v206, -v26, v174, v206
	v_fma_f32 v207, -v30, v174, v207
	v_fma_f32 v204, -v19, v175, v204
	v_fma_f32 v205, -v23, v175, v205
	v_fma_f32 v206, -v27, v175, v206
	v_fma_f32 v207, -v31, v175, v207
	ds_read_b128 v[16:19], v63 offset:15280
	ds_read_b128 v[20:23], v63 offset:15552
	ds_read_b128 v[24:27], v63 offset:15824
	ds_read_b128 v[28:31], v63 offset:16096
	s_waitcnt lgkmcnt(11)
	v_fma_f32 v208, -v32, v172, v208
	s_waitcnt lgkmcnt(10)
	v_fma_f32 v209, -v36, v172, v209
	s_waitcnt lgkmcnt(9)
	v_fma_f32 v210, -v40, v172, v210
	s_waitcnt lgkmcnt(8)
	v_fma_f32 v211, -v44, v172, v211
	v_fma_f32 v208, -v33, v173, v208
	v_fma_f32 v209, -v37, v173, v209
	v_fma_f32 v210, -v41, v173, v210
	v_fma_f32 v211, -v45, v173, v211
	v_fma_f32 v208, -v34, v174, v208
	v_fma_f32 v209, -v38, v174, v209
	v_fma_f32 v210, -v42, v174, v210
	v_fma_f32 v211, -v46, v174, v211
	v_fma_f32 v208, -v35, v175, v208
	v_fma_f32 v209, -v39, v175, v209
	v_fma_f32 v210, -v43, v175, v210
	v_fma_f32 v211, -v47, v175, v211
	ds_read_b128 v[32:35], v63 offset:16368
	ds_read_b128 v[36:39], v63 offset:16640
	ds_read_b128 v[40:43], v63 offset:16912
	ds_read_b128 v[44:47], v63 offset:17184
	s_waitcnt lgkmcnt(11)
	v_fma_f32 v212, -v0, v172, v212
	s_waitcnt lgkmcnt(10)
	v_fma_f32 v213, -v4, v172, v213
	s_waitcnt lgkmcnt(9)
	v_fma_f32 v214, -v8, v172, v214
	s_waitcnt lgkmcnt(8)
	v_fma_f32 v215, -v12, v172, v215
	v_fma_f32 v212, -v1, v173, v212
	v_fma_f32 v213, -v5, v173, v213
	v_fma_f32 v214, -v9, v173, v214
	v_fma_f32 v215, -v13, v173, v215
	v_fma_f32 v212, -v2, v174, v212
	v_fma_f32 v213, -v6, v174, v213
	v_fma_f32 v214, -v10, v174, v214
	v_fma_f32 v215, -v14, v174, v215
	v_fma_f32 v212, -v3, v175, v212
	v_fma_f32 v213, -v7, v175, v213
	v_fma_f32 v214, -v11, v175, v214
	v_fma_f32 v215, -v15, v175, v215
	ds_read_b128 v[0:3], v63 offset:5504
	ds_read_b128 v[4:7], v63 offset:5776
	ds_read_b128 v[8:11], v63 offset:6048
	ds_read_b128 v[12:15], v63 offset:6320
	s_waitcnt lgkmcnt(11)
	v_fma_f32 v216, -v16, v172, v216
	s_waitcnt lgkmcnt(10)
	v_fma_f32 v217, -v20, v172, v217
	s_waitcnt lgkmcnt(9)
	v_fma_f32 v218, -v24, v172, v218
	s_waitcnt lgkmcnt(8)
	v_fma_f32 v219, -v28, v172, v219
	v_fma_f32 v216, -v17, v173, v216
	v_fma_f32 v217, -v21, v173, v217
	v_fma_f32 v218, -v25, v173, v218
	v_fma_f32 v219, -v29, v173, v219
	v_fma_f32 v216, -v18, v174, v216
	v_fma_f32 v217, -v22, v174, v217
	v_fma_f32 v218, -v26, v174, v218
	v_fma_f32 v219, -v30, v174, v219
	v_fma_f32 v216, -v19, v175, v216
	v_fma_f32 v217, -v23, v175, v217
	v_fma_f32 v218, -v27, v175, v218
	v_fma_f32 v219, -v31, v175, v219
	ds_read_b128 v[16:19], v63 offset:6592
	ds_read_b128 v[20:23], v63 offset:6864
	ds_read_b128 v[24:27], v63 offset:7136
	ds_read_b128 v[28:31], v63 offset:7408
	s_waitcnt lgkmcnt(11)
	v_fma_f32 v220, -v32, v172, v220
	s_waitcnt lgkmcnt(10)
	v_fma_f32 v221, -v36, v172, v221
	s_waitcnt lgkmcnt(9)
	v_fma_f32 v222, -v40, v172, v222
	s_waitcnt lgkmcnt(8)
	v_fma_f32 v223, -v44, v172, v223
	v_fma_f32 v220, -v33, v173, v220
	v_fma_f32 v221, -v37, v173, v221
	v_fma_f32 v222, -v41, v173, v222
	v_fma_f32 v223, -v45, v173, v223
	v_fma_f32 v220, -v34, v174, v220
	v_fma_f32 v221, -v38, v174, v221
	v_fma_f32 v222, -v42, v174, v222
	v_fma_f32 v223, -v46, v174, v223
	v_fma_f32 v220, -v35, v175, v220
	v_fma_f32 v221, -v39, v175, v221
	v_fma_f32 v222, -v43, v175, v222
	v_fma_f32 v223, -v47, v175, v223
	ds_read_b128 v[48:51], v63 offset:5792
	ds_read_b128 v[52:55], v63 offset:6064
	ds_read_b128 v[56:59], v63 offset:6336
	ds_read_b128 v[32:35], v63 offset:7680
	ds_read_b128 v[36:39], v63 offset:7952
	ds_read_b128 v[40:43], v63 offset:8224
	ds_read_b128 v[44:47], v63 offset:8496
	s_waitcnt lgkmcnt(14)
	v_fma_f32 v180, -v0, v176, v180
	s_waitcnt lgkmcnt(13)
	v_fma_f32 v181, -v4, v176, v181
	s_waitcnt lgkmcnt(12)
	v_fma_f32 v182, -v8, v176, v182
	s_waitcnt lgkmcnt(11)
	v_fma_f32 v183, -v12, v176, v183
	v_fma_f32 v180, -v1, v177, v180
	v_fma_f32 v181, -v5, v177, v181
	v_fma_f32 v182, -v9, v177, v182
	v_fma_f32 v183, -v13, v177, v183
	v_fma_f32 v180, -v2, v178, v180
	v_fma_f32 v181, -v6, v178, v181
	v_fma_f32 v182, -v10, v178, v182
	v_fma_f32 v183, -v14, v178, v183
	v_fma_f32 v180, -v3, v179, v180
	v_fma_f32 v181, -v7, v179, v181
	v_fma_f32 v182, -v11, v179, v182
	v_fma_f32 v183, -v15, v179, v183
	ds_read_b128 v[0:3], v63 offset:8768
	ds_read_b128 v[4:7], v63 offset:9040
	ds_read_b128 v[8:11], v63 offset:9312
	ds_read_b128 v[12:15], v63 offset:9584
	s_waitcnt lgkmcnt(14)
	v_fma_f32 v184, -v16, v176, v184
	s_waitcnt lgkmcnt(13)
	v_fma_f32 v185, -v20, v176, v185
	s_waitcnt lgkmcnt(10)
	v_fma_f32 v181, -v48, v180, v181
	s_waitcnt lgkmcnt(12)
	v_fma_f32 v186, -v24, v176, v186
	s_waitcnt lgkmcnt(11)
	v_fma_f32 v187, -v28, v176, v187
	s_waitcnt lgkmcnt(9)
	v_fma_f32 v182, -v52, v180, v182
	v_fma_f32 v184, -v17, v177, v184
	v_fma_f32 v185, -v21, v177, v185
	s_waitcnt lgkmcnt(8)
	v_fma_f32 v183, -v56, v180, v183
	v_fma_f32 v186, -v25, v177, v186
	v_fma_f32 v187, -v29, v177, v187
	v_fma_f32 v182, -v53, v181, v182
	v_fma_f32 v184, -v18, v178, v184
	v_fma_f32 v185, -v22, v178, v185
	v_fma_f32 v183, -v57, v181, v183
	v_fma_f32 v186, -v26, v178, v186
	v_fma_f32 v187, -v30, v178, v187
	v_fma_f32 v183, -v58, v182, v183
	v_fma_f32 v184, -v19, v179, v184
	v_fma_f32 v185, -v23, v179, v185
	v_fma_f32 v186, -v27, v179, v186
	v_fma_f32 v187, -v31, v179, v187
	ds_read_b128 v[16:19], v63 offset:9856
	ds_read_b128 v[20:23], v63 offset:10128
	ds_read_b128 v[24:27], v63 offset:10400
	ds_read_b128 v[28:31], v63 offset:10672
	s_waitcnt lgkmcnt(11)
	v_fma_f32 v188, -v32, v176, v188
	s_waitcnt lgkmcnt(10)
	v_fma_f32 v189, -v36, v176, v189
	s_waitcnt lgkmcnt(9)
	v_fma_f32 v190, -v40, v176, v190
	s_waitcnt lgkmcnt(8)
	v_fma_f32 v191, -v44, v176, v191
	v_fma_f32 v188, -v33, v177, v188
	v_fma_f32 v189, -v37, v177, v189
	v_fma_f32 v190, -v41, v177, v190
	v_fma_f32 v191, -v45, v177, v191
	v_fma_f32 v188, -v34, v178, v188
	v_fma_f32 v189, -v38, v178, v189
	v_fma_f32 v190, -v42, v178, v190
	v_fma_f32 v191, -v46, v178, v191
	v_fma_f32 v188, -v35, v179, v188
	v_fma_f32 v189, -v39, v179, v189
	v_fma_f32 v190, -v43, v179, v190
	v_fma_f32 v191, -v47, v179, v191
	ds_read_b128 v[32:35], v63 offset:10944
	ds_read_b128 v[36:39], v63 offset:11216
	ds_read_b128 v[40:43], v63 offset:11488
	ds_read_b128 v[44:47], v63 offset:11760
	s_waitcnt lgkmcnt(11)
	v_fma_f32 v192, -v0, v176, v192
	s_waitcnt lgkmcnt(10)
	v_fma_f32 v193, -v4, v176, v193
	s_waitcnt lgkmcnt(9)
	v_fma_f32 v194, -v8, v176, v194
	s_waitcnt lgkmcnt(8)
	v_fma_f32 v195, -v12, v176, v195
	v_fma_f32 v192, -v1, v177, v192
	v_fma_f32 v193, -v5, v177, v193
	v_fma_f32 v194, -v9, v177, v194
	v_fma_f32 v195, -v13, v177, v195
	v_fma_f32 v192, -v2, v178, v192
	v_fma_f32 v193, -v6, v178, v193
	v_fma_f32 v194, -v10, v178, v194
	v_fma_f32 v195, -v14, v178, v195
	v_fma_f32 v192, -v3, v179, v192
	v_fma_f32 v193, -v7, v179, v193
	v_fma_f32 v194, -v11, v179, v194
	v_fma_f32 v195, -v15, v179, v195
	ds_read_b128 v[0:3], v63 offset:12032
	ds_read_b128 v[4:7], v63 offset:12304
	ds_read_b128 v[8:11], v63 offset:12576
	ds_read_b128 v[12:15], v63 offset:12848
	s_waitcnt lgkmcnt(11)
	v_fma_f32 v196, -v16, v176, v196
	s_waitcnt lgkmcnt(10)
	v_fma_f32 v197, -v20, v176, v197
	s_waitcnt lgkmcnt(9)
	v_fma_f32 v198, -v24, v176, v198
	s_waitcnt lgkmcnt(8)
	v_fma_f32 v199, -v28, v176, v199
	v_fma_f32 v196, -v17, v177, v196
	v_fma_f32 v197, -v21, v177, v197
	v_fma_f32 v198, -v25, v177, v198
	v_fma_f32 v199, -v29, v177, v199
	v_fma_f32 v196, -v18, v178, v196
	v_fma_f32 v197, -v22, v178, v197
	v_fma_f32 v198, -v26, v178, v198
	v_fma_f32 v199, -v30, v178, v199
	v_fma_f32 v196, -v19, v179, v196
	v_fma_f32 v197, -v23, v179, v197
	v_fma_f32 v198, -v27, v179, v198
	v_fma_f32 v199, -v31, v179, v199
	ds_read_b128 v[16:19], v63 offset:13120
	ds_read_b128 v[20:23], v63 offset:13392
	ds_read_b128 v[24:27], v63 offset:13664
	ds_read_b128 v[28:31], v63 offset:13936
	s_waitcnt lgkmcnt(11)
	v_fma_f32 v200, -v32, v176, v200
	s_waitcnt lgkmcnt(10)
	v_fma_f32 v201, -v36, v176, v201
	s_waitcnt lgkmcnt(9)
	v_fma_f32 v202, -v40, v176, v202
	s_waitcnt lgkmcnt(8)
	v_fma_f32 v203, -v44, v176, v203
	v_fma_f32 v200, -v33, v177, v200
	v_fma_f32 v201, -v37, v177, v201
	v_fma_f32 v202, -v41, v177, v202
	v_fma_f32 v203, -v45, v177, v203
	v_fma_f32 v200, -v34, v178, v200
	v_fma_f32 v201, -v38, v178, v201
	v_fma_f32 v202, -v42, v178, v202
	v_fma_f32 v203, -v46, v178, v203
	v_fma_f32 v200, -v35, v179, v200
	v_fma_f32 v201, -v39, v179, v201
	v_fma_f32 v202, -v43, v179, v202
	v_fma_f32 v203, -v47, v179, v203
	ds_read_b128 v[32:35], v63 offset:14208
	ds_read_b128 v[36:39], v63 offset:14480
	ds_read_b128 v[40:43], v63 offset:14752
	ds_read_b128 v[44:47], v63 offset:15024
	s_waitcnt lgkmcnt(11)
	v_fma_f32 v204, -v0, v176, v204
	s_waitcnt lgkmcnt(10)
	v_fma_f32 v205, -v4, v176, v205
	s_waitcnt lgkmcnt(9)
	v_fma_f32 v206, -v8, v176, v206
	s_waitcnt lgkmcnt(8)
	v_fma_f32 v207, -v12, v176, v207
	v_fma_f32 v204, -v1, v177, v204
	v_fma_f32 v205, -v5, v177, v205
	v_fma_f32 v206, -v9, v177, v206
	v_fma_f32 v207, -v13, v177, v207
	v_fma_f32 v204, -v2, v178, v204
	v_fma_f32 v205, -v6, v178, v205
	v_fma_f32 v206, -v10, v178, v206
	v_fma_f32 v207, -v14, v178, v207
	v_fma_f32 v204, -v3, v179, v204
	v_fma_f32 v205, -v7, v179, v205
	v_fma_f32 v206, -v11, v179, v206
	v_fma_f32 v207, -v15, v179, v207
	ds_read_b128 v[0:3], v63 offset:15296
	ds_read_b128 v[4:7], v63 offset:15568
	ds_read_b128 v[8:11], v63 offset:15840
	ds_read_b128 v[12:15], v63 offset:16112
	s_waitcnt lgkmcnt(11)
	v_fma_f32 v208, -v16, v176, v208
	s_waitcnt lgkmcnt(10)
	v_fma_f32 v209, -v20, v176, v209
	s_waitcnt lgkmcnt(9)
	v_fma_f32 v210, -v24, v176, v210
	s_waitcnt lgkmcnt(8)
	v_fma_f32 v211, -v28, v176, v211
	v_fma_f32 v208, -v17, v177, v208
	v_fma_f32 v209, -v21, v177, v209
	v_fma_f32 v210, -v25, v177, v210
	v_fma_f32 v211, -v29, v177, v211
	v_fma_f32 v208, -v18, v178, v208
	v_fma_f32 v209, -v22, v178, v209
	v_fma_f32 v210, -v26, v178, v210
	v_fma_f32 v211, -v30, v178, v211
	v_fma_f32 v208, -v19, v179, v208
	v_fma_f32 v209, -v23, v179, v209
	v_fma_f32 v210, -v27, v179, v210
	v_fma_f32 v211, -v31, v179, v211
	ds_read_b128 v[16:19], v63 offset:16384
	ds_read_b128 v[20:23], v63 offset:16656
	ds_read_b128 v[24:27], v63 offset:16928
	ds_read_b128 v[28:31], v63 offset:17200
	s_waitcnt lgkmcnt(11)
	v_fma_f32 v212, -v32, v176, v212
	s_waitcnt lgkmcnt(10)
	v_fma_f32 v213, -v36, v176, v213
	s_waitcnt lgkmcnt(9)
	v_fma_f32 v214, -v40, v176, v214
	s_waitcnt lgkmcnt(8)
	v_fma_f32 v215, -v44, v176, v215
	v_fma_f32 v212, -v33, v177, v212
	v_fma_f32 v213, -v37, v177, v213
	v_fma_f32 v214, -v41, v177, v214
	v_fma_f32 v215, -v45, v177, v215
	v_fma_f32 v212, -v34, v178, v212
	v_fma_f32 v213, -v38, v178, v213
	v_fma_f32 v214, -v42, v178, v214
	v_fma_f32 v215, -v46, v178, v215
	v_fma_f32 v212, -v35, v179, v212
	v_fma_f32 v213, -v39, v179, v213
	v_fma_f32 v214, -v43, v179, v214
	v_fma_f32 v215, -v47, v179, v215
	ds_read_b128 v[32:35], v63 offset:6608
	ds_read_b128 v[36:39], v63 offset:6880
	ds_read_b128 v[40:43], v63 offset:7152
	ds_read_b128 v[44:47], v63 offset:7424
	s_waitcnt lgkmcnt(11)
	v_fma_f32 v216, -v0, v176, v216
	s_waitcnt lgkmcnt(10)
	v_fma_f32 v217, -v4, v176, v217
	s_waitcnt lgkmcnt(9)
	v_fma_f32 v218, -v8, v176, v218
	s_waitcnt lgkmcnt(8)
	v_fma_f32 v219, -v12, v176, v219
	v_fma_f32 v216, -v1, v177, v216
	v_fma_f32 v217, -v5, v177, v217
	v_fma_f32 v218, -v9, v177, v218
	v_fma_f32 v219, -v13, v177, v219
	v_fma_f32 v216, -v2, v178, v216
	v_fma_f32 v217, -v6, v178, v217
	v_fma_f32 v218, -v10, v178, v218
	v_fma_f32 v219, -v14, v178, v219
	v_fma_f32 v216, -v3, v179, v216
	v_fma_f32 v217, -v7, v179, v217
	v_fma_f32 v218, -v11, v179, v218
	v_fma_f32 v219, -v15, v179, v219
	ds_read_b128 v[0:3], v63 offset:7696
	ds_read_b128 v[4:7], v63 offset:7968
	ds_read_b128 v[8:11], v63 offset:8240
	ds_read_b128 v[12:15], v63 offset:8512
	s_waitcnt lgkmcnt(11)
	v_fma_f32 v220, -v16, v176, v220
	s_waitcnt lgkmcnt(10)
	v_fma_f32 v221, -v20, v176, v221
	s_waitcnt lgkmcnt(9)
	v_fma_f32 v222, -v24, v176, v222
	s_waitcnt lgkmcnt(8)
	v_fma_f32 v223, -v28, v176, v223
	v_fma_f32 v220, -v17, v177, v220
	v_fma_f32 v221, -v21, v177, v221
	v_fma_f32 v222, -v25, v177, v222
	v_fma_f32 v223, -v29, v177, v223
	v_fma_f32 v220, -v18, v178, v220
	v_fma_f32 v221, -v22, v178, v221
	v_fma_f32 v222, -v26, v178, v222
	v_fma_f32 v223, -v30, v178, v223
	v_fma_f32 v220, -v19, v179, v220
	v_fma_f32 v221, -v23, v179, v221
	v_fma_f32 v222, -v27, v179, v222
	v_fma_f32 v223, -v31, v179, v223
	ds_read_b128 v[48:51], v63 offset:6896
	ds_read_b128 v[52:55], v63 offset:7168
	ds_read_b128 v[56:59], v63 offset:7440
	ds_read_b128 v[16:19], v63 offset:8784
	ds_read_b128 v[20:23], v63 offset:9056
	ds_read_b128 v[24:27], v63 offset:9328
	ds_read_b128 v[28:31], v63 offset:9600
	s_waitcnt lgkmcnt(14)
	v_fma_f32 v184, -v32, v180, v184
	s_waitcnt lgkmcnt(13)
	v_fma_f32 v185, -v36, v180, v185
	s_waitcnt lgkmcnt(12)
	v_fma_f32 v186, -v40, v180, v186
	s_waitcnt lgkmcnt(11)
	v_fma_f32 v187, -v44, v180, v187
	v_fma_f32 v184, -v33, v181, v184
	v_fma_f32 v185, -v37, v181, v185
	v_fma_f32 v186, -v41, v181, v186
	v_fma_f32 v187, -v45, v181, v187
	v_fma_f32 v184, -v34, v182, v184
	v_fma_f32 v185, -v38, v182, v185
	v_fma_f32 v186, -v42, v182, v186
	v_fma_f32 v187, -v46, v182, v187
	v_fma_f32 v184, -v35, v183, v184
	v_fma_f32 v185, -v39, v183, v185
	v_fma_f32 v186, -v43, v183, v186
	v_fma_f32 v187, -v47, v183, v187
	ds_read_b128 v[32:35], v63 offset:9872
	ds_read_b128 v[36:39], v63 offset:10144
	ds_read_b128 v[40:43], v63 offset:10416
	ds_read_b128 v[44:47], v63 offset:10688
	s_waitcnt lgkmcnt(14)
	v_fma_f32 v188, -v0, v180, v188
	s_waitcnt lgkmcnt(13)
	v_fma_f32 v189, -v4, v180, v189
	s_waitcnt lgkmcnt(10)
	v_fma_f32 v185, -v48, v184, v185
	s_waitcnt lgkmcnt(12)
	v_fma_f32 v190, -v8, v180, v190
	s_waitcnt lgkmcnt(11)
	v_fma_f32 v191, -v12, v180, v191
	s_waitcnt lgkmcnt(9)
	v_fma_f32 v186, -v52, v184, v186
	v_fma_f32 v188, -v1, v181, v188
	v_fma_f32 v189, -v5, v181, v189
	s_waitcnt lgkmcnt(8)
	v_fma_f32 v187, -v56, v184, v187
	v_fma_f32 v190, -v9, v181, v190
	v_fma_f32 v191, -v13, v181, v191
	v_fma_f32 v186, -v53, v185, v186
	v_fma_f32 v188, -v2, v182, v188
	v_fma_f32 v189, -v6, v182, v189
	v_fma_f32 v187, -v57, v185, v187
	v_fma_f32 v190, -v10, v182, v190
	v_fma_f32 v191, -v14, v182, v191
	v_fma_f32 v187, -v58, v186, v187
	v_fma_f32 v188, -v3, v183, v188
	v_fma_f32 v189, -v7, v183, v189
	v_fma_f32 v190, -v11, v183, v190
	v_fma_f32 v191, -v15, v183, v191
	ds_read_b128 v[0:3], v63 offset:10960
	ds_read_b128 v[4:7], v63 offset:11232
	ds_read_b128 v[8:11], v63 offset:11504
	ds_read_b128 v[12:15], v63 offset:11776
	s_waitcnt lgkmcnt(11)
	v_fma_f32 v192, -v16, v180, v192
	s_waitcnt lgkmcnt(10)
	v_fma_f32 v193, -v20, v180, v193
	s_waitcnt lgkmcnt(9)
	v_fma_f32 v194, -v24, v180, v194
	s_waitcnt lgkmcnt(8)
	v_fma_f32 v195, -v28, v180, v195
	v_fma_f32 v192, -v17, v181, v192
	v_fma_f32 v193, -v21, v181, v193
	v_fma_f32 v194, -v25, v181, v194
	v_fma_f32 v195, -v29, v181, v195
	v_fma_f32 v192, -v18, v182, v192
	v_fma_f32 v193, -v22, v182, v193
	v_fma_f32 v194, -v26, v182, v194
	v_fma_f32 v195, -v30, v182, v195
	v_fma_f32 v192, -v19, v183, v192
	v_fma_f32 v193, -v23, v183, v193
	v_fma_f32 v194, -v27, v183, v194
	v_fma_f32 v195, -v31, v183, v195
	ds_read_b128 v[16:19], v63 offset:12048
	ds_read_b128 v[20:23], v63 offset:12320
	ds_read_b128 v[24:27], v63 offset:12592
	ds_read_b128 v[28:31], v63 offset:12864
	s_waitcnt lgkmcnt(11)
	v_fma_f32 v196, -v32, v180, v196
	s_waitcnt lgkmcnt(10)
	v_fma_f32 v197, -v36, v180, v197
	s_waitcnt lgkmcnt(9)
	v_fma_f32 v198, -v40, v180, v198
	s_waitcnt lgkmcnt(8)
	v_fma_f32 v199, -v44, v180, v199
	v_fma_f32 v196, -v33, v181, v196
	v_fma_f32 v197, -v37, v181, v197
	v_fma_f32 v198, -v41, v181, v198
	v_fma_f32 v199, -v45, v181, v199
	v_fma_f32 v196, -v34, v182, v196
	v_fma_f32 v197, -v38, v182, v197
	v_fma_f32 v198, -v42, v182, v198
	v_fma_f32 v199, -v46, v182, v199
	v_fma_f32 v196, -v35, v183, v196
	v_fma_f32 v197, -v39, v183, v197
	v_fma_f32 v198, -v43, v183, v198
	v_fma_f32 v199, -v47, v183, v199
	ds_read_b128 v[32:35], v63 offset:13136
	ds_read_b128 v[36:39], v63 offset:13408
	ds_read_b128 v[40:43], v63 offset:13680
	ds_read_b128 v[44:47], v63 offset:13952
	s_waitcnt lgkmcnt(11)
	v_fma_f32 v200, -v0, v180, v200
	s_waitcnt lgkmcnt(10)
	v_fma_f32 v201, -v4, v180, v201
	s_waitcnt lgkmcnt(9)
	v_fma_f32 v202, -v8, v180, v202
	s_waitcnt lgkmcnt(8)
	v_fma_f32 v203, -v12, v180, v203
	v_fma_f32 v200, -v1, v181, v200
	v_fma_f32 v201, -v5, v181, v201
	v_fma_f32 v202, -v9, v181, v202
	v_fma_f32 v203, -v13, v181, v203
	v_fma_f32 v200, -v2, v182, v200
	v_fma_f32 v201, -v6, v182, v201
	v_fma_f32 v202, -v10, v182, v202
	v_fma_f32 v203, -v14, v182, v203
	v_fma_f32 v200, -v3, v183, v200
	v_fma_f32 v201, -v7, v183, v201
	v_fma_f32 v202, -v11, v183, v202
	v_fma_f32 v203, -v15, v183, v203
	ds_read_b128 v[0:3], v63 offset:14224
	ds_read_b128 v[4:7], v63 offset:14496
	ds_read_b128 v[8:11], v63 offset:14768
	ds_read_b128 v[12:15], v63 offset:15040
	s_waitcnt lgkmcnt(11)
	v_fma_f32 v204, -v16, v180, v204
	s_waitcnt lgkmcnt(10)
	v_fma_f32 v205, -v20, v180, v205
	s_waitcnt lgkmcnt(9)
	v_fma_f32 v206, -v24, v180, v206
	s_waitcnt lgkmcnt(8)
	v_fma_f32 v207, -v28, v180, v207
	v_fma_f32 v204, -v17, v181, v204
	v_fma_f32 v205, -v21, v181, v205
	v_fma_f32 v206, -v25, v181, v206
	v_fma_f32 v207, -v29, v181, v207
	v_fma_f32 v204, -v18, v182, v204
	v_fma_f32 v205, -v22, v182, v205
	v_fma_f32 v206, -v26, v182, v206
	v_fma_f32 v207, -v30, v182, v207
	v_fma_f32 v204, -v19, v183, v204
	v_fma_f32 v205, -v23, v183, v205
	v_fma_f32 v206, -v27, v183, v206
	v_fma_f32 v207, -v31, v183, v207
	ds_read_b128 v[16:19], v63 offset:15312
	ds_read_b128 v[20:23], v63 offset:15584
	ds_read_b128 v[24:27], v63 offset:15856
	ds_read_b128 v[28:31], v63 offset:16128
	s_waitcnt lgkmcnt(11)
	v_fma_f32 v208, -v32, v180, v208
	s_waitcnt lgkmcnt(10)
	v_fma_f32 v209, -v36, v180, v209
	s_waitcnt lgkmcnt(9)
	v_fma_f32 v210, -v40, v180, v210
	s_waitcnt lgkmcnt(8)
	v_fma_f32 v211, -v44, v180, v211
	v_fma_f32 v208, -v33, v181, v208
	v_fma_f32 v209, -v37, v181, v209
	v_fma_f32 v210, -v41, v181, v210
	v_fma_f32 v211, -v45, v181, v211
	v_fma_f32 v208, -v34, v182, v208
	v_fma_f32 v209, -v38, v182, v209
	v_fma_f32 v210, -v42, v182, v210
	v_fma_f32 v211, -v46, v182, v211
	v_fma_f32 v208, -v35, v183, v208
	v_fma_f32 v209, -v39, v183, v209
	v_fma_f32 v210, -v43, v183, v210
	v_fma_f32 v211, -v47, v183, v211
	ds_read_b128 v[32:35], v63 offset:16400
	ds_read_b128 v[36:39], v63 offset:16672
	ds_read_b128 v[40:43], v63 offset:16944
	ds_read_b128 v[44:47], v63 offset:17216
	s_waitcnt lgkmcnt(11)
	v_fma_f32 v212, -v0, v180, v212
	s_waitcnt lgkmcnt(10)
	v_fma_f32 v213, -v4, v180, v213
	s_waitcnt lgkmcnt(9)
	v_fma_f32 v214, -v8, v180, v214
	s_waitcnt lgkmcnt(8)
	v_fma_f32 v215, -v12, v180, v215
	v_fma_f32 v212, -v1, v181, v212
	v_fma_f32 v213, -v5, v181, v213
	v_fma_f32 v214, -v9, v181, v214
	v_fma_f32 v215, -v13, v181, v215
	v_fma_f32 v212, -v2, v182, v212
	v_fma_f32 v213, -v6, v182, v213
	v_fma_f32 v214, -v10, v182, v214
	v_fma_f32 v215, -v14, v182, v215
	v_fma_f32 v212, -v3, v183, v212
	v_fma_f32 v213, -v7, v183, v213
	v_fma_f32 v214, -v11, v183, v214
	v_fma_f32 v215, -v15, v183, v215
	ds_read_b128 v[0:3], v63 offset:7712
	ds_read_b128 v[4:7], v63 offset:7984
	ds_read_b128 v[8:11], v63 offset:8256
	ds_read_b128 v[12:15], v63 offset:8528
	s_waitcnt lgkmcnt(11)
	v_fma_f32 v216, -v16, v180, v216
	s_waitcnt lgkmcnt(10)
	v_fma_f32 v217, -v20, v180, v217
	s_waitcnt lgkmcnt(9)
	v_fma_f32 v218, -v24, v180, v218
	s_waitcnt lgkmcnt(8)
	v_fma_f32 v219, -v28, v180, v219
	v_fma_f32 v216, -v17, v181, v216
	v_fma_f32 v217, -v21, v181, v217
	v_fma_f32 v218, -v25, v181, v218
	v_fma_f32 v219, -v29, v181, v219
	v_fma_f32 v216, -v18, v182, v216
	v_fma_f32 v217, -v22, v182, v217
	v_fma_f32 v218, -v26, v182, v218
	v_fma_f32 v219, -v30, v182, v219
	v_fma_f32 v216, -v19, v183, v216
	v_fma_f32 v217, -v23, v183, v217
	v_fma_f32 v218, -v27, v183, v218
	v_fma_f32 v219, -v31, v183, v219
	ds_read_b128 v[16:19], v63 offset:8800
	ds_read_b128 v[20:23], v63 offset:9072
	ds_read_b128 v[24:27], v63 offset:9344
	ds_read_b128 v[28:31], v63 offset:9616
	s_waitcnt lgkmcnt(11)
	v_fma_f32 v220, -v32, v180, v220
	s_waitcnt lgkmcnt(10)
	v_fma_f32 v221, -v36, v180, v221
	s_waitcnt lgkmcnt(9)
	v_fma_f32 v222, -v40, v180, v222
	s_waitcnt lgkmcnt(8)
	v_fma_f32 v223, -v44, v180, v223
	v_fma_f32 v220, -v33, v181, v220
	v_fma_f32 v221, -v37, v181, v221
	v_fma_f32 v222, -v41, v181, v222
	v_fma_f32 v223, -v45, v181, v223
	v_fma_f32 v220, -v34, v182, v220
	v_fma_f32 v221, -v38, v182, v221
	v_fma_f32 v222, -v42, v182, v222
	v_fma_f32 v223, -v46, v182, v223
	v_fma_f32 v220, -v35, v183, v220
	v_fma_f32 v221, -v39, v183, v221
	v_fma_f32 v222, -v43, v183, v222
	v_fma_f32 v223, -v47, v183, v223
	ds_read_b128 v[48:51], v63 offset:8000
	ds_read_b128 v[52:55], v63 offset:8272
	ds_read_b128 v[56:59], v63 offset:8544
	ds_read_b128 v[32:35], v63 offset:9888
	ds_read_b128 v[36:39], v63 offset:10160
	ds_read_b128 v[40:43], v63 offset:10432
	ds_read_b128 v[44:47], v63 offset:10704
	s_waitcnt lgkmcnt(14)
	v_fma_f32 v188, -v0, v184, v188
	s_waitcnt lgkmcnt(13)
	v_fma_f32 v189, -v4, v184, v189
	s_waitcnt lgkmcnt(12)
	v_fma_f32 v190, -v8, v184, v190
	s_waitcnt lgkmcnt(11)
	v_fma_f32 v191, -v12, v184, v191
	v_fma_f32 v188, -v1, v185, v188
	v_fma_f32 v189, -v5, v185, v189
	v_fma_f32 v190, -v9, v185, v190
	v_fma_f32 v191, -v13, v185, v191
	v_fma_f32 v188, -v2, v186, v188
	v_fma_f32 v189, -v6, v186, v189
	v_fma_f32 v190, -v10, v186, v190
	v_fma_f32 v191, -v14, v186, v191
	v_fma_f32 v188, -v3, v187, v188
	v_fma_f32 v189, -v7, v187, v189
	v_fma_f32 v190, -v11, v187, v190
	v_fma_f32 v191, -v15, v187, v191
	ds_read_b128 v[0:3], v63 offset:10976
	ds_read_b128 v[4:7], v63 offset:11248
	ds_read_b128 v[8:11], v63 offset:11520
	ds_read_b128 v[12:15], v63 offset:11792
	s_waitcnt lgkmcnt(14)
	v_fma_f32 v192, -v16, v184, v192
	s_waitcnt lgkmcnt(13)
	v_fma_f32 v193, -v20, v184, v193
	s_waitcnt lgkmcnt(10)
	v_fma_f32 v189, -v48, v188, v189
	s_waitcnt lgkmcnt(12)
	v_fma_f32 v194, -v24, v184, v194
	s_waitcnt lgkmcnt(11)
	v_fma_f32 v195, -v28, v184, v195
	s_waitcnt lgkmcnt(9)
	v_fma_f32 v190, -v52, v188, v190
	v_fma_f32 v192, -v17, v185, v192
	v_fma_f32 v193, -v21, v185, v193
	s_waitcnt lgkmcnt(8)
	v_fma_f32 v191, -v56, v188, v191
	v_fma_f32 v194, -v25, v185, v194
	v_fma_f32 v195, -v29, v185, v195
	v_fma_f32 v190, -v53, v189, v190
	v_fma_f32 v192, -v18, v186, v192
	v_fma_f32 v193, -v22, v186, v193
	v_fma_f32 v191, -v57, v189, v191
	v_fma_f32 v194, -v26, v186, v194
	v_fma_f32 v195, -v30, v186, v195
	v_fma_f32 v191, -v58, v190, v191
	v_fma_f32 v192, -v19, v187, v192
	v_fma_f32 v193, -v23, v187, v193
	v_fma_f32 v194, -v27, v187, v194
	v_fma_f32 v195, -v31, v187, v195
	ds_read_b128 v[16:19], v63 offset:12064
	ds_read_b128 v[20:23], v63 offset:12336
	ds_read_b128 v[24:27], v63 offset:12608
	ds_read_b128 v[28:31], v63 offset:12880
	s_waitcnt lgkmcnt(11)
	v_fma_f32 v196, -v32, v184, v196
	s_waitcnt lgkmcnt(10)
	v_fma_f32 v197, -v36, v184, v197
	s_waitcnt lgkmcnt(9)
	v_fma_f32 v198, -v40, v184, v198
	s_waitcnt lgkmcnt(8)
	v_fma_f32 v199, -v44, v184, v199
	v_fma_f32 v196, -v33, v185, v196
	v_fma_f32 v197, -v37, v185, v197
	v_fma_f32 v198, -v41, v185, v198
	v_fma_f32 v199, -v45, v185, v199
	v_fma_f32 v196, -v34, v186, v196
	v_fma_f32 v197, -v38, v186, v197
	v_fma_f32 v198, -v42, v186, v198
	v_fma_f32 v199, -v46, v186, v199
	v_fma_f32 v196, -v35, v187, v196
	v_fma_f32 v197, -v39, v187, v197
	v_fma_f32 v198, -v43, v187, v198
	v_fma_f32 v199, -v47, v187, v199
	ds_read_b128 v[32:35], v63 offset:13152
	ds_read_b128 v[36:39], v63 offset:13424
	ds_read_b128 v[40:43], v63 offset:13696
	ds_read_b128 v[44:47], v63 offset:13968
	s_waitcnt lgkmcnt(11)
	v_fma_f32 v200, -v0, v184, v200
	s_waitcnt lgkmcnt(10)
	v_fma_f32 v201, -v4, v184, v201
	s_waitcnt lgkmcnt(9)
	v_fma_f32 v202, -v8, v184, v202
	s_waitcnt lgkmcnt(8)
	v_fma_f32 v203, -v12, v184, v203
	v_fma_f32 v200, -v1, v185, v200
	v_fma_f32 v201, -v5, v185, v201
	v_fma_f32 v202, -v9, v185, v202
	v_fma_f32 v203, -v13, v185, v203
	v_fma_f32 v200, -v2, v186, v200
	v_fma_f32 v201, -v6, v186, v201
	v_fma_f32 v202, -v10, v186, v202
	v_fma_f32 v203, -v14, v186, v203
	v_fma_f32 v200, -v3, v187, v200
	v_fma_f32 v201, -v7, v187, v201
	v_fma_f32 v202, -v11, v187, v202
	v_fma_f32 v203, -v15, v187, v203
	ds_read_b128 v[0:3], v63 offset:14240
	ds_read_b128 v[4:7], v63 offset:14512
	ds_read_b128 v[8:11], v63 offset:14784
	ds_read_b128 v[12:15], v63 offset:15056
	s_waitcnt lgkmcnt(11)
	v_fma_f32 v204, -v16, v184, v204
	s_waitcnt lgkmcnt(10)
	v_fma_f32 v205, -v20, v184, v205
	s_waitcnt lgkmcnt(9)
	v_fma_f32 v206, -v24, v184, v206
	s_waitcnt lgkmcnt(8)
	v_fma_f32 v207, -v28, v184, v207
	v_fma_f32 v204, -v17, v185, v204
	v_fma_f32 v205, -v21, v185, v205
	v_fma_f32 v206, -v25, v185, v206
	v_fma_f32 v207, -v29, v185, v207
	v_fma_f32 v204, -v18, v186, v204
	v_fma_f32 v205, -v22, v186, v205
	v_fma_f32 v206, -v26, v186, v206
	v_fma_f32 v207, -v30, v186, v207
	v_fma_f32 v204, -v19, v187, v204
	v_fma_f32 v205, -v23, v187, v205
	v_fma_f32 v206, -v27, v187, v206
	v_fma_f32 v207, -v31, v187, v207
	ds_read_b128 v[16:19], v63 offset:15328
	ds_read_b128 v[20:23], v63 offset:15600
	ds_read_b128 v[24:27], v63 offset:15872
	ds_read_b128 v[28:31], v63 offset:16144
	s_waitcnt lgkmcnt(11)
	v_fma_f32 v208, -v32, v184, v208
	s_waitcnt lgkmcnt(10)
	v_fma_f32 v209, -v36, v184, v209
	s_waitcnt lgkmcnt(9)
	v_fma_f32 v210, -v40, v184, v210
	s_waitcnt lgkmcnt(8)
	v_fma_f32 v211, -v44, v184, v211
	v_fma_f32 v208, -v33, v185, v208
	v_fma_f32 v209, -v37, v185, v209
	v_fma_f32 v210, -v41, v185, v210
	v_fma_f32 v211, -v45, v185, v211
	v_fma_f32 v208, -v34, v186, v208
	v_fma_f32 v209, -v38, v186, v209
	v_fma_f32 v210, -v42, v186, v210
	v_fma_f32 v211, -v46, v186, v211
	v_fma_f32 v208, -v35, v187, v208
	v_fma_f32 v209, -v39, v187, v209
	v_fma_f32 v210, -v43, v187, v210
	v_fma_f32 v211, -v47, v187, v211
	ds_read_b128 v[32:35], v63 offset:16416
	ds_read_b128 v[36:39], v63 offset:16688
	ds_read_b128 v[40:43], v63 offset:16960
	ds_read_b128 v[44:47], v63 offset:17232
	s_waitcnt lgkmcnt(11)
	v_fma_f32 v212, -v0, v184, v212
	s_waitcnt lgkmcnt(10)
	v_fma_f32 v213, -v4, v184, v213
	s_waitcnt lgkmcnt(9)
	v_fma_f32 v214, -v8, v184, v214
	s_waitcnt lgkmcnt(8)
	v_fma_f32 v215, -v12, v184, v215
	v_fma_f32 v212, -v1, v185, v212
	v_fma_f32 v213, -v5, v185, v213
	v_fma_f32 v214, -v9, v185, v214
	v_fma_f32 v215, -v13, v185, v215
	v_fma_f32 v212, -v2, v186, v212
	v_fma_f32 v213, -v6, v186, v213
	v_fma_f32 v214, -v10, v186, v214
	v_fma_f32 v215, -v14, v186, v215
	v_fma_f32 v212, -v3, v187, v212
	v_fma_f32 v213, -v7, v187, v213
	v_fma_f32 v214, -v11, v187, v214
	v_fma_f32 v215, -v15, v187, v215
	ds_read_b128 v[0:3], v63 offset:8816
	ds_read_b128 v[4:7], v63 offset:9088
	ds_read_b128 v[8:11], v63 offset:9360
	ds_read_b128 v[12:15], v63 offset:9632
	s_waitcnt lgkmcnt(11)
	v_fma_f32 v216, -v16, v184, v216
	s_waitcnt lgkmcnt(10)
	v_fma_f32 v217, -v20, v184, v217
	s_waitcnt lgkmcnt(9)
	v_fma_f32 v218, -v24, v184, v218
	s_waitcnt lgkmcnt(8)
	v_fma_f32 v219, -v28, v184, v219
	v_fma_f32 v216, -v17, v185, v216
	v_fma_f32 v217, -v21, v185, v217
	v_fma_f32 v218, -v25, v185, v218
	v_fma_f32 v219, -v29, v185, v219
	v_fma_f32 v216, -v18, v186, v216
	v_fma_f32 v217, -v22, v186, v217
	v_fma_f32 v218, -v26, v186, v218
	v_fma_f32 v219, -v30, v186, v219
	v_fma_f32 v216, -v19, v187, v216
	v_fma_f32 v217, -v23, v187, v217
	v_fma_f32 v218, -v27, v187, v218
	v_fma_f32 v219, -v31, v187, v219
	ds_read_b128 v[16:19], v63 offset:9904
	ds_read_b128 v[20:23], v63 offset:10176
	ds_read_b128 v[24:27], v63 offset:10448
	ds_read_b128 v[28:31], v63 offset:10720
	s_waitcnt lgkmcnt(11)
	v_fma_f32 v220, -v32, v184, v220
	s_waitcnt lgkmcnt(10)
	v_fma_f32 v221, -v36, v184, v221
	s_waitcnt lgkmcnt(9)
	v_fma_f32 v222, -v40, v184, v222
	s_waitcnt lgkmcnt(8)
	v_fma_f32 v223, -v44, v184, v223
	v_fma_f32 v220, -v33, v185, v220
	v_fma_f32 v221, -v37, v185, v221
	v_fma_f32 v222, -v41, v185, v222
	v_fma_f32 v223, -v45, v185, v223
	v_fma_f32 v220, -v34, v186, v220
	v_fma_f32 v221, -v38, v186, v221
	v_fma_f32 v222, -v42, v186, v222
	v_fma_f32 v223, -v46, v186, v223
	v_fma_f32 v220, -v35, v187, v220
	v_fma_f32 v221, -v39, v187, v221
	v_fma_f32 v222, -v43, v187, v222
	v_fma_f32 v223, -v47, v187, v223
	ds_read_b128 v[48:51], v63 offset:9104
	ds_read_b128 v[52:55], v63 offset:9376
	ds_read_b128 v[56:59], v63 offset:9648
	ds_read_b128 v[32:35], v63 offset:10992
	ds_read_b128 v[36:39], v63 offset:11264
	ds_read_b128 v[40:43], v63 offset:11536
	ds_read_b128 v[44:47], v63 offset:11808
	s_waitcnt lgkmcnt(14)
	v_fma_f32 v192, -v0, v188, v192
	s_waitcnt lgkmcnt(13)
	v_fma_f32 v193, -v4, v188, v193
	s_waitcnt lgkmcnt(12)
	v_fma_f32 v194, -v8, v188, v194
	s_waitcnt lgkmcnt(11)
	v_fma_f32 v195, -v12, v188, v195
	v_fma_f32 v192, -v1, v189, v192
	v_fma_f32 v193, -v5, v189, v193
	v_fma_f32 v194, -v9, v189, v194
	v_fma_f32 v195, -v13, v189, v195
	v_fma_f32 v192, -v2, v190, v192
	v_fma_f32 v193, -v6, v190, v193
	v_fma_f32 v194, -v10, v190, v194
	v_fma_f32 v195, -v14, v190, v195
	v_fma_f32 v192, -v3, v191, v192
	v_fma_f32 v193, -v7, v191, v193
	v_fma_f32 v194, -v11, v191, v194
	v_fma_f32 v195, -v15, v191, v195
	ds_read_b128 v[0:3], v63 offset:12080
	ds_read_b128 v[4:7], v63 offset:12352
	ds_read_b128 v[8:11], v63 offset:12624
	ds_read_b128 v[12:15], v63 offset:12896
	s_waitcnt lgkmcnt(14)
	v_fma_f32 v196, -v16, v188, v196
	s_waitcnt lgkmcnt(13)
	v_fma_f32 v197, -v20, v188, v197
	s_waitcnt lgkmcnt(10)
	v_fma_f32 v193, -v48, v192, v193
	s_waitcnt lgkmcnt(12)
	v_fma_f32 v198, -v24, v188, v198
	s_waitcnt lgkmcnt(11)
	v_fma_f32 v199, -v28, v188, v199
	s_waitcnt lgkmcnt(9)
	v_fma_f32 v194, -v52, v192, v194
	v_fma_f32 v196, -v17, v189, v196
	v_fma_f32 v197, -v21, v189, v197
	s_waitcnt lgkmcnt(8)
	v_fma_f32 v195, -v56, v192, v195
	v_fma_f32 v198, -v25, v189, v198
	v_fma_f32 v199, -v29, v189, v199
	v_fma_f32 v194, -v53, v193, v194
	v_fma_f32 v196, -v18, v190, v196
	v_fma_f32 v197, -v22, v190, v197
	v_fma_f32 v195, -v57, v193, v195
	v_fma_f32 v198, -v26, v190, v198
	v_fma_f32 v199, -v30, v190, v199
	v_fma_f32 v195, -v58, v194, v195
	v_fma_f32 v196, -v19, v191, v196
	v_fma_f32 v197, -v23, v191, v197
	v_fma_f32 v198, -v27, v191, v198
	v_fma_f32 v199, -v31, v191, v199
	ds_read_b128 v[16:19], v63 offset:13168
	ds_read_b128 v[20:23], v63 offset:13440
	ds_read_b128 v[24:27], v63 offset:13712
	ds_read_b128 v[28:31], v63 offset:13984
	s_waitcnt lgkmcnt(11)
	v_fma_f32 v200, -v32, v188, v200
	s_waitcnt lgkmcnt(10)
	v_fma_f32 v201, -v36, v188, v201
	s_waitcnt lgkmcnt(9)
	v_fma_f32 v202, -v40, v188, v202
	s_waitcnt lgkmcnt(8)
	v_fma_f32 v203, -v44, v188, v203
	v_fma_f32 v200, -v33, v189, v200
	v_fma_f32 v201, -v37, v189, v201
	v_fma_f32 v202, -v41, v189, v202
	v_fma_f32 v203, -v45, v189, v203
	v_fma_f32 v200, -v34, v190, v200
	v_fma_f32 v201, -v38, v190, v201
	v_fma_f32 v202, -v42, v190, v202
	v_fma_f32 v203, -v46, v190, v203
	v_fma_f32 v200, -v35, v191, v200
	v_fma_f32 v201, -v39, v191, v201
	v_fma_f32 v202, -v43, v191, v202
	v_fma_f32 v203, -v47, v191, v203
	ds_read_b128 v[32:35], v63 offset:14256
	ds_read_b128 v[36:39], v63 offset:14528
	ds_read_b128 v[40:43], v63 offset:14800
	ds_read_b128 v[44:47], v63 offset:15072
	s_waitcnt lgkmcnt(11)
	v_fma_f32 v204, -v0, v188, v204
	s_waitcnt lgkmcnt(10)
	v_fma_f32 v205, -v4, v188, v205
	s_waitcnt lgkmcnt(9)
	v_fma_f32 v206, -v8, v188, v206
	s_waitcnt lgkmcnt(8)
	v_fma_f32 v207, -v12, v188, v207
	v_fma_f32 v204, -v1, v189, v204
	v_fma_f32 v205, -v5, v189, v205
	v_fma_f32 v206, -v9, v189, v206
	v_fma_f32 v207, -v13, v189, v207
	v_fma_f32 v204, -v2, v190, v204
	v_fma_f32 v205, -v6, v190, v205
	v_fma_f32 v206, -v10, v190, v206
	v_fma_f32 v207, -v14, v190, v207
	v_fma_f32 v204, -v3, v191, v204
	v_fma_f32 v205, -v7, v191, v205
	v_fma_f32 v206, -v11, v191, v206
	v_fma_f32 v207, -v15, v191, v207
	ds_read_b128 v[0:3], v63 offset:15344
	ds_read_b128 v[4:7], v63 offset:15616
	ds_read_b128 v[8:11], v63 offset:15888
	ds_read_b128 v[12:15], v63 offset:16160
	s_waitcnt lgkmcnt(11)
	v_fma_f32 v208, -v16, v188, v208
	s_waitcnt lgkmcnt(10)
	v_fma_f32 v209, -v20, v188, v209
	s_waitcnt lgkmcnt(9)
	v_fma_f32 v210, -v24, v188, v210
	s_waitcnt lgkmcnt(8)
	v_fma_f32 v211, -v28, v188, v211
	v_fma_f32 v208, -v17, v189, v208
	v_fma_f32 v209, -v21, v189, v209
	v_fma_f32 v210, -v25, v189, v210
	v_fma_f32 v211, -v29, v189, v211
	v_fma_f32 v208, -v18, v190, v208
	v_fma_f32 v209, -v22, v190, v209
	v_fma_f32 v210, -v26, v190, v210
	v_fma_f32 v211, -v30, v190, v211
	v_fma_f32 v208, -v19, v191, v208
	v_fma_f32 v209, -v23, v191, v209
	v_fma_f32 v210, -v27, v191, v210
	v_fma_f32 v211, -v31, v191, v211
	ds_read_b128 v[16:19], v63 offset:16432
	ds_read_b128 v[20:23], v63 offset:16704
	ds_read_b128 v[24:27], v63 offset:16976
	ds_read_b128 v[28:31], v63 offset:17248
	s_waitcnt lgkmcnt(11)
	v_fma_f32 v212, -v32, v188, v212
	s_waitcnt lgkmcnt(10)
	v_fma_f32 v213, -v36, v188, v213
	s_waitcnt lgkmcnt(9)
	v_fma_f32 v214, -v40, v188, v214
	s_waitcnt lgkmcnt(8)
	v_fma_f32 v215, -v44, v188, v215
	v_fma_f32 v212, -v33, v189, v212
	v_fma_f32 v213, -v37, v189, v213
	v_fma_f32 v214, -v41, v189, v214
	v_fma_f32 v215, -v45, v189, v215
	v_fma_f32 v212, -v34, v190, v212
	v_fma_f32 v213, -v38, v190, v213
	v_fma_f32 v214, -v42, v190, v214
	v_fma_f32 v215, -v46, v190, v215
	v_fma_f32 v212, -v35, v191, v212
	v_fma_f32 v213, -v39, v191, v213
	v_fma_f32 v214, -v43, v191, v214
	v_fma_f32 v215, -v47, v191, v215
	ds_read_b128 v[32:35], v63 offset:9920
	ds_read_b128 v[36:39], v63 offset:10192
	ds_read_b128 v[40:43], v63 offset:10464
	ds_read_b128 v[44:47], v63 offset:10736
	s_waitcnt lgkmcnt(11)
	v_fma_f32 v216, -v0, v188, v216
	s_waitcnt lgkmcnt(10)
	v_fma_f32 v217, -v4, v188, v217
	s_waitcnt lgkmcnt(9)
	v_fma_f32 v218, -v8, v188, v218
	s_waitcnt lgkmcnt(8)
	v_fma_f32 v219, -v12, v188, v219
	v_fma_f32 v216, -v1, v189, v216
	v_fma_f32 v217, -v5, v189, v217
	v_fma_f32 v218, -v9, v189, v218
	v_fma_f32 v219, -v13, v189, v219
	v_fma_f32 v216, -v2, v190, v216
	v_fma_f32 v217, -v6, v190, v217
	v_fma_f32 v218, -v10, v190, v218
	v_fma_f32 v219, -v14, v190, v219
	v_fma_f32 v216, -v3, v191, v216
	v_fma_f32 v217, -v7, v191, v217
	v_fma_f32 v218, -v11, v191, v218
	v_fma_f32 v219, -v15, v191, v219
	ds_read_b128 v[0:3], v63 offset:11008
	ds_read_b128 v[4:7], v63 offset:11280
	ds_read_b128 v[8:11], v63 offset:11552
	ds_read_b128 v[12:15], v63 offset:11824
	s_waitcnt lgkmcnt(11)
	v_fma_f32 v220, -v16, v188, v220
	s_waitcnt lgkmcnt(10)
	v_fma_f32 v221, -v20, v188, v221
	s_waitcnt lgkmcnt(9)
	v_fma_f32 v222, -v24, v188, v222
	s_waitcnt lgkmcnt(8)
	v_fma_f32 v223, -v28, v188, v223
	v_fma_f32 v220, -v17, v189, v220
	v_fma_f32 v221, -v21, v189, v221
	v_fma_f32 v222, -v25, v189, v222
	v_fma_f32 v223, -v29, v189, v223
	v_fma_f32 v220, -v18, v190, v220
	v_fma_f32 v221, -v22, v190, v221
	v_fma_f32 v222, -v26, v190, v222
	v_fma_f32 v223, -v30, v190, v223
	v_fma_f32 v220, -v19, v191, v220
	v_fma_f32 v221, -v23, v191, v221
	v_fma_f32 v222, -v27, v191, v222
	v_fma_f32 v223, -v31, v191, v223
	ds_read_b128 v[48:51], v63 offset:10208
	ds_read_b128 v[52:55], v63 offset:10480
	ds_read_b128 v[56:59], v63 offset:10752
	ds_read_b128 v[16:19], v63 offset:12096
	ds_read_b128 v[20:23], v63 offset:12368
	ds_read_b128 v[24:27], v63 offset:12640
	ds_read_b128 v[28:31], v63 offset:12912
	s_waitcnt lgkmcnt(14)
	v_fma_f32 v196, -v32, v192, v196
	s_waitcnt lgkmcnt(13)
	v_fma_f32 v197, -v36, v192, v197
	s_waitcnt lgkmcnt(12)
	v_fma_f32 v198, -v40, v192, v198
	s_waitcnt lgkmcnt(11)
	v_fma_f32 v199, -v44, v192, v199
	v_fma_f32 v196, -v33, v193, v196
	v_fma_f32 v197, -v37, v193, v197
	v_fma_f32 v198, -v41, v193, v198
	v_fma_f32 v199, -v45, v193, v199
	v_fma_f32 v196, -v34, v194, v196
	v_fma_f32 v197, -v38, v194, v197
	v_fma_f32 v198, -v42, v194, v198
	v_fma_f32 v199, -v46, v194, v199
	v_fma_f32 v196, -v35, v195, v196
	v_fma_f32 v197, -v39, v195, v197
	v_fma_f32 v198, -v43, v195, v198
	v_fma_f32 v199, -v47, v195, v199
	ds_read_b128 v[32:35], v63 offset:13184
	ds_read_b128 v[36:39], v63 offset:13456
	ds_read_b128 v[40:43], v63 offset:13728
	ds_read_b128 v[44:47], v63 offset:14000
	s_waitcnt lgkmcnt(14)
	v_fma_f32 v200, -v0, v192, v200
	s_waitcnt lgkmcnt(13)
	v_fma_f32 v201, -v4, v192, v201
	s_waitcnt lgkmcnt(10)
	v_fma_f32 v197, -v48, v196, v197
	s_waitcnt lgkmcnt(12)
	v_fma_f32 v202, -v8, v192, v202
	s_waitcnt lgkmcnt(11)
	v_fma_f32 v203, -v12, v192, v203
	s_waitcnt lgkmcnt(9)
	v_fma_f32 v198, -v52, v196, v198
	v_fma_f32 v200, -v1, v193, v200
	v_fma_f32 v201, -v5, v193, v201
	s_waitcnt lgkmcnt(8)
	v_fma_f32 v199, -v56, v196, v199
	v_fma_f32 v202, -v9, v193, v202
	v_fma_f32 v203, -v13, v193, v203
	v_fma_f32 v198, -v53, v197, v198
	v_fma_f32 v200, -v2, v194, v200
	v_fma_f32 v201, -v6, v194, v201
	v_fma_f32 v199, -v57, v197, v199
	v_fma_f32 v202, -v10, v194, v202
	v_fma_f32 v203, -v14, v194, v203
	v_fma_f32 v199, -v58, v198, v199
	v_fma_f32 v200, -v3, v195, v200
	v_fma_f32 v201, -v7, v195, v201
	v_fma_f32 v202, -v11, v195, v202
	v_fma_f32 v203, -v15, v195, v203
	ds_read_b128 v[0:3], v63 offset:14272
	ds_read_b128 v[4:7], v63 offset:14544
	ds_read_b128 v[8:11], v63 offset:14816
	ds_read_b128 v[12:15], v63 offset:15088
	s_waitcnt lgkmcnt(11)
	v_fma_f32 v204, -v16, v192, v204
	s_waitcnt lgkmcnt(10)
	v_fma_f32 v205, -v20, v192, v205
	s_waitcnt lgkmcnt(9)
	v_fma_f32 v206, -v24, v192, v206
	s_waitcnt lgkmcnt(8)
	v_fma_f32 v207, -v28, v192, v207
	v_fma_f32 v204, -v17, v193, v204
	v_fma_f32 v205, -v21, v193, v205
	v_fma_f32 v206, -v25, v193, v206
	v_fma_f32 v207, -v29, v193, v207
	v_fma_f32 v204, -v18, v194, v204
	v_fma_f32 v205, -v22, v194, v205
	v_fma_f32 v206, -v26, v194, v206
	v_fma_f32 v207, -v30, v194, v207
	v_fma_f32 v204, -v19, v195, v204
	v_fma_f32 v205, -v23, v195, v205
	v_fma_f32 v206, -v27, v195, v206
	v_fma_f32 v207, -v31, v195, v207
	ds_read_b128 v[16:19], v63 offset:15360
	ds_read_b128 v[20:23], v63 offset:15632
	ds_read_b128 v[24:27], v63 offset:15904
	ds_read_b128 v[28:31], v63 offset:16176
	s_waitcnt lgkmcnt(11)
	v_fma_f32 v208, -v32, v192, v208
	s_waitcnt lgkmcnt(10)
	v_fma_f32 v209, -v36, v192, v209
	s_waitcnt lgkmcnt(9)
	v_fma_f32 v210, -v40, v192, v210
	s_waitcnt lgkmcnt(8)
	v_fma_f32 v211, -v44, v192, v211
	v_fma_f32 v208, -v33, v193, v208
	v_fma_f32 v209, -v37, v193, v209
	v_fma_f32 v210, -v41, v193, v210
	v_fma_f32 v211, -v45, v193, v211
	v_fma_f32 v208, -v34, v194, v208
	v_fma_f32 v209, -v38, v194, v209
	v_fma_f32 v210, -v42, v194, v210
	v_fma_f32 v211, -v46, v194, v211
	v_fma_f32 v208, -v35, v195, v208
	v_fma_f32 v209, -v39, v195, v209
	v_fma_f32 v210, -v43, v195, v210
	v_fma_f32 v211, -v47, v195, v211
	ds_read_b128 v[32:35], v63 offset:16448
	ds_read_b128 v[36:39], v63 offset:16720
	ds_read_b128 v[40:43], v63 offset:16992
	ds_read_b128 v[44:47], v63 offset:17264
	s_waitcnt lgkmcnt(11)
	v_fma_f32 v212, -v0, v192, v212
	s_waitcnt lgkmcnt(10)
	v_fma_f32 v213, -v4, v192, v213
	s_waitcnt lgkmcnt(9)
	v_fma_f32 v214, -v8, v192, v214
	s_waitcnt lgkmcnt(8)
	v_fma_f32 v215, -v12, v192, v215
	v_fma_f32 v212, -v1, v193, v212
	v_fma_f32 v213, -v5, v193, v213
	v_fma_f32 v214, -v9, v193, v214
	v_fma_f32 v215, -v13, v193, v215
	v_fma_f32 v212, -v2, v194, v212
	v_fma_f32 v213, -v6, v194, v213
	v_fma_f32 v214, -v10, v194, v214
	v_fma_f32 v215, -v14, v194, v215
	v_fma_f32 v212, -v3, v195, v212
	v_fma_f32 v213, -v7, v195, v213
	v_fma_f32 v214, -v11, v195, v214
	v_fma_f32 v215, -v15, v195, v215
	ds_read_b128 v[0:3], v63 offset:11024
	ds_read_b128 v[4:7], v63 offset:11296
	ds_read_b128 v[8:11], v63 offset:11568
	ds_read_b128 v[12:15], v63 offset:11840
	s_waitcnt lgkmcnt(11)
	v_fma_f32 v216, -v16, v192, v216
	s_waitcnt lgkmcnt(10)
	v_fma_f32 v217, -v20, v192, v217
	s_waitcnt lgkmcnt(9)
	v_fma_f32 v218, -v24, v192, v218
	s_waitcnt lgkmcnt(8)
	v_fma_f32 v219, -v28, v192, v219
	v_fma_f32 v216, -v17, v193, v216
	v_fma_f32 v217, -v21, v193, v217
	v_fma_f32 v218, -v25, v193, v218
	v_fma_f32 v219, -v29, v193, v219
	v_fma_f32 v216, -v18, v194, v216
	v_fma_f32 v217, -v22, v194, v217
	v_fma_f32 v218, -v26, v194, v218
	v_fma_f32 v219, -v30, v194, v219
	v_fma_f32 v216, -v19, v195, v216
	v_fma_f32 v217, -v23, v195, v217
	v_fma_f32 v218, -v27, v195, v218
	v_fma_f32 v219, -v31, v195, v219
	ds_read_b128 v[16:19], v63 offset:12112
	ds_read_b128 v[20:23], v63 offset:12384
	ds_read_b128 v[24:27], v63 offset:12656
	ds_read_b128 v[28:31], v63 offset:12928
	s_waitcnt lgkmcnt(11)
	v_fma_f32 v220, -v32, v192, v220
	s_waitcnt lgkmcnt(10)
	v_fma_f32 v221, -v36, v192, v221
	s_waitcnt lgkmcnt(9)
	v_fma_f32 v222, -v40, v192, v222
	s_waitcnt lgkmcnt(8)
	v_fma_f32 v223, -v44, v192, v223
	v_fma_f32 v220, -v33, v193, v220
	v_fma_f32 v221, -v37, v193, v221
	v_fma_f32 v222, -v41, v193, v222
	v_fma_f32 v223, -v45, v193, v223
	v_fma_f32 v220, -v34, v194, v220
	v_fma_f32 v221, -v38, v194, v221
	v_fma_f32 v222, -v42, v194, v222
	v_fma_f32 v223, -v46, v194, v223
	v_fma_f32 v220, -v35, v195, v220
	v_fma_f32 v221, -v39, v195, v221
	v_fma_f32 v222, -v43, v195, v222
	v_fma_f32 v223, -v47, v195, v223
	ds_read_b128 v[48:51], v63 offset:11312
	ds_read_b128 v[52:55], v63 offset:11584
	ds_read_b128 v[56:59], v63 offset:11856
	ds_read_b128 v[32:35], v63 offset:13200
	ds_read_b128 v[36:39], v63 offset:13472
	ds_read_b128 v[40:43], v63 offset:13744
	ds_read_b128 v[44:47], v63 offset:14016
	s_waitcnt lgkmcnt(14)
	v_fma_f32 v200, -v0, v196, v200
	s_waitcnt lgkmcnt(13)
	v_fma_f32 v201, -v4, v196, v201
	s_waitcnt lgkmcnt(12)
	v_fma_f32 v202, -v8, v196, v202
	s_waitcnt lgkmcnt(11)
	v_fma_f32 v203, -v12, v196, v203
	v_fma_f32 v200, -v1, v197, v200
	v_fma_f32 v201, -v5, v197, v201
	v_fma_f32 v202, -v9, v197, v202
	v_fma_f32 v203, -v13, v197, v203
	v_fma_f32 v200, -v2, v198, v200
	v_fma_f32 v201, -v6, v198, v201
	v_fma_f32 v202, -v10, v198, v202
	v_fma_f32 v203, -v14, v198, v203
	v_fma_f32 v200, -v3, v199, v200
	v_fma_f32 v201, -v7, v199, v201
	v_fma_f32 v202, -v11, v199, v202
	v_fma_f32 v203, -v15, v199, v203
	ds_read_b128 v[0:3], v63 offset:14288
	ds_read_b128 v[4:7], v63 offset:14560
	ds_read_b128 v[8:11], v63 offset:14832
	ds_read_b128 v[12:15], v63 offset:15104
	s_waitcnt lgkmcnt(14)
	v_fma_f32 v204, -v16, v196, v204
	s_waitcnt lgkmcnt(13)
	v_fma_f32 v205, -v20, v196, v205
	s_waitcnt lgkmcnt(10)
	v_fma_f32 v201, -v48, v200, v201
	s_waitcnt lgkmcnt(12)
	v_fma_f32 v206, -v24, v196, v206
	s_waitcnt lgkmcnt(11)
	v_fma_f32 v207, -v28, v196, v207
	s_waitcnt lgkmcnt(9)
	v_fma_f32 v202, -v52, v200, v202
	v_fma_f32 v204, -v17, v197, v204
	v_fma_f32 v205, -v21, v197, v205
	s_waitcnt lgkmcnt(8)
	v_fma_f32 v203, -v56, v200, v203
	v_fma_f32 v206, -v25, v197, v206
	v_fma_f32 v207, -v29, v197, v207
	v_fma_f32 v202, -v53, v201, v202
	v_fma_f32 v204, -v18, v198, v204
	v_fma_f32 v205, -v22, v198, v205
	v_fma_f32 v203, -v57, v201, v203
	v_fma_f32 v206, -v26, v198, v206
	v_fma_f32 v207, -v30, v198, v207
	v_fma_f32 v203, -v58, v202, v203
	v_fma_f32 v204, -v19, v199, v204
	v_fma_f32 v205, -v23, v199, v205
	v_fma_f32 v206, -v27, v199, v206
	v_fma_f32 v207, -v31, v199, v207
	ds_read_b128 v[16:19], v63 offset:15376
	ds_read_b128 v[20:23], v63 offset:15648
	ds_read_b128 v[24:27], v63 offset:15920
	ds_read_b128 v[28:31], v63 offset:16192
	s_waitcnt lgkmcnt(11)
	v_fma_f32 v208, -v32, v196, v208
	s_waitcnt lgkmcnt(10)
	v_fma_f32 v209, -v36, v196, v209
	s_waitcnt lgkmcnt(9)
	v_fma_f32 v210, -v40, v196, v210
	s_waitcnt lgkmcnt(8)
	v_fma_f32 v211, -v44, v196, v211
	v_fma_f32 v208, -v33, v197, v208
	v_fma_f32 v209, -v37, v197, v209
	v_fma_f32 v210, -v41, v197, v210
	v_fma_f32 v211, -v45, v197, v211
	v_fma_f32 v208, -v34, v198, v208
	v_fma_f32 v209, -v38, v198, v209
	v_fma_f32 v210, -v42, v198, v210
	v_fma_f32 v211, -v46, v198, v211
	v_fma_f32 v208, -v35, v199, v208
	v_fma_f32 v209, -v39, v199, v209
	v_fma_f32 v210, -v43, v199, v210
	v_fma_f32 v211, -v47, v199, v211
	ds_read_b128 v[32:35], v63 offset:16464
	ds_read_b128 v[36:39], v63 offset:16736
	ds_read_b128 v[40:43], v63 offset:17008
	ds_read_b128 v[44:47], v63 offset:17280
	s_waitcnt lgkmcnt(11)
	v_fma_f32 v212, -v0, v196, v212
	s_waitcnt lgkmcnt(10)
	v_fma_f32 v213, -v4, v196, v213
	s_waitcnt lgkmcnt(9)
	v_fma_f32 v214, -v8, v196, v214
	s_waitcnt lgkmcnt(8)
	v_fma_f32 v215, -v12, v196, v215
	v_fma_f32 v212, -v1, v197, v212
	v_fma_f32 v213, -v5, v197, v213
	v_fma_f32 v214, -v9, v197, v214
	v_fma_f32 v215, -v13, v197, v215
	v_fma_f32 v212, -v2, v198, v212
	v_fma_f32 v213, -v6, v198, v213
	v_fma_f32 v214, -v10, v198, v214
	v_fma_f32 v215, -v14, v198, v215
	v_fma_f32 v212, -v3, v199, v212
	v_fma_f32 v213, -v7, v199, v213
	v_fma_f32 v214, -v11, v199, v214
	v_fma_f32 v215, -v15, v199, v215
	ds_read_b128 v[0:3], v63 offset:12128
	ds_read_b128 v[4:7], v63 offset:12400
	ds_read_b128 v[8:11], v63 offset:12672
	ds_read_b128 v[12:15], v63 offset:12944
	s_waitcnt lgkmcnt(11)
	v_fma_f32 v216, -v16, v196, v216
	s_waitcnt lgkmcnt(10)
	v_fma_f32 v217, -v20, v196, v217
	s_waitcnt lgkmcnt(9)
	v_fma_f32 v218, -v24, v196, v218
	s_waitcnt lgkmcnt(8)
	v_fma_f32 v219, -v28, v196, v219
	v_fma_f32 v216, -v17, v197, v216
	v_fma_f32 v217, -v21, v197, v217
	v_fma_f32 v218, -v25, v197, v218
	v_fma_f32 v219, -v29, v197, v219
	v_fma_f32 v216, -v18, v198, v216
	v_fma_f32 v217, -v22, v198, v217
	v_fma_f32 v218, -v26, v198, v218
	v_fma_f32 v219, -v30, v198, v219
	v_fma_f32 v216, -v19, v199, v216
	v_fma_f32 v217, -v23, v199, v217
	v_fma_f32 v218, -v27, v199, v218
	v_fma_f32 v219, -v31, v199, v219
	ds_read_b128 v[16:19], v63 offset:13216
	ds_read_b128 v[20:23], v63 offset:13488
	ds_read_b128 v[24:27], v63 offset:13760
	ds_read_b128 v[28:31], v63 offset:14032
	s_waitcnt lgkmcnt(11)
	v_fma_f32 v220, -v32, v196, v220
	s_waitcnt lgkmcnt(10)
	v_fma_f32 v221, -v36, v196, v221
	s_waitcnt lgkmcnt(9)
	v_fma_f32 v222, -v40, v196, v222
	s_waitcnt lgkmcnt(8)
	v_fma_f32 v223, -v44, v196, v223
	v_fma_f32 v220, -v33, v197, v220
	v_fma_f32 v221, -v37, v197, v221
	v_fma_f32 v222, -v41, v197, v222
	v_fma_f32 v223, -v45, v197, v223
	v_fma_f32 v220, -v34, v198, v220
	v_fma_f32 v221, -v38, v198, v221
	v_fma_f32 v222, -v42, v198, v222
	v_fma_f32 v223, -v46, v198, v223
	v_fma_f32 v220, -v35, v199, v220
	v_fma_f32 v221, -v39, v199, v221
	v_fma_f32 v222, -v43, v199, v222
	v_fma_f32 v223, -v47, v199, v223
	ds_read_b128 v[48:51], v63 offset:12416
	ds_read_b128 v[52:55], v63 offset:12688
	ds_read_b128 v[56:59], v63 offset:12960
	ds_read_b128 v[32:35], v63 offset:14304
	ds_read_b128 v[36:39], v63 offset:14576
	ds_read_b128 v[40:43], v63 offset:14848
	ds_read_b128 v[44:47], v63 offset:15120
	s_waitcnt lgkmcnt(14)
	v_fma_f32 v204, -v0, v200, v204
	s_waitcnt lgkmcnt(13)
	v_fma_f32 v205, -v4, v200, v205
	s_waitcnt lgkmcnt(12)
	v_fma_f32 v206, -v8, v200, v206
	s_waitcnt lgkmcnt(11)
	v_fma_f32 v207, -v12, v200, v207
	v_fma_f32 v204, -v1, v201, v204
	v_fma_f32 v205, -v5, v201, v205
	v_fma_f32 v206, -v9, v201, v206
	v_fma_f32 v207, -v13, v201, v207
	v_fma_f32 v204, -v2, v202, v204
	v_fma_f32 v205, -v6, v202, v205
	v_fma_f32 v206, -v10, v202, v206
	v_fma_f32 v207, -v14, v202, v207
	v_fma_f32 v204, -v3, v203, v204
	v_fma_f32 v205, -v7, v203, v205
	v_fma_f32 v206, -v11, v203, v206
	v_fma_f32 v207, -v15, v203, v207
	ds_read_b128 v[0:3], v63 offset:15392
	ds_read_b128 v[4:7], v63 offset:15664
	ds_read_b128 v[8:11], v63 offset:15936
	ds_read_b128 v[12:15], v63 offset:16208
	s_waitcnt lgkmcnt(14)
	v_fma_f32 v208, -v16, v200, v208
	s_waitcnt lgkmcnt(13)
	v_fma_f32 v209, -v20, v200, v209
	s_waitcnt lgkmcnt(10)
	v_fma_f32 v205, -v48, v204, v205
	s_waitcnt lgkmcnt(12)
	v_fma_f32 v210, -v24, v200, v210
	s_waitcnt lgkmcnt(11)
	v_fma_f32 v211, -v28, v200, v211
	s_waitcnt lgkmcnt(9)
	v_fma_f32 v206, -v52, v204, v206
	v_fma_f32 v208, -v17, v201, v208
	v_fma_f32 v209, -v21, v201, v209
	s_waitcnt lgkmcnt(8)
	v_fma_f32 v207, -v56, v204, v207
	v_fma_f32 v210, -v25, v201, v210
	v_fma_f32 v211, -v29, v201, v211
	v_fma_f32 v206, -v53, v205, v206
	v_fma_f32 v208, -v18, v202, v208
	v_fma_f32 v209, -v22, v202, v209
	v_fma_f32 v207, -v57, v205, v207
	v_fma_f32 v210, -v26, v202, v210
	v_fma_f32 v211, -v30, v202, v211
	v_fma_f32 v207, -v58, v206, v207
	v_fma_f32 v208, -v19, v203, v208
	v_fma_f32 v209, -v23, v203, v209
	v_fma_f32 v210, -v27, v203, v210
	v_fma_f32 v211, -v31, v203, v211
	ds_read_b128 v[16:19], v63 offset:16480
	ds_read_b128 v[20:23], v63 offset:16752
	ds_read_b128 v[24:27], v63 offset:17024
	ds_read_b128 v[28:31], v63 offset:17296
	s_waitcnt lgkmcnt(11)
	v_fma_f32 v212, -v32, v200, v212
	s_waitcnt lgkmcnt(10)
	v_fma_f32 v213, -v36, v200, v213
	s_waitcnt lgkmcnt(9)
	v_fma_f32 v214, -v40, v200, v214
	s_waitcnt lgkmcnt(8)
	v_fma_f32 v215, -v44, v200, v215
	v_fma_f32 v212, -v33, v201, v212
	v_fma_f32 v213, -v37, v201, v213
	v_fma_f32 v214, -v41, v201, v214
	v_fma_f32 v215, -v45, v201, v215
	v_fma_f32 v212, -v34, v202, v212
	v_fma_f32 v213, -v38, v202, v213
	v_fma_f32 v214, -v42, v202, v214
	v_fma_f32 v215, -v46, v202, v215
	v_fma_f32 v212, -v35, v203, v212
	v_fma_f32 v213, -v39, v203, v213
	v_fma_f32 v214, -v43, v203, v214
	v_fma_f32 v215, -v47, v203, v215
	ds_read_b128 v[32:35], v63 offset:13232
	ds_read_b128 v[36:39], v63 offset:13504
	ds_read_b128 v[40:43], v63 offset:13776
	ds_read_b128 v[44:47], v63 offset:14048
	s_waitcnt lgkmcnt(11)
	v_fma_f32 v216, -v0, v200, v216
	s_waitcnt lgkmcnt(10)
	v_fma_f32 v217, -v4, v200, v217
	s_waitcnt lgkmcnt(9)
	v_fma_f32 v218, -v8, v200, v218
	s_waitcnt lgkmcnt(8)
	v_fma_f32 v219, -v12, v200, v219
	v_fma_f32 v216, -v1, v201, v216
	v_fma_f32 v217, -v5, v201, v217
	v_fma_f32 v218, -v9, v201, v218
	v_fma_f32 v219, -v13, v201, v219
	v_fma_f32 v216, -v2, v202, v216
	v_fma_f32 v217, -v6, v202, v217
	v_fma_f32 v218, -v10, v202, v218
	v_fma_f32 v219, -v14, v202, v219
	v_fma_f32 v216, -v3, v203, v216
	v_fma_f32 v217, -v7, v203, v217
	v_fma_f32 v218, -v11, v203, v218
	v_fma_f32 v219, -v15, v203, v219
	ds_read_b128 v[0:3], v63 offset:14320
	ds_read_b128 v[4:7], v63 offset:14592
	ds_read_b128 v[8:11], v63 offset:14864
	ds_read_b128 v[12:15], v63 offset:15136
	s_waitcnt lgkmcnt(11)
	v_fma_f32 v220, -v16, v200, v220
	s_waitcnt lgkmcnt(10)
	v_fma_f32 v221, -v20, v200, v221
	s_waitcnt lgkmcnt(9)
	v_fma_f32 v222, -v24, v200, v222
	s_waitcnt lgkmcnt(8)
	v_fma_f32 v223, -v28, v200, v223
	v_fma_f32 v220, -v17, v201, v220
	v_fma_f32 v221, -v21, v201, v221
	v_fma_f32 v222, -v25, v201, v222
	v_fma_f32 v223, -v29, v201, v223
	v_fma_f32 v220, -v18, v202, v220
	v_fma_f32 v221, -v22, v202, v221
	v_fma_f32 v222, -v26, v202, v222
	v_fma_f32 v223, -v30, v202, v223
	v_fma_f32 v220, -v19, v203, v220
	v_fma_f32 v221, -v23, v203, v221
	v_fma_f32 v222, -v27, v203, v222
	v_fma_f32 v223, -v31, v203, v223
	ds_read_b128 v[48:51], v63 offset:13520
	ds_read_b128 v[52:55], v63 offset:13792
	ds_read_b128 v[56:59], v63 offset:14064
	ds_read_b128 v[16:19], v63 offset:15408
	ds_read_b128 v[20:23], v63 offset:15680
	ds_read_b128 v[24:27], v63 offset:15952
	ds_read_b128 v[28:31], v63 offset:16224
	s_waitcnt lgkmcnt(14)
	v_fma_f32 v208, -v32, v204, v208
	s_waitcnt lgkmcnt(13)
	v_fma_f32 v209, -v36, v204, v209
	s_waitcnt lgkmcnt(12)
	v_fma_f32 v210, -v40, v204, v210
	s_waitcnt lgkmcnt(11)
	v_fma_f32 v211, -v44, v204, v211
	v_fma_f32 v208, -v33, v205, v208
	v_fma_f32 v209, -v37, v205, v209
	v_fma_f32 v210, -v41, v205, v210
	v_fma_f32 v211, -v45, v205, v211
	v_fma_f32 v208, -v34, v206, v208
	v_fma_f32 v209, -v38, v206, v209
	v_fma_f32 v210, -v42, v206, v210
	v_fma_f32 v211, -v46, v206, v211
	v_fma_f32 v208, -v35, v207, v208
	v_fma_f32 v209, -v39, v207, v209
	v_fma_f32 v210, -v43, v207, v210
	v_fma_f32 v211, -v47, v207, v211
	ds_read_b128 v[32:35], v63 offset:16496
	ds_read_b128 v[36:39], v63 offset:16768
	ds_read_b128 v[40:43], v63 offset:17040
	ds_read_b128 v[44:47], v63 offset:17312
	s_waitcnt lgkmcnt(14)
	v_fma_f32 v212, -v0, v204, v212
	s_waitcnt lgkmcnt(13)
	v_fma_f32 v213, -v4, v204, v213
	s_waitcnt lgkmcnt(10)
	v_fma_f32 v209, -v48, v208, v209
	s_waitcnt lgkmcnt(12)
	v_fma_f32 v214, -v8, v204, v214
	s_waitcnt lgkmcnt(11)
	v_fma_f32 v215, -v12, v204, v215
	s_waitcnt lgkmcnt(9)
	v_fma_f32 v210, -v52, v208, v210
	v_fma_f32 v212, -v1, v205, v212
	v_fma_f32 v213, -v5, v205, v213
	s_waitcnt lgkmcnt(8)
	v_fma_f32 v211, -v56, v208, v211
	v_fma_f32 v214, -v9, v205, v214
	v_fma_f32 v215, -v13, v205, v215
	v_fma_f32 v210, -v53, v209, v210
	v_fma_f32 v212, -v2, v206, v212
	v_fma_f32 v213, -v6, v206, v213
	v_fma_f32 v211, -v57, v209, v211
	v_fma_f32 v214, -v10, v206, v214
	v_fma_f32 v215, -v14, v206, v215
	v_fma_f32 v211, -v58, v210, v211
	v_fma_f32 v212, -v3, v207, v212
	v_fma_f32 v213, -v7, v207, v213
	v_fma_f32 v214, -v11, v207, v214
	v_fma_f32 v215, -v15, v207, v215
	ds_read_b128 v[0:3], v63 offset:14336
	ds_read_b128 v[4:7], v63 offset:14608
	ds_read_b128 v[8:11], v63 offset:14880
	ds_read_b128 v[12:15], v63 offset:15152
	s_waitcnt lgkmcnt(11)
	v_fma_f32 v216, -v16, v204, v216
	s_waitcnt lgkmcnt(10)
	v_fma_f32 v217, -v20, v204, v217
	s_waitcnt lgkmcnt(9)
	v_fma_f32 v218, -v24, v204, v218
	s_waitcnt lgkmcnt(8)
	v_fma_f32 v219, -v28, v204, v219
	v_fma_f32 v216, -v17, v205, v216
	v_fma_f32 v217, -v21, v205, v217
	v_fma_f32 v218, -v25, v205, v218
	v_fma_f32 v219, -v29, v205, v219
	v_fma_f32 v216, -v18, v206, v216
	v_fma_f32 v217, -v22, v206, v217
	v_fma_f32 v218, -v26, v206, v218
	v_fma_f32 v219, -v30, v206, v219
	v_fma_f32 v216, -v19, v207, v216
	v_fma_f32 v217, -v23, v207, v217
	v_fma_f32 v218, -v27, v207, v218
	v_fma_f32 v219, -v31, v207, v219
	ds_read_b128 v[16:19], v63 offset:15424
	ds_read_b128 v[20:23], v63 offset:15696
	ds_read_b128 v[24:27], v63 offset:15968
	ds_read_b128 v[28:31], v63 offset:16240
	s_waitcnt lgkmcnt(11)
	v_fma_f32 v220, -v32, v204, v220
	s_waitcnt lgkmcnt(10)
	v_fma_f32 v221, -v36, v204, v221
	s_waitcnt lgkmcnt(9)
	v_fma_f32 v222, -v40, v204, v222
	s_waitcnt lgkmcnt(8)
	v_fma_f32 v223, -v44, v204, v223
	v_fma_f32 v220, -v33, v205, v220
	v_fma_f32 v221, -v37, v205, v221
	v_fma_f32 v222, -v41, v205, v222
	v_fma_f32 v223, -v45, v205, v223
	v_fma_f32 v220, -v34, v206, v220
	v_fma_f32 v221, -v38, v206, v221
	v_fma_f32 v222, -v42, v206, v222
	v_fma_f32 v223, -v46, v206, v223
	v_fma_f32 v220, -v35, v207, v220
	v_fma_f32 v221, -v39, v207, v221
	v_fma_f32 v222, -v43, v207, v222
	v_fma_f32 v223, -v47, v207, v223
	ds_read_b128 v[48:51], v63 offset:14624
	ds_read_b128 v[52:55], v63 offset:14896
	ds_read_b128 v[56:59], v63 offset:15168
	ds_read_b128 v[32:35], v63 offset:16512
	ds_read_b128 v[36:39], v63 offset:16784
	ds_read_b128 v[40:43], v63 offset:17056
	ds_read_b128 v[44:47], v63 offset:17328
	s_waitcnt lgkmcnt(14)
	v_fma_f32 v212, -v0, v208, v212
	s_waitcnt lgkmcnt(13)
	v_fma_f32 v213, -v4, v208, v213
	s_waitcnt lgkmcnt(12)
	v_fma_f32 v214, -v8, v208, v214
	s_waitcnt lgkmcnt(11)
	v_fma_f32 v215, -v12, v208, v215
	v_fma_f32 v212, -v1, v209, v212
	v_fma_f32 v213, -v5, v209, v213
	v_fma_f32 v214, -v9, v209, v214
	v_fma_f32 v215, -v13, v209, v215
	v_fma_f32 v212, -v2, v210, v212
	v_fma_f32 v213, -v6, v210, v213
	v_fma_f32 v214, -v10, v210, v214
	v_fma_f32 v215, -v14, v210, v215
	v_fma_f32 v212, -v3, v211, v212
	v_fma_f32 v213, -v7, v211, v213
	v_fma_f32 v214, -v11, v211, v214
	v_fma_f32 v215, -v15, v211, v215
	ds_read_b128 v[0:3], v63 offset:15440
	ds_read_b128 v[4:7], v63 offset:15712
	ds_read_b128 v[8:11], v63 offset:15984
	ds_read_b128 v[12:15], v63 offset:16256
	s_waitcnt lgkmcnt(14)
	v_fma_f32 v216, -v16, v208, v216
	s_waitcnt lgkmcnt(13)
	v_fma_f32 v217, -v20, v208, v217
	s_waitcnt lgkmcnt(10)
	v_fma_f32 v213, -v48, v212, v213
	s_waitcnt lgkmcnt(12)
	v_fma_f32 v218, -v24, v208, v218
	s_waitcnt lgkmcnt(11)
	v_fma_f32 v219, -v28, v208, v219
	s_waitcnt lgkmcnt(9)
	v_fma_f32 v214, -v52, v212, v214
	v_fma_f32 v216, -v17, v209, v216
	v_fma_f32 v217, -v21, v209, v217
	s_waitcnt lgkmcnt(8)
	v_fma_f32 v215, -v56, v212, v215
	v_fma_f32 v218, -v25, v209, v218
	v_fma_f32 v219, -v29, v209, v219
	v_fma_f32 v214, -v53, v213, v214
	v_fma_f32 v216, -v18, v210, v216
	v_fma_f32 v217, -v22, v210, v217
	v_fma_f32 v215, -v57, v213, v215
	v_fma_f32 v218, -v26, v210, v218
	v_fma_f32 v219, -v30, v210, v219
	v_fma_f32 v215, -v58, v214, v215
	v_fma_f32 v216, -v19, v211, v216
	v_fma_f32 v217, -v23, v211, v217
	v_fma_f32 v218, -v27, v211, v218
	v_fma_f32 v219, -v31, v211, v219
	ds_read_b128 v[16:19], v63 offset:16528
	ds_read_b128 v[20:23], v63 offset:16800
	ds_read_b128 v[24:27], v63 offset:17072
	ds_read_b128 v[28:31], v63 offset:17344
	s_waitcnt lgkmcnt(11)
	v_fma_f32 v220, -v32, v208, v220
	s_waitcnt lgkmcnt(10)
	v_fma_f32 v221, -v36, v208, v221
	s_waitcnt lgkmcnt(9)
	v_fma_f32 v222, -v40, v208, v222
	s_waitcnt lgkmcnt(8)
	v_fma_f32 v223, -v44, v208, v223
	v_fma_f32 v220, -v33, v209, v220
	v_fma_f32 v221, -v37, v209, v221
	v_fma_f32 v222, -v41, v209, v222
	v_fma_f32 v223, -v45, v209, v223
	v_fma_f32 v220, -v34, v210, v220
	v_fma_f32 v221, -v38, v210, v221
	v_fma_f32 v222, -v42, v210, v222
	v_fma_f32 v223, -v46, v210, v223
	v_fma_f32 v220, -v35, v211, v220
	v_fma_f32 v221, -v39, v211, v221
	v_fma_f32 v222, -v43, v211, v222
	v_fma_f32 v223, -v47, v211, v223
	ds_read_b128 v[48:51], v63 offset:15728
	ds_read_b128 v[52:55], v63 offset:16000
	ds_read_b128 v[56:59], v63 offset:16272
	ds_read_b128 v[32:35], v63 offset:16544
	ds_read_b128 v[36:39], v63 offset:16816
	ds_read_b128 v[40:43], v63 offset:17088
	ds_read_b128 v[44:47], v63 offset:17360
	s_waitcnt lgkmcnt(14)
	v_fma_f32 v216, -v0, v212, v216
	s_waitcnt lgkmcnt(13)
	v_fma_f32 v217, -v4, v212, v217
	s_waitcnt lgkmcnt(12)
	v_fma_f32 v218, -v8, v212, v218
	s_waitcnt lgkmcnt(11)
	v_fma_f32 v219, -v12, v212, v219
	v_fma_f32 v216, -v1, v213, v216
	v_fma_f32 v217, -v5, v213, v217
	v_fma_f32 v218, -v9, v213, v218
	v_fma_f32 v219, -v13, v213, v219
	v_fma_f32 v216, -v2, v214, v216
	v_fma_f32 v217, -v6, v214, v217
	v_fma_f32 v218, -v10, v214, v218
	v_fma_f32 v219, -v14, v214, v219
	v_fma_f32 v216, -v3, v215, v216
	v_fma_f32 v217, -v7, v215, v217
	v_fma_f32 v218, -v11, v215, v218
	v_fma_f32 v219, -v15, v215, v219
	s_waitcnt lgkmcnt(10)
	v_fma_f32 v220, -v16, v212, v220
	s_waitcnt lgkmcnt(9)
	v_fma_f32 v221, -v20, v212, v221
	s_waitcnt lgkmcnt(6)
	v_fma_f32 v217, -v48, v216, v217
	s_waitcnt lgkmcnt(8)
	v_fma_f32 v222, -v24, v212, v222
	s_waitcnt lgkmcnt(7)
	v_fma_f32 v223, -v28, v212, v223
	s_waitcnt lgkmcnt(5)
	v_fma_f32 v218, -v52, v216, v218
	v_fma_f32 v220, -v17, v213, v220
	v_fma_f32 v221, -v21, v213, v221
	s_waitcnt lgkmcnt(4)
	v_fma_f32 v219, -v56, v216, v219
	v_fma_f32 v222, -v25, v213, v222
	v_fma_f32 v223, -v29, v213, v223
	v_fma_f32 v218, -v53, v217, v218
	v_fma_f32 v220, -v18, v214, v220
	v_fma_f32 v221, -v22, v214, v221
	v_fma_f32 v219, -v57, v217, v219
	v_fma_f32 v222, -v26, v214, v222
	v_fma_f32 v223, -v30, v214, v223
	v_fma_f32 v219, -v58, v218, v219
	v_fma_f32 v220, -v19, v215, v220
	v_fma_f32 v221, -v23, v215, v221
	v_fma_f32 v222, -v27, v215, v222
	v_fma_f32 v223, -v31, v215, v223
	ds_read_b128 v[48:51], v63 offset:16832
	ds_read_b128 v[52:55], v63 offset:17104
	ds_read_b128 v[56:59], v63 offset:17376
	s_waitcnt lgkmcnt(6)
	v_fma_f32 v220, -v32, v216, v220
	s_waitcnt lgkmcnt(5)
	v_fma_f32 v221, -v36, v216, v221
	s_waitcnt lgkmcnt(4)
	v_fma_f32 v222, -v40, v216, v222
	s_waitcnt lgkmcnt(3)
	v_fma_f32 v223, -v44, v216, v223
	v_fma_f32 v220, -v33, v217, v220
	v_fma_f32 v221, -v37, v217, v221
	v_fma_f32 v222, -v41, v217, v222
	v_fma_f32 v223, -v45, v217, v223
	v_fma_f32 v220, -v34, v218, v220
	v_fma_f32 v221, -v38, v218, v221
	v_fma_f32 v222, -v42, v218, v222
	v_fma_f32 v223, -v46, v218, v223
	v_fma_f32 v220, -v35, v219, v220
	v_fma_f32 v221, -v39, v219, v221
	v_fma_f32 v222, -v43, v219, v222
	v_fma_f32 v223, -v47, v219, v223
	s_waitcnt lgkmcnt(2)
	v_fma_f32 v221, -v48, v220, v221
	s_waitcnt lgkmcnt(1)
	v_fma_f32 v222, -v52, v220, v222
	s_waitcnt lgkmcnt(0)
	v_fma_f32 v223, -v56, v220, v223
	v_fma_f32 v222, -v53, v221, v222
	v_fma_f32 v223, -v57, v221, v223
	v_fma_f32 v223, -v58, v222, v223
	v_readfirstlane_b32 s7, v100
	s_lshl_b32 s22, s6, 14
	v_cvt_pk_bf16_f32 v0, v160, v161
	v_cvt_pk_bf16_f32 v1, v162, v163
	v_cvt_pk_bf16_f32 v2, v164, v165
	v_cvt_pk_bf16_f32 v3, v166, v167
	v_cvt_pk_bf16_f32 v4, v168, v169
	v_cvt_pk_bf16_f32 v5, v170, v171
	v_cvt_pk_bf16_f32 v6, v172, v173
	v_cvt_pk_bf16_f32 v7, v174, v175
	v_cvt_pk_bf16_f32 v8, v176, v177
	v_cvt_pk_bf16_f32 v9, v178, v179
	v_cvt_pk_bf16_f32 v10, v180, v181
	v_cvt_pk_bf16_f32 v11, v182, v183
	v_cvt_pk_bf16_f32 v12, v184, v185
	v_cvt_pk_bf16_f32 v13, v186, v187
	v_cvt_pk_bf16_f32 v14, v188, v189
	v_cvt_pk_bf16_f32 v15, v190, v191
	v_cvt_pk_bf16_f32 v16, v192, v193
	v_cvt_pk_bf16_f32 v17, v194, v195
	v_cvt_pk_bf16_f32 v18, v196, v197
	v_cvt_pk_bf16_f32 v19, v198, v199
	v_cvt_pk_bf16_f32 v20, v200, v201
	v_cvt_pk_bf16_f32 v21, v202, v203
	v_cvt_pk_bf16_f32 v22, v204, v205
	v_cvt_pk_bf16_f32 v23, v206, v207
	v_cvt_pk_bf16_f32 v24, v208, v209
	v_cvt_pk_bf16_f32 v25, v210, v211
	v_cvt_pk_bf16_f32 v26, v212, v213
	v_cvt_pk_bf16_f32 v27, v214, v215
	v_cvt_pk_bf16_f32 v28, v216, v217
	v_cvt_pk_bf16_f32 v29, v218, v219
	v_cvt_pk_bf16_f32 v30, v220, v221
	v_cvt_pk_bf16_f32 v31, v222, v223
	s_cmpk_lt_u32 s7, 0x80
	s_cbranch_scc0 .Lgsolve_w_out
	v_readlane_b32 s10, v245, 10
	v_readlane_b32 s11, v245, 11
	s_add_u32 s10, s10, s22
	s_addc_u32 s11, s11, 0
	v_lshlrev_b32_e32 v60, 7, v100
	v_mov_b32_e32 v61, 0
	v_lshl_add_u64 v[60:61], s[10:11], 0, v[60:61]
	global_store_dwordx4 v[60:61], v[0:3], off
	global_store_dwordx4 v[60:61], v[4:7], off offset:16
	global_store_dwordx4 v[60:61], v[8:11], off offset:32
	global_store_dwordx4 v[60:61], v[12:15], off offset:48
	global_store_dwordx4 v[60:61], v[16:19], off offset:64
	global_store_dwordx4 v[60:61], v[20:23], off offset:80
	global_store_dwordx4 v[60:61], v[24:27], off offset:96
	global_store_dwordx4 v[60:61], v[28:31], off offset:112
	s_branch .LBB0_392
.Lgsolve_w_out:
	v_readlane_b32 s10, v245, 12
	v_readlane_b32 s11, v245, 13
	s_add_u32 s10, s10, s22
	s_addc_u32 s11, s11, 0
	v_lshlrev_b32_e32 v60, 1, v100
	v_add_u32_e32 v60, 0xffffff00, v60
	v_mov_b32_e32 v61, 0
	v_lshl_add_u64 v[60:61], s[10:11], 0, v[60:61]
	s_mov_b64 s[24:25], 0x1000
	v_lshl_add_u64 v[62:63], v[60:61], 0, s[24:25]
	v_lshl_add_u64 v[64:65], v[62:63], 0, s[24:25]
	v_lshl_add_u64 v[66:67], v[64:65], 0, s[24:25]
	global_store_short v[60:61], v0, off
	global_store_short_d16_hi v[60:61], v0, off offset:256
	global_store_short v[60:61], v1, off offset:512
	global_store_short_d16_hi v[60:61], v1, off offset:768
	global_store_short v[60:61], v2, off offset:1024
	global_store_short_d16_hi v[60:61], v2, off offset:1280
	global_store_short v[60:61], v3, off offset:1536
	global_store_short_d16_hi v[60:61], v3, off offset:1792
	global_store_short v[60:61], v4, off offset:2048
	global_store_short_d16_hi v[60:61], v4, off offset:2304
	global_store_short v[60:61], v5, off offset:2560
	global_store_short_d16_hi v[60:61], v5, off offset:2816
	global_store_short v[60:61], v6, off offset:3072
	global_store_short_d16_hi v[60:61], v6, off offset:3328
	global_store_short v[60:61], v7, off offset:3584
	global_store_short_d16_hi v[60:61], v7, off offset:3840
	global_store_short v[62:63], v8, off
	global_store_short_d16_hi v[62:63], v8, off offset:256
	global_store_short v[62:63], v9, off offset:512
	global_store_short_d16_hi v[62:63], v9, off offset:768
	global_store_short v[62:63], v10, off offset:1024
	global_store_short_d16_hi v[62:63], v10, off offset:1280
	global_store_short v[62:63], v11, off offset:1536
	global_store_short_d16_hi v[62:63], v11, off offset:1792
	global_store_short v[62:63], v12, off offset:2048
	global_store_short_d16_hi v[62:63], v12, off offset:2304
	global_store_short v[62:63], v13, off offset:2560
	global_store_short_d16_hi v[62:63], v13, off offset:2816
	global_store_short v[62:63], v14, off offset:3072
	global_store_short_d16_hi v[62:63], v14, off offset:3328
	global_store_short v[62:63], v15, off offset:3584
	global_store_short_d16_hi v[62:63], v15, off offset:3840
	global_store_short v[64:65], v16, off
	global_store_short_d16_hi v[64:65], v16, off offset:256
	global_store_short v[64:65], v17, off offset:512
	global_store_short_d16_hi v[64:65], v17, off offset:768
	global_store_short v[64:65], v18, off offset:1024
	global_store_short_d16_hi v[64:65], v18, off offset:1280
	global_store_short v[64:65], v19, off offset:1536
	global_store_short_d16_hi v[64:65], v19, off offset:1792
	global_store_short v[64:65], v20, off offset:2048
	global_store_short_d16_hi v[64:65], v20, off offset:2304
	global_store_short v[64:65], v21, off offset:2560
	global_store_short_d16_hi v[64:65], v21, off offset:2816
	global_store_short v[64:65], v22, off offset:3072
	global_store_short_d16_hi v[64:65], v22, off offset:3328
	global_store_short v[64:65], v23, off offset:3584
	global_store_short_d16_hi v[64:65], v23, off offset:3840
	global_store_short v[66:67], v24, off
	global_store_short_d16_hi v[66:67], v24, off offset:256
	global_store_short v[66:67], v25, off offset:512
	global_store_short_d16_hi v[66:67], v25, off offset:768
	global_store_short v[66:67], v26, off offset:1024
	global_store_short_d16_hi v[66:67], v26, off offset:1280
	global_store_short v[66:67], v27, off offset:1536
	global_store_short_d16_hi v[66:67], v27, off offset:1792
	global_store_short v[66:67], v28, off offset:2048
	global_store_short_d16_hi v[66:67], v28, off offset:2304
	global_store_short v[66:67], v29, off offset:2560
	global_store_short_d16_hi v[66:67], v29, off offset:2816
	global_store_short v[66:67], v30, off offset:3072
	global_store_short_d16_hi v[66:67], v30, off offset:3328
	global_store_short v[66:67], v31, off offset:3584
	global_store_short_d16_hi v[66:67], v31, off offset:3840
	s_branch .LBB0_392
